# rwkv prep: output-gate rows staged in the same LDS slots and written as whole 128-byte rows with the records
# speedup vs baseline: 1.0024x; 1.0024x over previous
; __device__ __forceinline__ float bflo(unsigned u) { return __uint_as_float(u << 16); }
; __device__ __forceinline__ float bfhi(unsigned u) { return __uint_as_float(u & 0xffff0000u); }
; __device__ __forceinline__ float tanhf_(float x) { return 1.0f - 2.0f * __builtin_amdgcn_rcpf(1.0f + __expf(2.0f * x)); }
; __device__ __forceinline__ void rwkv_prep_item(const Params& p, const Lt& lt, int l, int item) {
;     const int tid = lt.tid, lane = tid & 63, w = __builtin_amdgcn_readfirstlane(tid >> 6), qi = lane & 15, quad = lane >> 4;
;     const int t = item * 32 + (w >> 2) * 16 + qi, hg = w & 3;
;     const bf16_t* P = (const bf16_t*)(p.ws + WS_P);
;     const bf16_t* pt = P + (size_t)t * INC;
;     const bf16_t* pp = P + (size_t)(t > 0 ? t - 1 : 0) * INC;
;     const float pm = t > 0 ? 1.f : 0.f;
;     const float* mu = p.in[3] + l * 2560;
;     const bf16_t* lora = (const bf16_t*)(p.ws + WS_LORA + l * SZ_LORA);
;     const bf16_t* decT = lora; const bf16_t* aT = lora + 49152; const bf16_t* gT = lora + 98304;
;     bf16x8 fw[2], fa[2], fg[4];
; #pragma unroll
;     for (int ks = 0; ks < 8; ++ks) {
;         const int col = COL_XW + ks * 32 + quad * 8;
;         const u32x4 c4 = *(const u32x4*)(pt + col), q4 = *(const u32x4*)(pp + col);
;         const f32x4 m0 = *(const f32x4*)(mu + col), m1 = *(const f32x4*)(mu + col + 4);
;         float v[8];
; #pragma unroll
;         for (int i = 0; i < 4; ++i) {
;             const float c0 = bflo(c4[i]), c1 = bfhi(c4[i]), p0 = bflo(q4[i]) * pm, p1 = bfhi(q4[i]) * pm;
;             const float mu0 = (i < 2) ? m0[2 * i] : m1[2 * i - 4], mu1 = (i < 2) ? m0[2 * i + 1] : m1[2 * i - 3];
;             v[2 * i] = c0 + (p0 - c0) * mu0; v[2 * i + 1] = c1 + (p1 - c1) * mu1;
;         }
;         if (ks < 2) {
; #pragma unroll
;             for (int i = 0; i < 8; ++i) v[i] = tanhf_(v[i]);
.LBB0_343:
	s_and_b32 s0, s54, 0xfe
	s_ashr_i32 s1, s55, 7
	s_add_i32 s4, s0, s1
	v_and_b32_e32 v210, 63, v245
	v_lshrrev_b32_e32 v211, 6, v245
	v_and_b32_e32 v212, 15, v245
	v_mul_u32_u24_e32 v213, 16640, v211
	v_lshl_add_u32 v226, v210, 4, v213
	v_lshrrev_b32_e32 v214, 2, v211
	v_lshlrev_b32_e32 v214, 4, v214
	s_lshl_b32 s98, s4, 5
	v_add_u32_e32 v214, s98, v214
	v_and_b32_e32 v215, 3, v211
	v_cmp_gt_u32_e32 vcc, 56, v210
	v_mov_b32_e32 v216, 0x600
	v_mov_b32_e32 v217, 0x2a00
	s_nop 0
	v_cndmask_b32_e32 v194, v216, v217, vcc
	v_mov_b32_e32 v195, 0
	v_mov_b32_e32 v216, 0x80
	v_mov_b32_e32 v217, 0x380
	v_cndmask_b32_e32 v198, v216, v217, vcc
	v_mov_b32_e32 v199, 0
	v_mul_lo_u32 v216, v214, v194
	v_mul_u32_u24_e32 v217, 3, v215
	v_mul_lo_u32 v217, v217, v198
	v_add_u32_e32 v216, v216, v217
	v_lshlrev_b32_e32 v218, 4, v210
	v_add_u32_e32 v217, 0xfffffc80, v218
	v_cndmask_b32_e32 v218, v217, v218, vcc
	v_add_u32_e32 v218, v216, v218
	v_mov_b32_e32 v219, 0
	v_readlane_b32 s98, v253, 63
	v_readlane_b32 s99, v254, 0
	v_mov_b32_e32 v216, 0x28f00000
	v_mov_b32_e32 v217, 0x23b00000
	v_cndmask_b32_e32 v216, v216, v217, vcc
	v_add_co_u32_e32 v218, vcc, v218, v216
	s_nop 1
	v_addc_co_u32_e32 v219, vcc, 0, v219, vcc
	v_lshl_add_u64 v[234:235], s[98:99], 0, v[218:219]
	s_add_u32 s98, s98, 0x23b00000
	v_mul_u32_u24_e32 v216, 0xa80, v215
	s_movk_i32 s99, 0x2a00
	v_mul_lo_u32 v217, v214, s99
	v_add_u32_e32 v216, v216, v217
	v_mul_u32_u24_e32 v217, 9712, v212
	v_add_u32_e32 v216, v216, v217
	v_sub_u32_e32 v216, v216, v213
	v_add_u32_e32 v230, s98, v216
	v_add_u32_e32 v231, 0x380, v230
	v_add_u32_e32 v232, 0x700, v230
	v_readlane_b32 s98, v253, 63
	s_add_u32 s98, s98, 0x28f00000
	v_mul_u32_u24_e32 v216, 0x180, v215
	s_movk_i32 s99, 0x600
	v_mul_lo_u32 v217, v214, s99
	v_add_u32_e32 v216, v216, v217
	v_mul_u32_u24_e32 v217, 496, v212
	v_add_u32_e32 v216, v216, v217
	v_sub_u32_e32 v216, v216, v213
	v_add_u32_e32 v216, 0xfffffc80, v216
	v_add_u32_e32 v236, s98, v216
	v_add_u32_e32 v237, 0x80, v236
	v_add_u32_e32 v227, 0x100, v236
	v_readlane_b32 s0, v253, 52
	v_readlane_b32 s1, v253, 53
	v_mov_b32_e32 v0, v245
	s_and_b64 s[0:1], s[0:1], exec
	s_cselect_b32 s1, s4, s55
	v_readfirstlane_b32 s0, v0
	s_ashr_i32 s4, s0, 4
	v_bfe_u32 v1, v0, 4, 2
	s_lshl_b32 s1, s1, 5
	s_and_b32 s4, s4, -16
	v_and_b32_e32 v180, 15, v0
	s_add_i32 s4, s4, s1
	v_lshlrev_b32_e32 v44, 3, v1
	v_or_b32_e32 v84, s4, v180
	s_waitcnt vmcnt(63) lgkmcnt(0)
	v_mov_b64_e32 v[4:5], s[6:7]
	v_or_b32_e32 v0, 0x900, v44
	v_mad_i64_i32 v[114:115], s[4:5], v84, s76, v[4:5]
	v_lshlrev_b32_e32 v2, 1, v0
	v_lshl_add_u64 v[6:7], v[114:115], 0, v[2:3]
	global_load_dwordx4 v[8:11], v[6:7], off
	v_max_i32_e32 v6, 1, v84
	v_add_u32_e32 v6, -1, v6
	v_mad_u64_u32 v[110:111], s[4:5], v6, s76, v[4:5]
	v_lshl_add_u64 v[4:5], v[110:111], 0, v[2:3]
	global_load_dwordx4 v[12:15], v[4:5], off
	v_lshlrev_b32_e32 v0, 2, v0
	global_load_dwordx4 v[16:19], v0, s[8:9]
	global_load_dwordx4 v[20:23], v0, s[8:9] offset:16
	v_or_b32_e32 v2, 0x920, v44
	v_lshlrev_b32_e32 v0, 2, v2
	v_lshlrev_b32_e32 v2, 1, v2
	v_lshl_add_u64 v[28:29], v[114:115], 0, v[2:3]
	v_lshl_add_u64 v[32:33], v[110:111], 0, v[2:3]
	global_load_dwordx4 v[4:7], v0, s[8:9] offset:16
	global_load_dwordx4 v[24:27], v0, s[8:9]
	s_nop 0
	global_load_dwordx4 v[28:31], v[28:29], off
	s_nop 0
	global_load_dwordx4 v[32:35], v[32:33], off
	v_cmp_lt_i32_e32 vcc, 0, v84
	v_or_b32_e32 v59, 0x980, v44
	s_bfe_u32 s4, s0, 0x20006
	v_cndmask_b32_e64 v0, 0, 1.0, vcc
	s_mul_i32 s5, s4, 0xc0
	v_lshlrev_b32_e32 v112, 4, v1
	v_mov_b32_e32 v113, v3
	v_lshl_add_u64 v[88:89], s[28:29], 0, v[112:113]
	v_lshl_add_u64 v[92:93], s[30:31], 0, v[112:113]
	v_lshlrev_b32_e32 v181, 2, v1
	s_mul_i32 s10, s4, 0xa80
	v_lshl_add_u64 v[94:95], s[34:35], 0, v[112:113]
	s_mov_b32 s57, 0x3f317217
	s_mov_b32 s58, 0x7f800000
	s_mul_i32 s56, s4, 3
	s_waitcnt vmcnt(7)
	v_lshlrev_b32_e32 v2, 16, v8
	v_and_b32_e32 v8, 0xffff0000, v8
	v_lshlrev_b32_e32 v38, 16, v11
	v_and_b32_e32 v39, 0xffff0000, v11
	v_lshlrev_b32_e32 v36, 16, v9
	v_and_b32_e32 v9, 0xffff0000, v9
	s_waitcnt vmcnt(6)
	v_lshlrev_b32_e32 v11, 16, v12
	v_and_b32_e32 v12, 0xffff0000, v12
	v_lshlrev_b32_e32 v40, 16, v13
	v_and_b32_e32 v13, 0xffff0000, v13
	v_fma_f32 v12, v0, v12, -v8
	v_fma_f32 v11, v0, v11, -v2
	v_fma_f32 v13, v0, v13, -v9
	s_waitcnt vmcnt(5)
	v_fmac_f32_e32 v8, v17, v12
	v_fmac_f32_e32 v2, v16, v11
	v_fmac_f32_e32 v9, v19, v13
	v_add_f32_e32 v8, v8, v8
	v_add_f32_e32 v2, v2, v2
	v_add_f32_e32 v9, v9, v9
	v_mul_f32_e32 v8, 0x3fb8aa3b, v8
	v_mul_f32_e32 v2, 0x3fb8aa3b, v2
	v_mul_f32_e32 v9, 0x3fb8aa3b, v9
	v_exp_f32_e32 v8, v8
	v_exp_f32_e32 v2, v2
	v_exp_f32_e32 v9, v9
	v_lshlrev_b32_e32 v37, 16, v10
	v_and_b32_e32 v10, 0xffff0000, v10
	v_lshlrev_b32_e32 v41, 16, v14
	v_and_b32_e32 v14, 0xffff0000, v14
	v_lshlrev_b32_e32 v42, 16, v15
	v_and_b32_e32 v15, 0xffff0000, v15
	v_fma_f32 v40, v0, v40, -v36
	v_fma_f32 v14, v0, v14, -v10
	v_fma_f32 v42, v0, v42, -v38
	v_add_f32_e32 v13, 1.0, v8
	v_fmac_f32_e32 v36, v18, v40
	s_waitcnt vmcnt(4)
	v_fmac_f32_e32 v10, v21, v14
	v_fmac_f32_e32 v38, v22, v42
	v_add_f32_e32 v2, 1.0, v2
	v_add_f32_e32 v14, 1.0, v9
	v_rcp_f32_e32 v9, v13
	v_fma_f32 v13, v0, v15, -v39
	v_add_f32_e32 v11, v36, v36
	v_rcp_f32_e32 v8, v2
	v_add_f32_e32 v2, v38, v38
	v_fmac_f32_e32 v39, v23, v13
	v_add_f32_e32 v10, v10, v10
	v_mul_f32_e32 v11, 0x3fb8aa3b, v11
	v_mul_f32_e32 v2, 0x3fb8aa3b, v2
	v_add_f32_e32 v13, v39, v39
	v_mul_f32_e32 v10, 0x3fb8aa3b, v10
	v_exp_f32_e32 v11, v11
	v_exp_f32_e32 v2, v2
	v_mul_f32_e32 v13, 0x3fb8aa3b, v13
	v_exp_f32_e32 v10, v10
	v_exp_f32_e32 v15, v13
	v_fma_f32 v41, v0, v41, -v37
	v_add_f32_e32 v11, 1.0, v11
	v_add_f32_e32 v2, 1.0, v2
	v_fmac_f32_e32 v37, v20, v41
	v_add_f32_e32 v16, 1.0, v10
	v_rcp_f32_e32 v10, v11
	v_rcp_f32_e32 v11, v14
	v_rcp_f32_e32 v14, v2
	v_add_f32_e32 v2, 1.0, v15
	v_add_f32_e32 v12, v37, v37
	v_rcp_f32_e32 v15, v2
	v_pk_fma_f32 v[8:9], v[8:9], 2.0, 1.0 op_sel_hi:[1,0,0] neg_lo:[1,0,0] neg_hi:[1,0,0]
	s_waitcnt vmcnt(1)
; __device__ __forceinline__ unsigned cvt_pk_bf16(float lo, float hi) { const f32x2 v = {lo, hi}; return __builtin_bit_cast(unsigned, __builtin_convertvector(v, bf16x2_t)); }
; __device__ __forceinline__ float bflo(unsigned u) { return __uint_as_float(u << 16); }
; __device__ __forceinline__ float bfhi(unsigned u) { return __uint_as_float(u & 0xffff0000u); }
; __device__ __forceinline__ float sigmoidf_(float x) { return __builtin_amdgcn_rcpf(1.0f + __expf(-x)); }
; __device__ __forceinline__ float tanhf_(float x) { return 1.0f - 2.0f * __builtin_amdgcn_rcpf(1.0f + __expf(2.0f * x)); }
; __device__ __forceinline__ void rwkv_prep_item(const Params& p, const Lt& lt, int l, int item) {
;     ...
;     for (int ks = 0; ks < 8; ++ks) {
;         const int col = COL_XW + ks * 32 + quad * 8;
;         const u32x4 c4 = *(const u32x4*)(pt + col), q4 = *(const u32x4*)(pp + col);
;         const f32x4 m0 = *(const f32x4*)(mu + col), m1 = *(const f32x4*)(mu + col + 4);
;         float v[8];
; #pragma unroll
;         for (int i = 0; i < 4; ++i) {
;             const float c0 = bflo(c4[i]), c1 = bfhi(c4[i]), p0 = bflo(q4[i]) * pm, p1 = bfhi(q4[i]) * pm;
;             const float mu0 = (i < 2) ? m0[2 * i] : m1[2 * i - 4], mu1 = (i < 2) ? m0[2 * i + 1] : m1[2 * i - 3];
;             v[2 * i] = c0 + (p0 - c0) * mu0; v[2 * i + 1] = c1 + (p1 - c1) * mu1;
;         }
;         if (ks < 2) {
; #pragma unroll
;             for (int i = 0; i < 8; ++i) v[i] = tanhf_(v[i]);
;         } else if (ks >= 4) {
; #pragma unroll
;             for (int i = 0; i < 8; ++i) v[i] = sigmoidf_(v[i]);
;         }
;         u32x4 pk; pk.x = cvt_pk_bf16(v[0], v[1]); pk.y = cvt_pk_bf16(v[2], v[3]); pk.z = cvt_pk_bf16(v[4], v[5]); pk.w = cvt_pk_bf16(v[6], v[7]);
;         const bf16x8 f = __builtin_bit_cast(bf16x8, pk);
;         if (ks < 2) fw[ks] = f; else if (ks < 4) fa[ks - 2] = f; else fg[ks - 4] = f;
	v_lshlrev_b32_e32 v40, 16, v28
	s_waitcnt vmcnt(0)
	v_lshlrev_b32_e32 v2, 16, v32
	v_mul_f32_e32 v12, 0x3fb8aa3b, v12
	v_cvt_pk_bf16_f32 v20, v8, v9
	v_and_b32_e32 v28, 0xffff0000, v28
	v_and_b32_e32 v8, 0xffff0000, v32
	v_fma_f32 v2, v0, v2, -v40
	v_exp_f32_e32 v12, v12
	v_fmac_f32_e32 v40, v24, v2
	v_fma_f32 v2, v0, v8, -v28
	v_fmac_f32_e32 v28, v25, v2
	v_lshlrev_b32_e32 v25, 16, v29
	v_lshlrev_b32_e32 v2, 16, v33
	v_and_b32_e32 v29, 0xffff0000, v29
	v_and_b32_e32 v8, 0xffff0000, v33
	v_fma_f32 v2, v0, v2, -v25
	v_fmac_f32_e32 v25, v26, v2
	v_fma_f32 v2, v0, v8, -v29
	v_add_f32_e32 v12, 1.0, v12
	v_fmac_f32_e32 v29, v27, v2
	v_lshlrev_b32_e32 v27, 16, v30
	v_lshlrev_b32_e32 v2, 16, v34
	v_rcp_f32_e32 v12, v12
	v_rcp_f32_e32 v13, v16
	v_and_b32_e32 v30, 0xffff0000, v30
	v_and_b32_e32 v8, 0xffff0000, v34
	v_fma_f32 v2, v0, v2, -v27
	v_fmac_f32_e32 v27, v4, v2
	v_fma_f32 v2, v0, v8, -v30
	v_or_b32_e32 v16, 0x940, v44
	v_fmac_f32_e32 v30, v5, v2
	v_lshlrev_b32_e32 v2, 1, v16
	v_pk_fma_f32 v[10:11], v[10:11], 2.0, 1.0 op_sel_hi:[1,0,0] neg_lo:[1,0,0] neg_hi:[1,0,0]
	v_lshl_add_u64 v[4:5], v[114:115], 0, v[2:3]
	v_pk_fma_f32 v[12:13], v[12:13], 2.0, 1.0 op_sel_hi:[1,0,0] neg_lo:[1,0,0] neg_hi:[1,0,0]
	v_pk_fma_f32 v[14:15], v[14:15], 2.0, 1.0 op_sel_hi:[1,0,0] neg_lo:[1,0,0] neg_hi:[1,0,0]
	v_cvt_pk_bf16_f32 v21, v10, v11
	global_load_dwordx4 v[8:11], v[4:5], off
	v_lshl_add_u64 v[4:5], v[110:111], 0, v[2:3]
	v_lshlrev_b32_e32 v2, 2, v16
	v_cvt_pk_bf16_f32 v22, v12, v13
	v_cvt_pk_bf16_f32 v23, v14, v15
	global_load_dwordx4 v[12:15], v[4:5], off
	global_load_dwordx4 v[16:19], v2, s[8:9] offset:16
	global_load_dwordx4 v[36:39], v2, s[8:9]
	v_add_f32_e32 v2, v40, v40
	v_mul_f32_e32 v2, 0x3fb8aa3b, v2
	v_exp_f32_e32 v2, v2
	v_add_f32_e32 v4, v28, v28
	v_mul_f32_e32 v4, 0x3fb8aa3b, v4
	v_exp_f32_e32 v4, v4
	v_add_f32_e32 v2, 1.0, v2
	v_rcp_f32_e32 v24, v2
	v_add_f32_e32 v2, v25, v25
	v_mul_f32_e32 v2, 0x3fb8aa3b, v2
	v_exp_f32_e32 v28, v2
	v_add_f32_e32 v2, v29, v29
	v_mul_f32_e32 v2, 0x3fb8aa3b, v2
	v_or_b32_e32 v25, 0x960, v44
	v_exp_f32_e32 v29, v2
	v_lshlrev_b32_e32 v2, 1, v25
	v_add_f32_e32 v26, 1.0, v4
	v_lshl_add_u64 v[4:5], v[114:115], 0, v[2:3]
	v_lshlrev_b32_e32 v54, 16, v35
	v_and_b32_e32 v55, 0xffff0000, v35
	global_load_dwordx4 v[32:35], v[4:5], off
	v_lshl_add_u64 v[4:5], v[110:111], 0, v[2:3]
	global_load_dwordx4 v[40:43], v[4:5], off
	v_lshlrev_b32_e32 v2, 2, v25
	global_load_dwordx4 v[46:49], v2, s[8:9] offset:16
	global_load_dwordx4 v[50:53], v2, s[8:9]
	v_add_f32_e32 v4, v27, v27
	v_mul_f32_e32 v4, 0x3fb8aa3b, v4
	v_add_f32_e32 v5, v30, v30
	v_exp_f32_e32 v4, v4
	v_mul_f32_e32 v5, 0x3fb8aa3b, v5
	v_exp_f32_e32 v5, v5
	v_add_f32_e32 v2, 1.0, v28
	v_rcp_f32_e32 v25, v26
	v_rcp_f32_e32 v26, v2
	v_add_f32_e32 v2, 1.0, v29
	v_rcp_f32_e32 v27, v2
	v_add_f32_e32 v2, 1.0, v4
	v_lshlrev_b32_e32 v45, 16, v31
	v_rcp_f32_e32 v28, v2
	v_add_f32_e32 v2, 1.0, v5
	v_rcp_f32_e32 v29, v2
	v_fma_f32 v2, v0, v54, -v45
	v_fmac_f32_e32 v45, v6, v2
	v_add_f32_e32 v2, v45, v45
	v_and_b32_e32 v31, 0xffff0000, v31
	v_mul_f32_e32 v2, 0x3fb8aa3b, v2
	v_exp_f32_e32 v45, v2
	v_fma_f32 v2, v0, v55, -v31
	v_fmac_f32_e32 v31, v7, v2
	v_add_f32_e32 v2, v31, v31
	v_mul_f32_e32 v2, 0x3fb8aa3b, v2
	v_exp_f32_e32 v58, v2
	v_lshlrev_b32_e32 v2, 1, v59
	v_lshl_add_u64 v[4:5], v[114:115], 0, v[2:3]
	v_lshl_add_u64 v[30:31], v[110:111], 0, v[2:3]
	global_load_dwordx4 v[4:7], v[4:5], off
	v_add_f32_e32 v2, 1.0, v45
	global_load_dwordx4 v[54:57], v[30:31], off
	v_lshlrev_b32_e32 v31, 2, v59
	v_rcp_f32_e32 v30, v2
	v_add_f32_e32 v2, 1.0, v58
	global_load_dwordx4 v[58:61], v31, s[8:9] offset:16
	global_load_dwordx4 v[62:65], v31, s[8:9]
	v_rcp_f32_e32 v31, v2
	v_pk_fma_f32 v[24:25], v[24:25], 2.0, 1.0 op_sel_hi:[1,0,0] neg_lo:[1,0,0] neg_hi:[1,0,0]
	v_pk_fma_f32 v[26:27], v[26:27], 2.0, 1.0 op_sel_hi:[1,0,0] neg_lo:[1,0,0] neg_hi:[1,0,0]
	v_pk_fma_f32 v[28:29], v[28:29], 2.0, 1.0 op_sel_hi:[1,0,0] neg_lo:[1,0,0] neg_hi:[1,0,0]
	v_pk_fma_f32 v[30:31], v[30:31], 2.0, 1.0 op_sel_hi:[1,0,0] neg_lo:[1,0,0] neg_hi:[1,0,0]
	v_cvt_pk_bf16_f32 v24, v24, v25
	v_cvt_pk_bf16_f32 v25, v26, v27
	v_cvt_pk_bf16_f32 v26, v28, v29
	v_cvt_pk_bf16_f32 v27, v30, v31
	s_waitcnt vmcnt(11)
	v_lshlrev_b32_e32 v28, 16, v8
	v_and_b32_e32 v29, 0xffff0000, v8
	v_lshlrev_b32_e32 v8, 16, v9
	v_and_b32_e32 v9, 0xffff0000, v9
	s_waitcnt vmcnt(10)
	v_lshlrev_b32_e32 v30, 16, v12
	v_and_b32_e32 v31, 0xffff0000, v12
	v_lshlrev_b32_e32 v12, 16, v13
	v_and_b32_e32 v13, 0xffff0000, v13
	v_pk_fma_f32 v[30:31], v[0:1], v[30:31], v[28:29] op_sel_hi:[0,1,1] neg_lo:[0,0,1] neg_hi:[0,0,1]
	v_pk_fma_f32 v[12:13], v[0:1], v[12:13], v[8:9] op_sel_hi:[0,1,1] neg_lo:[0,0,1] neg_hi:[0,0,1]
	s_waitcnt vmcnt(8)
	v_pk_fma_f32 v[28:29], v[36:37], v[30:31], v[28:29]
	v_pk_fma_f32 v[8:9], v[38:39], v[12:13], v[8:9]
	v_lshlrev_b32_e32 v12, 16, v10
	v_and_b32_e32 v13, 0xffff0000, v10
	v_lshlrev_b32_e32 v30, 16, v14
	v_and_b32_e32 v31, 0xffff0000, v14
	v_lshlrev_b32_e32 v10, 16, v11
	v_and_b32_e32 v11, 0xffff0000, v11
	v_lshlrev_b32_e32 v14, 16, v15
	v_and_b32_e32 v15, 0xffff0000, v15
	v_pk_fma_f32 v[14:15], v[0:1], v[14:15], v[10:11] op_sel_hi:[0,1,1] neg_lo:[0,0,1] neg_hi:[0,0,1]
	v_pk_fma_f32 v[30:31], v[0:1], v[30:31], v[12:13] op_sel_hi:[0,1,1] neg_lo:[0,0,1] neg_hi:[0,0,1]
	v_pk_fma_f32 v[10:11], v[18:19], v[14:15], v[10:11]
	v_pk_fma_f32 v[12:13], v[16:17], v[30:31], v[12:13]
	v_cvt_pk_bf16_f32 v28, v28, v29
	v_cvt_pk_bf16_f32 v29, v8, v9
	v_cvt_pk_bf16_f32 v31, v10, v11
	s_waitcnt vmcnt(7)
	v_lshlrev_b32_e32 v8, 16, v32
	v_and_b32_e32 v9, 0xffff0000, v32
	s_waitcnt vmcnt(6)
; __device__ __forceinline__ unsigned cvt_pk_bf16(float lo, float hi) { const f32x2 v = {lo, hi}; return __builtin_bit_cast(unsigned, __builtin_convertvector(v, bf16x2_t)); }
; __device__ __forceinline__ float bflo(unsigned u) { return __uint_as_float(u << 16); }
; __device__ __forceinline__ float bfhi(unsigned u) { return __uint_as_float(u & 0xffff0000u); }
; __device__ __forceinline__ float sigmoidf_(float x) { return __builtin_amdgcn_rcpf(1.0f + __expf(-x)); }
; __device__ __forceinline__ float tanhf_(float x) { return 1.0f - 2.0f * __builtin_amdgcn_rcpf(1.0f + __expf(2.0f * x)); }
; __device__ __forceinline__ void rwkv_prep_item(const Params& p, const Lt& lt, int l, int item) {
;     ...
;     for (int ks = 0; ks < 8; ++ks) {
;         const int col = COL_XW + ks * 32 + quad * 8;
;         const u32x4 c4 = *(const u32x4*)(pt + col), q4 = *(const u32x4*)(pp + col);
;         const f32x4 m0 = *(const f32x4*)(mu + col), m1 = *(const f32x4*)(mu + col + 4);
;         float v[8];
; #pragma unroll
;         for (int i = 0; i < 4; ++i) {
;             const float c0 = bflo(c4[i]), c1 = bfhi(c4[i]), p0 = bflo(q4[i]) * pm, p1 = bfhi(q4[i]) * pm;
;             const float mu0 = (i < 2) ? m0[2 * i] : m1[2 * i - 4], mu1 = (i < 2) ? m0[2 * i + 1] : m1[2 * i - 3];
;             v[2 * i] = c0 + (p0 - c0) * mu0; v[2 * i + 1] = c1 + (p1 - c1) * mu1;
;         }
;         if (ks < 2) {
; #pragma unroll
;             for (int i = 0; i < 8; ++i) v[i] = tanhf_(v[i]);
;         } else if (ks >= 4) {
; #pragma unroll
;             for (int i = 0; i < 8; ++i) v[i] = sigmoidf_(v[i]);
;         }
;         u32x4 pk; pk.x = cvt_pk_bf16(v[0], v[1]); pk.y = cvt_pk_bf16(v[2], v[3]); pk.z = cvt_pk_bf16(v[4], v[5]); pk.w = cvt_pk_bf16(v[6], v[7]);
;         const bf16x8 f = __builtin_bit_cast(bf16x8, pk);
;         if (ks < 2) fw[ks] = f; else if (ks < 4) fa[ks - 2] = f; else fg[ks - 4] = f;
	v_lshlrev_b32_e32 v10, 16, v40
	v_and_b32_e32 v11, 0xffff0000, v40
	v_pk_fma_f32 v[10:11], v[0:1], v[10:11], v[8:9] op_sel_hi:[0,1,1] neg_lo:[0,0,1] neg_hi:[0,0,1]
	s_waitcnt vmcnt(4)
	v_pk_fma_f32 v[16:17], v[50:51], v[10:11], v[8:9]
	v_lshlrev_b32_e32 v8, 16, v33
	v_and_b32_e32 v9, 0xffff0000, v33
	v_lshlrev_b32_e32 v10, 16, v41
	v_and_b32_e32 v11, 0xffff0000, v41
	v_pk_fma_f32 v[10:11], v[0:1], v[10:11], v[8:9] op_sel_hi:[0,1,1] neg_lo:[0,0,1] neg_hi:[0,0,1]
	v_pk_fma_f32 v[18:19], v[52:53], v[10:11], v[8:9]
	v_lshlrev_b32_e32 v8, 16, v34
	v_and_b32_e32 v9, 0xffff0000, v34
	v_lshlrev_b32_e32 v10, 16, v42
	v_and_b32_e32 v11, 0xffff0000, v42
	v_or_b32_e32 v40, 0x9a0, v44
	v_pk_fma_f32 v[10:11], v[0:1], v[10:11], v[8:9] op_sel_hi:[0,1,1] neg_lo:[0,0,1] neg_hi:[0,0,1]
	v_lshlrev_b32_e32 v2, 1, v40
	v_cvt_pk_bf16_f32 v30, v12, v13
	v_pk_fma_f32 v[36:37], v[46:47], v[10:11], v[8:9]
	v_lshlrev_b32_e32 v32, 16, v35
	v_and_b32_e32 v33, 0xffff0000, v35
	v_lshlrev_b32_e32 v34, 16, v43
	v_and_b32_e32 v35, 0xffff0000, v43
	v_lshl_add_u64 v[8:9], v[114:115], 0, v[2:3]
	v_lshl_add_u64 v[12:13], v[110:111], 0, v[2:3]
	global_load_dwordx4 v[8:11], v[8:9], off
	v_pk_fma_f32 v[34:35], v[0:1], v[34:35], v[32:33] op_sel_hi:[0,1,1] neg_lo:[0,0,1] neg_hi:[0,0,1]
	global_load_dwordx4 v[12:15], v[12:13], off
	v_pk_fma_f32 v[38:39], v[48:49], v[34:35], v[32:33]
	v_cvt_pk_bf16_f32 v34, v36, v37
	v_lshlrev_b32_e32 v36, 2, v40
	v_cvt_pk_bf16_f32 v32, v16, v17
	v_cvt_pk_bf16_f32 v33, v18, v19
	v_cvt_pk_bf16_f32 v35, v38, v39
	global_load_dwordx4 v[16:19], v36, s[8:9] offset:16
	s_nop 0
	global_load_dwordx4 v[36:39], v36, s[8:9]
	s_waitcnt vmcnt(7)
	v_lshlrev_b32_e32 v2, 16, v4
	v_and_b32_e32 v4, 0xffff0000, v4
	s_waitcnt vmcnt(6)
	v_lshlrev_b32_e32 v41, 16, v54
	v_and_b32_e32 v40, 0xffff0000, v54
	v_fma_f32 v41, v0, v41, -v2
	v_fma_f32 v40, v0, v40, -v4
	s_waitcnt vmcnt(4)
	v_fmac_f32_e32 v2, v62, v41
	v_fmac_f32_e32 v4, v63, v40
	v_lshlrev_b32_e32 v40, 16, v5
	v_lshlrev_b32_e32 v41, 16, v55
	v_and_b32_e32 v5, 0xffff0000, v5
	v_and_b32_e32 v42, 0xffff0000, v55
	v_fma_f32 v41, v0, v41, -v40
	v_fmac_f32_e32 v40, v64, v41
	v_fma_f32 v41, v0, v42, -v5
	v_fmac_f32_e32 v5, v65, v41
	v_lshlrev_b32_e32 v41, 16, v6
	v_lshlrev_b32_e32 v42, 16, v56
	v_and_b32_e32 v6, 0xffff0000, v6
	v_and_b32_e32 v43, 0xffff0000, v56
	v_fma_f32 v42, v0, v42, -v41
	v_fmac_f32_e32 v41, v58, v42
	v_fma_f32 v42, v0, v43, -v6
	v_fmac_f32_e32 v6, v59, v42
	v_lshlrev_b32_e32 v42, 16, v7
	v_lshlrev_b32_e32 v43, 16, v57
	v_and_b32_e32 v7, 0xffff0000, v7
	v_and_b32_e32 v45, 0xffff0000, v57
	v_fma_f32 v43, v0, v43, -v42
	v_mul_f32_e32 v2, 0xbfb8aa3b, v2
	v_mul_f32_e32 v4, 0xbfb8aa3b, v4
	v_fmac_f32_e32 v42, v60, v43
	v_fma_f32 v43, v0, v45, -v7
	v_exp_f32_e32 v2, v2
	v_exp_f32_e32 v4, v4
	v_mul_f32_e32 v40, 0xbfb8aa3b, v40
	v_mul_f32_e32 v5, 0xbfb8aa3b, v5
	v_mul_f32_e32 v41, 0xbfb8aa3b, v41
	v_mul_f32_e32 v6, 0xbfb8aa3b, v6
	v_fmac_f32_e32 v7, v61, v43
	v_exp_f32_e32 v40, v40
	v_exp_f32_e32 v5, v5
	v_exp_f32_e32 v41, v41
	v_exp_f32_e32 v6, v6
	v_mul_f32_e32 v42, 0xbfb8aa3b, v42
	v_mul_f32_e32 v7, 0xbfb8aa3b, v7
	v_exp_f32_e32 v42, v42
	v_exp_f32_e32 v7, v7
	v_add_f32_e32 v2, 1.0, v2
	v_add_f32_e32 v4, 1.0, v4
	v_rcp_f32_e32 v2, v2
	v_rcp_f32_e32 v4, v4
	v_add_f32_e32 v40, 1.0, v40
	v_add_f32_e32 v5, 1.0, v5
	v_add_f32_e32 v41, 1.0, v41
	v_add_f32_e32 v6, 1.0, v6
	v_rcp_f32_e32 v40, v40
	v_rcp_f32_e32 v5, v5
	v_rcp_f32_e32 v41, v41
	v_rcp_f32_e32 v6, v6
	v_add_f32_e32 v42, 1.0, v42
	v_add_f32_e32 v7, 1.0, v7
	v_rcp_f32_e32 v42, v42
	v_rcp_f32_e32 v7, v7
	v_or_b32_e32 v45, 0x9c0, v44
	v_cvt_pk_bf16_f32 v4, v2, v4
	v_lshlrev_b32_e32 v2, 1, v45
	v_cvt_pk_bf16_f32 v5, v40, v5
	v_cvt_pk_bf16_f32 v6, v41, v6
	v_lshl_add_u64 v[40:41], v[114:115], 0, v[2:3]
	global_load_dwordx4 v[46:49], v[40:41], off
	v_lshl_add_u64 v[40:41], v[110:111], 0, v[2:3]
	v_lshlrev_b32_e32 v2, 2, v45
	v_cvt_pk_bf16_f32 v7, v42, v7
	s_waitcnt vmcnt(4)
	v_lshlrev_b32_e32 v42, 16, v8
	v_and_b32_e32 v8, 0xffff0000, v8
	s_waitcnt vmcnt(3)
	v_lshlrev_b32_e32 v43, 16, v12
	global_load_dwordx4 v[50:53], v[40:41], off
	global_load_dwordx4 v[54:57], v2, s[8:9] offset:16
	global_load_dwordx4 v[58:61], v2, s[8:9]
	v_and_b32_e32 v2, 0xffff0000, v12
	v_fma_f32 v12, v0, v43, -v42
	v_fma_f32 v2, v0, v2, -v8
	s_waitcnt vmcnt(4)
	v_fmac_f32_e32 v42, v36, v12
	v_fmac_f32_e32 v8, v37, v2
	v_lshlrev_b32_e32 v2, 16, v9
	v_lshlrev_b32_e32 v12, 16, v13
	v_and_b32_e32 v9, 0xffff0000, v9
	v_and_b32_e32 v13, 0xffff0000, v13
	v_fma_f32 v12, v0, v12, -v2
	v_fmac_f32_e32 v2, v38, v12
	v_fma_f32 v12, v0, v13, -v9
	v_mul_f32_e32 v8, 0xbfb8aa3b, v8
	v_fmac_f32_e32 v9, v39, v12
	v_lshlrev_b32_e32 v12, 16, v10
	v_lshlrev_b32_e32 v13, 16, v14
	v_exp_f32_e32 v8, v8
	v_and_b32_e32 v10, 0xffff0000, v10
	v_and_b32_e32 v14, 0xffff0000, v14
	v_fma_f32 v13, v0, v13, -v12
	v_fmac_f32_e32 v12, v16, v13
	v_fma_f32 v13, v0, v14, -v10
	v_fmac_f32_e32 v10, v17, v13
	v_lshlrev_b32_e32 v13, 16, v11
	v_lshlrev_b32_e32 v14, 16, v15
	v_and_b32_e32 v11, 0xffff0000, v11
	v_and_b32_e32 v15, 0xffff0000, v15
	v_fma_f32 v14, v0, v14, -v13
	v_mul_f32_e32 v2, 0xbfb8aa3b, v2
	v_add_f32_e32 v8, 1.0, v8
	v_fmac_f32_e32 v13, v18, v14
	v_fma_f32 v14, v0, v15, -v11
	v_exp_f32_e32 v2, v2
	v_rcp_f32_e32 v15, v8
	v_mul_f32_e32 v8, 0xbfb8aa3b, v9
	v_exp_f32_e32 v8, v8
	v_mul_f32_e32 v9, 0xbfb8aa3b, v12
	v_exp_f32_e32 v9, v9
	v_add_f32_e32 v2, 1.0, v2
	v_rcp_f32_e32 v12, v2
	v_add_f32_e32 v2, 1.0, v8
	v_mul_f32_e32 v8, 0xbfb8aa3b, v10
	v_rcp_f32_e32 v45, v2
	v_add_f32_e32 v2, 1.0, v9
	v_exp_f32_e32 v8, v8
	v_mul_f32_e32 v9, 0xbfb8aa3b, v13
	v_mul_f32_e32 v16, 0xbfb8aa3b, v42
	v_exp_f32_e32 v9, v9
	v_exp_f32_e32 v16, v16
	v_rcp_f32_e32 v10, v2
	v_add_f32_e32 v2, 1.0, v8
	v_fmac_f32_e32 v11, v19, v14
	v_rcp_f32_e32 v13, v2
	v_add_f32_e32 v2, 1.0, v9
	v_add_f32_e32 v14, 1.0, v16
	v_rcp_f32_e32 v66, v2
	v_mul_f32_e32 v2, 0xbfb8aa3b, v11
	v_or_b32_e32 v16, 0x9e0, v44
	v_exp_f32_e32 v11, v2
	v_lshlrev_b32_e32 v2, 1, v16
	v_lshl_add_u64 v[8:9], v[114:115], 0, v[2:3]
	global_load_dwordx4 v[36:39], v[8:9], off
	v_lshl_add_u64 v[8:9], v[110:111], 0, v[2:3]
	global_load_dwordx4 v[40:43], v[8:9], off
	v_lshlrev_b32_e32 v2, 2, v16
	global_load_dwordx4 v[16:19], v2, s[8:9] offset:16
	global_load_dwordx4 v[62:65], v2, s[8:9]
	v_add_f32_e32 v2, 1.0, v11
	v_rcp_f32_e32 v2, v2
	v_rcp_f32_e32 v14, v14
	v_cvt_pk_bf16_f32 v10, v10, v13
	v_cvt_pk_bf16_f32 v9, v12, v45
	v_cvt_pk_bf16_f32 v11, v66, v2
	s_waitcnt vmcnt(7)
; __device__ __forceinline__ void rwkv_prep_item(const Params& p, const Lt& lt, int l, int item) {
;     ...
;         if (ks < 2) {
; #pragma unroll
;             for (int i = 0; i < 8; ++i) v[i] = tanhf_(v[i]);
;         } else if (ks >= 4) {
; #pragma unroll
;             for (int i = 0; i < 8; ++i) v[i] = sigmoidf_(v[i]);
;         }
;         u32x4 pk; pk.x = cvt_pk_bf16(v[0], v[1]); pk.y = cvt_pk_bf16(v[2], v[3]); pk.z = cvt_pk_bf16(v[4], v[5]); pk.w = cvt_pk_bf16(v[6], v[7]);
;         const bf16x8 f = __builtin_bit_cast(bf16x8, pk);
;         if (ks < 2) fw[ks] = f; else if (ks < 4) fa[ks - 2] = f; else fg[ks - 4] = f;
;     }
;     unsigned char* opnd = p.ws + WS_OPND; float* gate = (float*)(p.ws + WS_GATE); float* bonus = (float*)(p.ws + WS_BONUS);
;     const float* w0 = p.in[4] + l * RW; const float* a0 = p.in[6] + l * RW; const float* kkp = p.in[9] + l * RW; const float* kap = p.in[10] + l * RW; const float* rkp = p.in[11] + l * RW;
; #pragma unroll
;     for (int hh = 0; hh < 3; ++hh) {
;         const int h = hg * 3 + hh;
;         f32x4 va[4], vkk[4];
;         float nrm = 0.f, bon = 0.f;
;         unsigned char* ob = opnd + (size_t)t * OPTB + h * OPB;
; #pragma unroll
;         for (int ct = 0; ct < 4; ++ct) {
;             const int crow = h * 64 + ct * 16 + qi;
;             f32x4 aw = {0.f, 0.f, 0.f, 0.f}, aa = aw, ag = aw;
; #pragma unroll
;             for (int ks = 0; ks < 2; ++ks) {
;                 aw = __builtin_amdgcn_mfma_f32_16x16x32_bf16(*(const bf16x8*)(decT + crow * 64 + ks * 32 + quad * 8), fw[ks], aw, 0, 0, 0);
;                 aa = __builtin_amdgcn_mfma_f32_16x16x32_bf16(*(const bf16x8*)(aT + crow * 64 + ks * 32 + quad * 8), fa[ks], aa, 0, 0, 0);
;             }
; #pragma unroll
;             for (int ks = 0; ks < 4; ++ks) ag = __builtin_amdgcn_mfma_f32_16x16x32_bf16(*(const bf16x8*)(gT + crow * 128 + ks * 32 + quad * 8), fg[ks], ag, 0, 0, 0);
;             const int c = h * 64 + ct * 16 + quad * 4;
;             const f32x4 mr = *(const f32x4*)(mu + c), mk = *(const f32x4*)(mu + COL_K + c), mv = *(const f32x4*)(mu + COL_V + c);
;             const f32x4 cr = ld_bf4(pt + c), ck = ld_bf4(pt + COL_K + c), cv = ld_bf4(pt + COL_V + c);
;             const f32x4 qr = ld_bf4(pp + c) * pm, qk = ld_bf4(pp + COL_K + c) * pm, qv = ld_bf4(pp + COL_V + c) * pm;
	v_lshlrev_b32_e32 v2, 16, v46
	v_cvt_pk_bf16_f32 v8, v14, v15
	v_and_b32_e32 v12, 0xffff0000, v46
	s_waitcnt vmcnt(6)
	v_lshlrev_b32_e32 v13, 16, v50
	v_and_b32_e32 v14, 0xffff0000, v50
	v_fma_f32 v13, v0, v13, -v2
	s_waitcnt vmcnt(4)
	v_fmac_f32_e32 v2, v58, v13
	v_fma_f32 v13, v0, v14, -v12
	v_fmac_f32_e32 v12, v59, v13
	v_lshlrev_b32_e32 v13, 16, v47
	v_lshlrev_b32_e32 v15, 16, v51
	v_and_b32_e32 v14, 0xffff0000, v47
	v_and_b32_e32 v45, 0xffff0000, v51
	v_fma_f32 v15, v0, v15, -v13
	v_fmac_f32_e32 v13, v60, v15
	v_fma_f32 v15, v0, v45, -v14
	v_fmac_f32_e32 v14, v61, v15
	v_lshlrev_b32_e32 v15, 16, v48
	v_lshlrev_b32_e32 v46, 16, v52
	v_and_b32_e32 v45, 0xffff0000, v48
	v_and_b32_e32 v47, 0xffff0000, v52
	v_fma_f32 v46, v0, v46, -v15
	v_fmac_f32_e32 v15, v54, v46
	v_fma_f32 v46, v0, v47, -v45
	v_fmac_f32_e32 v45, v55, v46
	v_mul_f32_e32 v2, 0xbfb8aa3b, v2
	v_mul_f32_e32 v12, 0xbfb8aa3b, v12
	v_mul_f32_e32 v13, 0xbfb8aa3b, v13
	v_mul_f32_e32 v14, 0xbfb8aa3b, v14
	v_mul_f32_e32 v15, 0xbfb8aa3b, v15
	v_mul_f32_e32 v45, 0xbfb8aa3b, v45
	v_lshlrev_b32_e32 v46, 16, v49
	v_lshlrev_b32_e32 v48, 16, v53
	v_exp_f32_e32 v2, v2
	v_exp_f32_e32 v12, v12
	v_exp_f32_e32 v13, v13
	v_exp_f32_e32 v14, v14
	v_exp_f32_e32 v15, v15
	v_exp_f32_e32 v45, v45
	v_and_b32_e32 v47, 0xffff0000, v49
	v_and_b32_e32 v49, 0xffff0000, v53
	v_fma_f32 v48, v0, v48, -v46
	v_fmac_f32_e32 v46, v56, v48
	v_fma_f32 v48, v0, v49, -v47
	v_fmac_f32_e32 v47, v57, v48
	v_add_f32_e32 v2, 1.0, v2
	v_add_f32_e32 v12, 1.0, v12
	v_add_f32_e32 v13, 1.0, v13
	v_add_f32_e32 v14, 1.0, v14
	v_add_f32_e32 v15, 1.0, v15
	v_add_f32_e32 v45, 1.0, v45
	v_mul_f32_e32 v46, 0xbfb8aa3b, v46
	v_mul_f32_e32 v47, 0xbfb8aa3b, v47
	v_rcp_f32_e32 v2, v2
	v_rcp_f32_e32 v12, v12
	v_rcp_f32_e32 v13, v13
	v_rcp_f32_e32 v14, v14
	v_rcp_f32_e32 v15, v15
	v_exp_f32_e32 v46, v46
	v_exp_f32_e32 v47, v47
	v_rcp_f32_e32 v45, v45
	v_cvt_pk_bf16_f32 v12, v2, v12
	v_add_f32_e32 v46, 1.0, v46
	v_add_f32_e32 v47, 1.0, v47
	v_cvt_pk_bf16_f32 v13, v13, v14
	v_cvt_pk_bf16_f32 v14, v15, v45
	s_waitcnt vmcnt(3)
	v_lshlrev_b32_e32 v2, 16, v36
	v_and_b32_e32 v45, 0xffff0000, v36
	s_waitcnt vmcnt(2)
	v_lshlrev_b32_e32 v36, 16, v40
	v_rcp_f32_e32 v46, v46
	v_rcp_f32_e32 v47, v47
	v_and_b32_e32 v40, 0xffff0000, v40
	v_fma_f32 v36, v0, v36, -v2
	s_waitcnt vmcnt(0)
	v_fmac_f32_e32 v2, v62, v36
	v_fma_f32 v36, v0, v40, -v45
	v_or_b32_e32 v60, s5, v180
	v_fmac_f32_e32 v45, v63, v36
	v_lshlrev_b32_e32 v58, 16, v37
	v_and_b32_e32 v59, 0xffff0000, v37
	v_lshlrev_b32_e32 v36, 7, v60
	v_mov_b32_e32 v37, v3
	v_lshlrev_b32_e32 v50, 16, v41
	v_and_b32_e32 v54, 0xffff0000, v41
	v_lshl_add_u64 v[40:41], v[88:89], 0, v[36:37]
	v_cvt_pk_bf16_f32 v15, v46, v47
	global_load_dwordx4 v[46:49], v[40:41], off
	v_fma_f32 v50, v0, v50, -v58
	v_lshl_add_u64 v[36:37], v[92:93], 0, v[36:37]
	v_fmac_f32_e32 v58, v64, v50
	global_load_dwordx4 v[50:53], v[36:37], off
	global_load_dwordx4 v[68:71], v[36:37], off offset:64
	v_fma_f32 v54, v0, v54, -v59
	v_fmac_f32_e32 v59, v65, v54
	global_load_dwordx4 v[54:57], v[40:41], off offset:64
	v_or_b32_e32 v36, s5, v181
	v_lshlrev_b32_e32 v64, 1, v36
	v_mov_b32_e32 v65, v3
	v_lshlrev_b32_e32 v61, 16, v38
	v_and_b32_e32 v40, 0xffff0000, v38
	v_lshlrev_b32_e32 v38, 16, v42
	v_lshl_add_u64 v[90:91], v[114:115], 0, v[64:65]
	v_and_b32_e32 v41, 0xffff0000, v42
	v_fma_f32 v38, v0, v38, -v61
	global_load_dwordx2 v[98:99], v[90:91], off
	global_load_dwordx2 v[104:105], v[90:91], off offset:3072
	v_fmac_f32_e32 v61, v16, v38
	v_fma_f32 v16, v0, v41, -v40
	v_lshl_add_u64 v[96:97], v[110:111], 0, v[64:65]
	v_fmac_f32_e32 v40, v17, v16
	v_lshlrev_b32_e32 v16, 16, v39
	global_load_dwordx2 v[106:107], v[96:97], off
	global_load_dwordx2 v[66:67], v[90:91], off offset:1536
	v_and_b32_e32 v17, 0xffff0000, v39
	v_lshlrev_b32_e32 v37, 16, v43
	v_and_b32_e32 v38, 0xffff0000, v43
	v_fma_f32 v37, v0, v37, -v16
	v_fma_f32 v38, v0, v38, -v17
	v_lshlrev_b32_e32 v160, 2, v36
	v_fmac_f32_e32 v17, v19, v38
	v_fmac_f32_e32 v16, v18, v37
	global_load_dwordx4 v[36:39], v160, s[8:9]
	global_load_dwordx4 v[72:75], v160, s[42:43]
	global_load_dwordx2 v[108:109], v[96:97], off offset:1536
	global_load_dwordx2 v[120:121], v[96:97], off offset:3072
	global_load_dwordx4 v[76:79], v160, s[44:45]
	v_mul_f32_e32 v17, 0xbfb8aa3b, v17
	v_exp_f32_e32 v17, v17
	v_mul_f32_e32 v2, 0xbfb8aa3b, v2
	v_mul_f32_e32 v18, 0xbfb8aa3b, v58
	v_mul_f32_e32 v41, 0xbfb8aa3b, v59
	v_add_f32_e32 v17, 1.0, v17
	v_rcp_f32_e32 v19, v17
	v_mul_f32_e32 v17, 0xbfb8aa3b, v45
	v_mul_f32_e32 v42, 0xbfb8aa3b, v61
	v_mul_f32_e32 v40, 0xbfb8aa3b, v40
	v_exp_f32_e32 v2, v2
	v_exp_f32_e32 v17, v17
	v_exp_f32_e32 v18, v18
	v_exp_f32_e32 v41, v41
	v_exp_f32_e32 v42, v42
	v_exp_f32_e32 v40, v40
	v_mul_f32_e32 v16, 0xbfb8aa3b, v16
	v_exp_f32_e32 v16, v16
	v_add_f32_e32 v2, 1.0, v2
	v_add_f32_e32 v17, 1.0, v17
	v_add_f32_e32 v18, 1.0, v18
	v_add_f32_e32 v41, 1.0, v41
	v_add_f32_e32 v42, 1.0, v42
	v_add_f32_e32 v40, 1.0, v40
	v_rcp_f32_e32 v2, v2
	v_rcp_f32_e32 v17, v17
	v_rcp_f32_e32 v18, v18
	v_rcp_f32_e32 v41, v41
	v_rcp_f32_e32 v42, v42
	v_rcp_f32_e32 v40, v40
	v_add_f32_e32 v16, 1.0, v16
	v_rcp_f32_e32 v43, v16
	v_cvt_pk_bf16_f32 v16, v2, v17
	v_cvt_pk_bf16_f32 v17, v18, v41
	v_cvt_pk_bf16_f32 v18, v42, v40
	v_mov_b64_e32 v[40:41], s[36:37]
	v_cvt_pk_bf16_f32 v19, v43, v19
	v_mad_i64_i32 v[118:119], s[0:1], v84, s65, v[40:41]
	s_waitcnt vmcnt(12)
	v_mfma_f32_16x16x32_bf16 v[40:43], v[46:49], v[20:23], 0
	v_lshl_add_u64 v[86:87], v[118:119], 0, s[10:11]
	s_mov_b32 s10, 0xbfb8aa3b
	v_mov_b32_e32 v2, v44
	s_waitcnt vmcnt(11)
; __device__ __forceinline__ float sigmoidf_(float x) { return __builtin_amdgcn_rcpf(1.0f + __expf(-x)); }
; __device__ __forceinline__ f32x4 ld_bf4(const bf16_t* q) { const u32x2 u = *(const u32x2*)q; return (f32x4){bflo(u.x), bfhi(u.x), bflo(u.y), bfhi(u.y)}; }
; __device__ __forceinline__ void rwkv_prep_item(const Params& p, const Lt& lt, int l, int item) {
;     ...
;             const int crow = h * 64 + ct * 16 + qi;
;             f32x4 aw = {0.f, 0.f, 0.f, 0.f}, aa = aw, ag = aw;
; #pragma unroll
;             for (int ks = 0; ks < 2; ++ks) {
;                 aw = __builtin_amdgcn_mfma_f32_16x16x32_bf16(*(const bf16x8*)(decT + crow * 64 + ks * 32 + quad * 8), fw[ks], aw, 0, 0, 0);
;                 aa = __builtin_amdgcn_mfma_f32_16x16x32_bf16(*(const bf16x8*)(aT + crow * 64 + ks * 32 + quad * 8), fa[ks], aa, 0, 0, 0);
;             }
; #pragma unroll
;             for (int ks = 0; ks < 4; ++ks) ag = __builtin_amdgcn_mfma_f32_16x16x32_bf16(*(const bf16x8*)(gT + crow * 128 + ks * 32 + quad * 8), fg[ks], ag, 0, 0, 0);
;             const int c = h * 64 + ct * 16 + quad * 4;
;             const f32x4 mr = *(const f32x4*)(mu + c), mk = *(const f32x4*)(mu + COL_K + c), mv = *(const f32x4*)(mu + COL_V + c);
;             const f32x4 cr = ld_bf4(pt + c), ck = ld_bf4(pt + COL_K + c), cv = ld_bf4(pt + COL_V + c);
;             const f32x4 qr = ld_bf4(pp + c) * pm, qk = ld_bf4(pp + COL_K + c) * pm, qv = ld_bf4(pp + COL_V + c) * pm;
;             const f32x4 r = cr + (qr - cr) * mr, k = ck + (qk - ck) * mk, v = cv + (qv - cv) * mv;
;             const f32x4 w0v = *(const f32x4*)(w0 + c), a0v = *(const f32x4*)(a0 + c), kkv = *(const f32x4*)(kkp + c), kav = *(const f32x4*)(kap + c), rkv = *(const f32x4*)(rkp + c);
;             f32x4 dec, a, kk, k2;
; #pragma unroll
;             for (int j = 0; j < 4; ++j) {
;                 const float z = -(w0v[j] + aw[j]);
;                 const float sp = fmaxf(z, 0.f) + __logf(1.0f + __expf(-fabsf(z)));
;                 dec[j] = __expf(-__expf(-sp - 0.5f));
;                 a[j] = sigmoidf_(a0v[j] + aa[j]);
	v_mfma_f32_16x16x32_bf16 v[80:83], v[50:53], v[28:31], 0
	v_mov_b64_e32 v[44:45], s[38:39]
	s_movk_i32 s0, 0x600
	v_mad_i64_i32 v[116:117], s[0:1], v84, s0, v[44:45]
	s_waitcnt vmcnt(9)
	v_mfma_f32_16x16x32_bf16 v[100:103], v[54:57], v[24:27], v[40:43]
	v_lshlrev_b32_e32 v44, 8, v60
	v_mov_b32_e32 v45, v3
	v_lshl_add_u64 v[44:45], v[94:95], 0, v[44:45]
	v_mfma_f32_16x16x32_bf16 v[80:83], v[68:71], v[32:35], v[80:83]
	s_waitcnt vmcnt(8)
	v_lshlrev_b32_e32 v40, 16, v98
	v_and_b32_e32 v41, 0xffff0000, v98
	v_lshlrev_b32_e32 v42, 16, v99
	v_and_b32_e32 v43, 0xffff0000, v99
	v_xor_b32_e32 v123, 0x80000000, v41
	v_xor_b32_e32 v122, 0x80000000, v40
	s_waitcnt vmcnt(6)
	v_lshlrev_b32_e32 v98, 16, v106
	v_and_b32_e32 v99, 0xffff0000, v106
	v_lshlrev_b32_e32 v68, 16, v104
	v_and_b32_e32 v69, 0xffff0000, v104
	v_lshlrev_b32_e32 v70, 16, v105
	v_and_b32_e32 v71, 0xffff0000, v105
	v_lshlrev_b32_e32 v104, 16, v107
	v_and_b32_e32 v105, 0xffff0000, v107
	v_pk_fma_f32 v[122:123], v[0:1], v[98:99], v[122:123] op_sel_hi:[0,1,1]
	v_xor_b32_e32 v99, 0x80000000, v43
	v_xor_b32_e32 v98, 0x80000000, v42
	v_pk_fma_f32 v[98:99], v[0:1], v[104:105], v[98:99] op_sel_hi:[0,1,1]
	s_waitcnt vmcnt(4)
	v_pk_fma_f32 v[98:99], v[38:39], v[98:99], v[42:43]
	s_waitcnt vmcnt(3)
	v_add_f32_e32 v38, v100, v72
	v_pk_fma_f32 v[128:129], v[36:37], v[122:123], v[40:41]
	v_mul_f32_e64 v36, |v38|, s10
	v_exp_f32_e32 v39, v36
	s_waitcnt vmcnt(1)
	v_lshlrev_b32_e32 v106, 16, v120
	v_and_b32_e32 v107, 0xffff0000, v120
	v_xor_b32_e32 v37, 0x80000000, v69
	v_xor_b32_e32 v36, 0x80000000, v68
	v_pk_fma_f32 v[130:131], v[0:1], v[106:107], v[36:37] op_sel_hi:[0,1,1]
	v_add_f32_e32 v36, 1.0, v39
	v_cmp_gt_f32_e32 vcc, s75, v36
	global_load_dwordx4 v[60:63], v[44:45], off
	global_load_dwordx4 v[52:55], v[44:45], off offset:64
	global_load_dwordx4 v[48:51], v[44:45], off offset:128
	s_nop 0
	global_load_dwordx4 v[44:47], v[44:45], off offset:192
	v_cndmask_b32_e64 v39, 0, 32, vcc
	v_ldexp_f32 v36, v36, v39
	v_log_f32_e32 v39, v36
	v_lshlrev_b32_e32 v120, 16, v121
	v_and_b32_e32 v121, 0xffff0000, v121
	v_xor_b32_e32 v37, 0x80000000, v71
	v_xor_b32_e32 v36, 0x80000000, v70
	v_pk_fma_f32 v[140:141], v[0:1], v[120:121], v[36:37] op_sel_hi:[0,1,1]
	v_mul_f32_e32 v37, 0x3f317217, v39
	v_fma_f32 v37, v39, s57, -v37
	v_fmac_f32_e32 v37, 0x3377d1cf, v39
	v_fmac_f32_e32 v37, 0x3f317217, v39
	v_cmp_lt_f32_e64 s[0:1], |v39|, s58
	v_max_f32_e64 v36, -v38, 0
	v_cndmask_b32_e32 v38, 0, v243, vcc
	v_cndmask_b32_e64 v37, v39, v37, s[0:1]
	v_sub_f32_e32 v37, v37, v38
	v_add_f32_e32 v36, v36, v37
	global_load_dwordx4 v[56:59], v160, s[8:9] offset:3072
	v_sub_f32_e32 v36, -0.5, v36
	v_mul_f32_e32 v36, 0x3fb8aa3b, v36
	v_exp_f32_e32 v72, v36
	global_load_dwordx4 v[36:39], v160, s[46:47]
	global_load_dwordx4 v[104:107], v160, s[48:49]
	global_load_dwordx4 v[122:125], v160, s[52:53]
	global_load_dwordx4 v[40:43], v160, s[50:51]
	v_add_f32_e32 v73, v101, v73
	v_mul_f32_e64 v85, |v73|, s10
	v_exp_f32_e32 v85, v85
	s_waitcnt vmcnt(9)
	v_add_f32_e32 v76, v80, v76
	v_mul_f32_e32 v76, 0xbfb8aa3b, v76
	v_max_f32_e64 v73, -v73, 0
	v_add_f32_e32 v80, 1.0, v85
	v_cmp_gt_f32_e32 vcc, s75, v80
	v_add_f32_e32 v74, v102, v74
	v_exp_f32_e32 v76, v76
	v_cndmask_b32_e64 v85, 0, 32, vcc
	v_ldexp_f32 v80, v80, v85
	v_log_f32_e32 v80, v80
	v_add_f32_e32 v76, 1.0, v76
	v_rcp_f32_e32 v100, v76
	v_add_f32_e32 v76, v81, v77
	v_mul_f32_e32 v85, 0x3f317217, v80
	v_fma_f32 v85, v80, s57, -v85
	v_fmac_f32_e32 v85, 0x3377d1cf, v80
	v_fmac_f32_e32 v85, 0x3f317217, v80
	v_cmp_lt_f32_e64 s[0:1], |v80|, s58
	v_mul_f32_e32 v76, 0xbfb8aa3b, v76
	v_exp_f32_e32 v76, v76
	v_cndmask_b32_e64 v80, v80, v85, s[0:1]
	v_cndmask_b32_e32 v85, 0, v243, vcc
	v_sub_f32_e32 v80, v80, v85
	v_add_f32_e32 v73, v73, v80
	v_mul_f32_e64 v80, |v74|, s10
	v_exp_f32_e32 v80, v80
	v_add_f32_e32 v76, 1.0, v76
	v_add_f32_e32 v75, v103, v75
	v_rcp_f32_e32 v101, v76
	v_add_f32_e32 v77, 1.0, v80
	v_cmp_gt_f32_e32 vcc, s75, v77
	v_mul_f32_e64 v76, |v75|, s10
	v_exp_f32_e32 v76, v76
	v_cndmask_b32_e64 v80, 0, 32, vcc
	v_ldexp_f32 v77, v77, v80
	v_log_f32_e32 v77, v77
	v_add_f32_e32 v76, 1.0, v76
	v_max_f32_e64 v74, -v74, 0
	s_waitcnt vmcnt(8)
	v_mfma_f32_16x16x32_bf16 v[60:63], v[60:63], v[4:7], 0
	v_mul_f32_e32 v80, 0x3f317217, v77
	v_fma_f32 v80, v77, s57, -v80
	v_fmac_f32_e32 v80, 0x3377d1cf, v77
	v_fmac_f32_e32 v80, 0x3f317217, v77
	v_cmp_lt_f32_e64 s[0:1], |v77|, s58
	v_max_f32_e64 v75, -v75, 0
	s_waitcnt vmcnt(7)
	v_mfma_f32_16x16x32_bf16 v[52:55], v[52:55], v[8:11], v[60:63]
	v_cndmask_b32_e64 v77, v77, v80, s[0:1]
	v_cndmask_b32_e32 v80, 0, v243, vcc
	v_sub_f32_e32 v77, v77, v80
	v_cmp_gt_f32_e32 vcc, s75, v76
	v_add_f32_e32 v74, v74, v77
	v_add_f32_e32 v77, v82, v78
	v_cndmask_b32_e64 v78, 0, 32, vcc
	v_ldexp_f32 v76, v76, v78
	v_log_f32_e32 v76, v76
	v_mul_f32_e32 v77, 0xbfb8aa3b, v77
	v_exp_f32_e32 v77, v77
	v_sub_f32_e32 v73, -0.5, v73
	v_mul_f32_e32 v78, 0x3f317217, v76
	v_fma_f32 v78, v76, s57, -v78
	v_fmac_f32_e32 v78, 0x3377d1cf, v76
	v_fmac_f32_e32 v78, 0x3f317217, v76
	v_cmp_lt_f32_e64 s[0:1], |v76|, s58
	v_sub_f32_e32 v74, -0.5, v74
	v_mul_f32_e32 v73, 0x3fb8aa3b, v73
	v_cndmask_b32_e64 v76, v76, v78, s[0:1]
	v_cndmask_b32_e32 v78, 0, v243, vcc
	v_sub_f32_e32 v76, v76, v78
	v_add_f32_e32 v75, v75, v76
	v_add_f32_e32 v76, v83, v79
	v_mul_f32_e32 v76, 0xbfb8aa3b, v76
	v_exp_f32_e32 v76, v76
	v_sub_f32_e32 v75, -0.5, v75
	v_mul_f32_e32 v74, 0x3fb8aa3b, v74
	v_mul_f32_e32 v75, 0x3fb8aa3b, v75
	v_exp_f32_e32 v73, v73
	v_exp_f32_e32 v74, v74
	v_exp_f32_e32 v75, v75
	v_add_f32_e32 v77, 1.0, v77
	v_add_f32_e32 v76, 1.0, v76
	s_waitcnt vmcnt(6)
; __device__ __forceinline__ float sigmoidf_(float x) { return __builtin_amdgcn_rcpf(1.0f + __expf(-x)); }
; __device__ __forceinline__ void st_bf4(unsigned char* q, f32x4 v) { u32x2 w; w.x = cvt_pk_bf16(v[0], v[1]); w.y = cvt_pk_bf16(v[2], v[3]); *(u32x2*)q = w; }
; __device__ __forceinline__ void rwkv_prep_item(const Params& p, const Lt& lt, int l, int item) {
;     ...
;             const int crow = h * 64 + ct * 16 + qi;
;             f32x4 aw = {0.f, 0.f, 0.f, 0.f}, aa = aw, ag = aw;
; #pragma unroll
;             for (int ks = 0; ks < 2; ++ks) {
;                 aw = __builtin_amdgcn_mfma_f32_16x16x32_bf16(*(const bf16x8*)(decT + crow * 64 + ks * 32 + quad * 8), fw[ks], aw, 0, 0, 0);
;                 aa = __builtin_amdgcn_mfma_f32_16x16x32_bf16(*(const bf16x8*)(aT + crow * 64 + ks * 32 + quad * 8), fa[ks], aa, 0, 0, 0);
;             }
; #pragma unroll
;             for (int ks = 0; ks < 4; ++ks) ag = __builtin_amdgcn_mfma_f32_16x16x32_bf16(*(const bf16x8*)(gT + crow * 128 + ks * 32 + quad * 8), fg[ks], ag, 0, 0, 0);
;     ...
;             const f32x4 r = cr + (qr - cr) * mr, k = ck + (qk - ck) * mk, v = cv + (qv - cv) * mv;
;             const f32x4 w0v = *(const f32x4*)(w0 + c), a0v = *(const f32x4*)(a0 + c), kkv = *(const f32x4*)(kkp + c), kav = *(const f32x4*)(kap + c), rkv = *(const f32x4*)(rkp + c);
;             f32x4 dec, a, kk, k2;
; #pragma unroll
;             for (int j = 0; j < 4; ++j) {
;                 const float z = -(w0v[j] + aw[j]);
;                 const float sp = fmaxf(z, 0.f) + __logf(1.0f + __expf(-fabsf(z)));
;                 dec[j] = __expf(-__expf(-sp - 0.5f));
;                 a[j] = sigmoidf_(a0v[j] + aa[j]);
;                 kk[j] = k[j] * kkv[j];
;                 nrm += kk[j] * kk[j];
;                 k2[j] = k[j] * (1.0f + (a[j] - 1.0f) * kav[j]);
;                 bon += r[j] * k2[j] * rkv[j];
;             }
;             va[ct] = a; vkk[ct] = kk;
;             { const int cc = ct * 16 + quad * 4; *(f32x4*)(ob + cc * 4) = dec; st_bf4(ob + 512 + cc * 2, k2); st_bf4(ob + 640 + cc * 2, v); st_bf4(ob + 768 + cc * 2, r); }
;             st_bf4((unsigned char*)((bf16_t*)gate + (size_t)t * RW + c), ag);
;         }
	v_mfma_f32_16x16x32_bf16 v[48:51], v[48:51], v[12:15], v[52:55]
	v_rcp_f32_e32 v120, v77
	v_rcp_f32_e32 v121, v76
	v_lshlrev_b32_e32 v78, 16, v66
	v_and_b32_e32 v79, 0xffff0000, v66
	v_lshlrev_b32_e32 v126, 16, v108
	v_and_b32_e32 v127, 0xffff0000, v108
	v_mul_f32_e32 v72, 0xbfb8aa3b, v72
	v_mul_f32_e32 v73, 0xbfb8aa3b, v73
	v_mul_f32_e32 v74, 0xbfb8aa3b, v74
	v_mul_f32_e32 v75, 0xbfb8aa3b, v75
	v_lshlrev_b32_e32 v76, 16, v67
	v_and_b32_e32 v77, 0xffff0000, v67
	v_xor_b32_e32 v81, 0x80000000, v79
	v_xor_b32_e32 v80, 0x80000000, v78
	v_lshlrev_b32_e32 v108, 16, v109
	v_and_b32_e32 v109, 0xffff0000, v109
	v_exp_f32_e32 v72, v72
	v_exp_f32_e32 v73, v73
	v_exp_f32_e32 v74, v74
	v_exp_f32_e32 v75, v75
	v_xor_b32_e32 v67, 0x80000000, v77
	v_xor_b32_e32 v66, 0x80000000, v76
	v_pk_fma_f32 v[80:81], v[0:1], v[126:127], v[80:81] op_sel_hi:[0,1,1]
	s_waitcnt vmcnt(5)
	v_mfma_f32_16x16x32_bf16 v[44:47], v[44:47], v[16:19], v[48:51]
	v_fma_f32 v66, v0, v108, v66
	v_fma_f32 v67, v0, v109, v67
	s_waitcnt vmcnt(4)
	v_pk_fma_f32 v[138:139], v[56:57], v[80:81], v[78:79]
	v_pk_add_f32 v[56:57], v[100:101], -1.0 op_sel_hi:[1,0]
	v_pk_add_f32 v[52:53], v[120:121], -1.0 op_sel_hi:[1,0]
	s_waitcnt vmcnt(2)
	v_pk_fma_f32 v[56:57], v[104:105], v[56:57], 1.0 op_sel_hi:[1,1,0]
	v_pk_fma_f32 v[132:133], v[58:59], v[66:67], v[76:77]
	v_pk_fma_f32 v[52:53], v[106:107], v[52:53], 1.0 op_sel_hi:[1,1,0]
	s_waitcnt vmcnt(1)
	v_pk_fma_f32 v[48:49], v[124:125], v[140:141], v[70:71]
	v_pk_fma_f32 v[50:51], v[122:123], v[130:131], v[68:69]
	s_or_b32 s0, s5, 16
	v_pk_mul_f32 v[136:137], v[138:139], v[56:57]
	v_pk_mul_f32 v[134:135], v[132:133], v[52:53]
	v_lshl_add_u64 v[52:53], v[86:87], 0, v[112:113]
	v_lshl_add_u64 v[122:123], v[86:87], 0, v[2:3]
	v_cvt_pk_bf16_f32 v50, v50, v51
	v_cvt_pk_bf16_f32 v51, v48, v49
	v_cvt_pk_bf16_f32 v48, v128, v129
	v_cvt_pk_bf16_f32 v49, v98, v99
	v_or_b32_e32 v58, s0, v180
	v_sub_u32_e32 v233, v52, v230
	ds_write_b128 v233, v[72:75]
	v_cvt_pk_bf16_f32 v52, v136, v137
	v_cvt_pk_bf16_f32 v53, v134, v135
	v_sub_u32_e32 v233, v122, v230
	ds_write_b64 v233, v[48:49] offset:768
	v_cvt_pk_bf16_f32 v44, v44, v45
	v_cvt_pk_bf16_f32 v45, v46, v47
	v_lshl_add_u64 v[124:125], v[116:117], 0, v[64:65]
	v_lshlrev_b32_e32 v48, 7, v58
	v_mov_b32_e32 v49, v3
	v_sub_u32_e32 v233, v122, v230
	ds_write_b64 v233, v[52:53] offset:512
	v_sub_u32_e32 v233, v122, v230
	ds_write_b64 v233, v[50:51] offset:640
	v_sub_u32_e32 v233, v124, v236
	ds_write_b64 v233, v[44:45]
	v_lshl_add_u64 v[52:53], v[88:89], 0, v[48:49]
	global_load_dwordx4 v[44:47], v[52:53], off
	v_lshl_add_u64 v[56:57], v[92:93], 0, v[48:49]
	global_load_dwordx4 v[48:51], v[56:57], off
	s_nop 0
	global_load_dwordx4 v[52:55], v[52:53], off offset:64
	s_nop 0
	global_load_dwordx4 v[68:71], v[56:57], off offset:64
	global_load_dwordx2 v[76:77], v[90:91], off offset:32
	global_load_dwordx2 v[78:79], v[90:91], off offset:3104
	global_load_dwordx2 v[126:127], v[96:97], off offset:32
	global_load_dwordx2 v[130:131], v[96:97], off offset:1568
	global_load_dwordx2 v[140:141], v[96:97], off offset:3104
	global_load_dwordx4 v[80:83], v160, s[8:9] offset:64
	global_load_dwordx4 v[102:105], v160, s[42:43] offset:64
	global_load_dwordx4 v[106:109], v160, s[44:45] offset:64
	global_load_dwordx2 v[154:155], v[90:91], off offset:1568
	s_waitcnt vmcnt(12)
	v_mfma_f32_16x16x32_bf16 v[44:47], v[44:47], v[20:23], 0
	v_lshlrev_b32_e32 v56, 8, v58
	v_mov_b32_e32 v57, v3
	v_lshl_add_u64 v[56:57], v[94:95], 0, v[56:57]
	s_waitcnt vmcnt(11)
	v_mfma_f32_16x16x32_bf16 v[48:51], v[48:51], v[28:31], 0
	global_load_dwordx4 v[72:75], v[56:57], off
	global_load_dwordx4 v[64:67], v[56:57], off offset:64
	global_load_dwordx4 v[60:63], v[56:57], off offset:128
	s_nop 0
	global_load_dwordx4 v[56:59], v[56:57], off offset:192
	s_waitcnt vmcnt(9)
	v_lshlrev_b32_e32 v156, 16, v130
	v_and_b32_e32 v157, 0xffff0000, v130
	v_mfma_f32_16x16x32_bf16 v[146:149], v[52:55], v[24:27], v[44:47]
	v_lshlrev_b32_e32 v158, 16, v131
	v_and_b32_e32 v159, 0xffff0000, v131
	s_waitcnt vmcnt(8)
	v_lshlrev_b32_e32 v130, 16, v141
	v_or_b32_e32 v44, s0, v181
	v_lshlrev_b32_e32 v44, 2, v44
	v_mfma_f32_16x16x32_bf16 v[150:153], v[68:71], v[32:35], v[48:51]
	global_load_dwordx4 v[68:71], v160, s[8:9] offset:3136
	global_load_dwordx4 v[52:55], v44, s[52:53]
	v_lshlrev_b32_e32 v44, 16, v76
	v_and_b32_e32 v45, 0xffff0000, v76
	v_lshlrev_b32_e32 v46, 16, v77
	v_and_b32_e32 v47, 0xffff0000, v77
	v_lshlrev_b32_e32 v48, 16, v126
	v_and_b32_e32 v49, 0xffff0000, v126
	v_lshlrev_b32_e32 v50, 16, v127
	v_and_b32_e32 v51, 0xffff0000, v127
	v_lshlrev_b32_e32 v126, 16, v140
	v_and_b32_e32 v127, 0xffff0000, v140
	v_and_b32_e32 v131, 0xffff0000, v141
	v_xor_b32_e32 v141, 0x80000000, v45
	v_xor_b32_e32 v140, 0x80000000, v44
	v_pk_fma_f32 v[48:49], v[0:1], v[48:49], v[140:141] op_sel_hi:[0,1,1]
	v_xor_b32_e32 v141, 0x80000000, v47
	v_xor_b32_e32 v140, 0x80000000, v46
	v_pk_fma_f32 v[50:51], v[0:1], v[50:51], v[140:141] op_sel_hi:[0,1,1]
	s_waitcnt vmcnt(9)
	v_pk_fma_f32 v[142:143], v[82:83], v[50:51], v[46:47]
	s_waitcnt vmcnt(8)
; __device__ __forceinline__ float sigmoidf_(float x) { return __builtin_amdgcn_rcpf(1.0f + __expf(-x)); }
; __device__ __forceinline__ f32x4 ld_bf4(const bf16_t* q) { const u32x2 u = *(const u32x2*)q; return (f32x4){bflo(u.x), bfhi(u.x), bflo(u.y), bfhi(u.y)}; }
; __device__ __forceinline__ void rwkv_prep_item(const Params& p, const Lt& lt, int l, int item) {
;     ...
;             const int c = h * 64 + ct * 16 + quad * 4;
;             const f32x4 mr = *(const f32x4*)(mu + c), mk = *(const f32x4*)(mu + COL_K + c), mv = *(const f32x4*)(mu + COL_V + c);
;             const f32x4 cr = ld_bf4(pt + c), ck = ld_bf4(pt + COL_K + c), cv = ld_bf4(pt + COL_V + c);
;             const f32x4 qr = ld_bf4(pp + c) * pm, qk = ld_bf4(pp + COL_K + c) * pm, qv = ld_bf4(pp + COL_V + c) * pm;
;             const f32x4 r = cr + (qr - cr) * mr, k = ck + (qk - ck) * mk, v = cv + (qv - cv) * mv;
;             const f32x4 w0v = *(const f32x4*)(w0 + c), a0v = *(const f32x4*)(a0 + c), kkv = *(const f32x4*)(kkp + c), kav = *(const f32x4*)(kap + c), rkv = *(const f32x4*)(rkp + c);
;             f32x4 dec, a, kk, k2;
; #pragma unroll
;             for (int j = 0; j < 4; ++j) {
;                 const float z = -(w0v[j] + aw[j]);
;                 const float sp = fmaxf(z, 0.f) + __logf(1.0f + __expf(-fabsf(z)));
;                 dec[j] = __expf(-__expf(-sp - 0.5f));
;                 a[j] = sigmoidf_(a0v[j] + aa[j]);
;                 kk[j] = k[j] * kkv[j];
;                 nrm += kk[j] * kk[j];
;                 k2[j] = k[j] * (1.0f + (a[j] - 1.0f) * kav[j]);
;                 bon += r[j] * k2[j] * rkv[j];
	v_add_f32_e32 v46, v146, v102
	v_pk_fma_f32 v[144:145], v[80:81], v[48:49], v[44:45]
	v_mul_f32_e64 v44, |v46|, s10
	v_exp_f32_e32 v47, v44
	v_lshlrev_b32_e32 v76, 16, v78
	v_and_b32_e32 v77, 0xffff0000, v78
	v_xor_b32_e32 v45, 0x80000000, v77
	v_xor_b32_e32 v44, 0x80000000, v76
	v_pk_fma_f32 v[140:141], v[0:1], v[126:127], v[44:45] op_sel_hi:[0,1,1]
	v_add_f32_e32 v44, 1.0, v47
	v_cmp_gt_f32_e32 vcc, s75, v44
	v_lshlrev_b32_e32 v78, 16, v79
	v_and_b32_e32 v79, 0xffff0000, v79
	v_cndmask_b32_e64 v47, 0, 32, vcc
	v_ldexp_f32 v44, v44, v47
	v_log_f32_e32 v47, v44
	v_xor_b32_e32 v45, 0x80000000, v79
	v_xor_b32_e32 v44, 0x80000000, v78
	v_pk_fma_f32 v[162:163], v[0:1], v[130:131], v[44:45] op_sel_hi:[0,1,1]
	v_mul_f32_e32 v45, 0x3f317217, v47
	v_fma_f32 v45, v47, s57, -v45
	v_fmac_f32_e32 v45, 0x3377d1cf, v47
	v_fmac_f32_e32 v45, 0x3f317217, v47
	v_cmp_lt_f32_e64 s[0:1], |v47|, s58
	v_max_f32_e64 v44, -v46, 0
	v_cndmask_b32_e32 v46, 0, v243, vcc
	v_cndmask_b32_e64 v45, v47, v45, s[0:1]
	v_sub_f32_e32 v45, v45, v46
	v_add_f32_e32 v44, v44, v45
	v_sub_f32_e32 v44, -0.5, v44
	v_mul_f32_e32 v44, 0x3fb8aa3b, v44
	v_exp_f32_e32 v85, v44
	global_load_dwordx4 v[48:51], v160, s[46:47] offset:64
	global_load_dwordx4 v[80:83], v160, s[48:49] offset:64
	global_load_dwordx4 v[44:47], v160, s[50:51] offset:64
	v_add_f32_e32 v103, v147, v103
	v_mul_f32_e64 v102, |v103|, s10
	v_exp_f32_e32 v102, v102
	s_waitcnt vmcnt(10)
	v_add_f32_e32 v106, v150, v106
	v_mul_f32_e32 v106, 0xbfb8aa3b, v106
	v_exp_f32_e32 v106, v106
	v_add_f32_e32 v102, 1.0, v102
	v_cmp_gt_f32_e32 vcc, s75, v102
	v_mul_f32_e32 v85, 0xbfb8aa3b, v85
	v_max_f32_e64 v103, -v103, 0
	v_cndmask_b32_e64 v126, 0, 32, vcc
	v_ldexp_f32 v102, v102, v126
	v_log_f32_e32 v126, v102
	v_exp_f32_e32 v102, v85
	v_add_f32_e32 v85, 1.0, v106
	v_add_f32_e32 v104, v148, v104
	v_mul_f32_e32 v106, 0x3f317217, v126
	v_fma_f32 v106, v126, s57, -v106
	v_fmac_f32_e32 v106, 0x3377d1cf, v126
	v_fmac_f32_e32 v106, 0x3f317217, v126
	v_cmp_lt_f32_e64 s[0:1], |v126|, s58
	v_add_f32_e32 v105, v149, v105
	s_waitcnt vmcnt(8)
	v_mfma_f32_16x16x32_bf16 v[72:75], v[72:75], v[4:7], 0
	v_cndmask_b32_e64 v106, v126, v106, s[0:1]
	v_cndmask_b32_e32 v126, 0, v243, vcc
	v_sub_f32_e32 v106, v106, v126
	v_add_f32_e32 v103, v103, v106
	v_mul_f32_e64 v106, |v104|, s10
	v_sub_f32_e32 v103, -0.5, v103
	v_exp_f32_e32 v106, v106
	v_mul_f32_e32 v103, 0x3fb8aa3b, v103
	v_exp_f32_e32 v103, v103
	v_rcp_f32_e32 v126, v85
	v_add_f32_e32 v106, 1.0, v106
	v_cmp_gt_f32_e32 vcc, s75, v106
	v_mul_f32_e32 v85, 0xbfb8aa3b, v103
	v_add_f32_e32 v103, v151, v107
	v_cndmask_b32_e64 v107, 0, 32, vcc
	v_ldexp_f32 v106, v106, v107
	v_log_f32_e32 v106, v106
	v_mul_f32_e32 v103, 0xbfb8aa3b, v103
	v_exp_f32_e32 v107, v103
	v_max_f32_e64 v103, -v104, 0
	v_mul_f32_e32 v104, 0x3f317217, v106
	v_fma_f32 v104, v106, s57, -v104
	v_fmac_f32_e32 v104, 0x3377d1cf, v106
	v_fmac_f32_e32 v104, 0x3f317217, v106
	v_cmp_lt_f32_e64 s[0:1], |v106|, s58
	s_waitcnt vmcnt(7)
	v_mfma_f32_16x16x32_bf16 v[64:67], v[64:67], v[8:11], v[72:75]
	s_waitcnt vmcnt(3)
	v_pk_fma_f32 v[54:55], v[54:55], v[162:163], v[78:79]
	v_cndmask_b32_e64 v104, v106, v104, s[0:1]
	v_cndmask_b32_e32 v106, 0, v243, vcc
	v_sub_f32_e32 v104, v104, v106
	v_add_f32_e32 v103, v103, v104
	v_sub_f32_e32 v103, -0.5, v103
	v_mul_f32_e32 v103, 0x3fb8aa3b, v103
	v_exp_f32_e32 v104, v103
	v_exp_f32_e32 v103, v85
	v_add_f32_e32 v85, 1.0, v107
	v_rcp_f32_e32 v127, v85
	v_mul_f32_e32 v85, 0xbfb8aa3b, v104
	v_mul_f32_e64 v104, |v105|, s10
	v_exp_f32_e32 v104, v104
	v_add_f32_e32 v106, v152, v108
	v_mul_f32_e32 v106, 0xbfb8aa3b, v106
	v_exp_f32_e32 v106, v106
	v_add_f32_e32 v104, 1.0, v104
	v_cmp_gt_f32_e32 vcc, s75, v104
	v_max_f32_e64 v105, -v105, 0
	v_mfma_f32_16x16x32_bf16 v[60:63], v[60:63], v[12:15], v[64:67]
	v_cndmask_b32_e64 v107, 0, 32, vcc
	v_ldexp_f32 v104, v104, v107
	v_log_f32_e32 v107, v104
	v_exp_f32_e32 v104, v85
	v_add_f32_e32 v85, 1.0, v106
	v_rcp_f32_e32 v130, v85
	v_mul_f32_e32 v106, 0x3f317217, v107
	v_fma_f32 v106, v107, s57, -v106
	v_fmac_f32_e32 v106, 0x3377d1cf, v107
	v_fmac_f32_e32 v106, 0x3f317217, v107
	v_cmp_lt_f32_e64 s[0:1], |v107|, s58
	v_lshlrev_b32_e32 v108, 16, v154
	v_xor_b32_e32 v148, 0x80000000, v108
	v_cndmask_b32_e64 v106, v107, v106, s[0:1]
	v_cndmask_b32_e32 v107, 0, v243, vcc
	v_sub_f32_e32 v106, v106, v107
	v_add_f32_e32 v105, v105, v106
	v_sub_f32_e32 v105, -0.5, v105
	v_mul_f32_e32 v105, 0x3fb8aa3b, v105
	v_add_f32_e32 v106, v153, v109
	v_exp_f32_e32 v105, v105
	v_mul_f32_e32 v106, 0xbfb8aa3b, v106
	v_exp_f32_e32 v106, v106
	v_and_b32_e32 v107, 0xffff0000, v155
	v_mul_f32_e32 v85, 0xbfb8aa3b, v105
	v_exp_f32_e32 v105, v85
	v_add_f32_e32 v85, 1.0, v106
	v_rcp_f32_e32 v131, v85
	v_lshlrev_b32_e32 v106, 16, v155
	v_and_b32_e32 v109, 0xffff0000, v154
	v_xor_b32_e32 v147, 0x80000000, v107
	v_xor_b32_e32 v146, 0x80000000, v106
	v_xor_b32_e32 v149, 0x80000000, v109
	v_pk_fma_f32 v[146:147], v[0:1], v[158:159], v[146:147] op_sel_hi:[0,1,1]
	v_pk_fma_f32 v[148:149], v[0:1], v[156:157], v[148:149] op_sel_hi:[0,1,1]
	v_mfma_f32_16x16x32_bf16 v[56:59], v[56:59], v[16:19], v[60:63]
	v_fma_f32 v152, v68, v148, v108
	v_fma_f32 v153, v69, v149, v109
	v_pk_fma_f32 v[148:149], v[70:71], v[146:147], v[106:107]
	v_mov_b32_e32 v107, v3
	v_or_b32_e32 v62, 16, v181
	v_lshlrev_b32_e32 v106, 2, v62
	v_pk_add_f32 v[68:69], v[126:127], -1.0 op_sel_hi:[1,0]
	v_pk_add_f32 v[64:65], v[130:131], -1.0 op_sel_hi:[1,0]
	v_pk_fma_f32 v[52:53], v[52:53], v[140:141], v[76:77]
	v_lshl_add_u64 v[60:61], v[86:87], 0, v[106:107]
	v_lshlrev_b32_e32 v108, 1, v62
	v_mov_b32_e32 v109, v3
	s_waitcnt vmcnt(1)
; __device__ __forceinline__ float sigmoidf_(float x) { return __builtin_amdgcn_rcpf(1.0f + __expf(-x)); }
; __device__ __forceinline__ void rwkv_prep_item(const Params& p, const Lt& lt, int l, int item) {
;     ...
;             const int crow = h * 64 + ct * 16 + qi;
;             f32x4 aw = {0.f, 0.f, 0.f, 0.f}, aa = aw, ag = aw;
; #pragma unroll
;             for (int ks = 0; ks < 2; ++ks) {
;                 aw = __builtin_amdgcn_mfma_f32_16x16x32_bf16(*(const bf16x8*)(decT + crow * 64 + ks * 32 + quad * 8), fw[ks], aw, 0, 0, 0);
;                 aa = __builtin_amdgcn_mfma_f32_16x16x32_bf16(*(const bf16x8*)(aT + crow * 64 + ks * 32 + quad * 8), fa[ks], aa, 0, 0, 0);
;             }
; #pragma unroll
;             for (int ks = 0; ks < 4; ++ks) ag = __builtin_amdgcn_mfma_f32_16x16x32_bf16(*(const bf16x8*)(gT + crow * 128 + ks * 32 + quad * 8), fg[ks], ag, 0, 0, 0);
;             const int c = h * 64 + ct * 16 + quad * 4;
;             const f32x4 mr = *(const f32x4*)(mu + c), mk = *(const f32x4*)(mu + COL_K + c), mv = *(const f32x4*)(mu + COL_V + c);
;             const f32x4 cr = ld_bf4(pt + c), ck = ld_bf4(pt + COL_K + c), cv = ld_bf4(pt + COL_V + c);
;             const f32x4 qr = ld_bf4(pp + c) * pm, qk = ld_bf4(pp + COL_K + c) * pm, qv = ld_bf4(pp + COL_V + c) * pm;
;             const f32x4 r = cr + (qr - cr) * mr, k = ck + (qk - ck) * mk, v = cv + (qv - cv) * mv;
;             const f32x4 w0v = *(const f32x4*)(w0 + c), a0v = *(const f32x4*)(a0 + c), kkv = *(const f32x4*)(kkp + c), kav = *(const f32x4*)(kap + c), rkv = *(const f32x4*)(rkp + c);
;             f32x4 dec, a, kk, k2;
; #pragma unroll
;             for (int j = 0; j < 4; ++j) {
;                 const float z = -(w0v[j] + aw[j]);
;                 const float sp = fmaxf(z, 0.f) + __logf(1.0f + __expf(-fabsf(z)));
;                 dec[j] = __expf(-__expf(-sp - 0.5f));
;                 a[j] = sigmoidf_(a0v[j] + aa[j]);
;     ...
;                 k2[j] = k[j] * (1.0f + (a[j] - 1.0f) * kav[j]);
;                 bon += r[j] * k2[j] * rkv[j];
;             }
;             va[ct] = a; vkk[ct] = kk;
;             { const int cc = ct * 16 + quad * 4; *(f32x4*)(ob + cc * 4) = dec; st_bf4(ob + 512 + cc * 2, k2); st_bf4(ob + 640 + cc * 2, v); st_bf4(ob + 768 + cc * 2, r); }
;             st_bf4((unsigned char*)((bf16_t*)gate + (size_t)t * RW + c), ag);
;         }
	v_pk_fma_f32 v[68:69], v[80:81], v[68:69], 1.0 op_sel_hi:[1,1,0]
	v_pk_fma_f32 v[64:65], v[82:83], v[64:65], 1.0 op_sel_hi:[1,1,0]
	v_sub_u32_e32 v233, v60, v230
	ds_write_b128 v233, v[102:105]
	v_lshl_add_u64 v[60:61], v[86:87], 0, v[108:109]
	v_cvt_pk_bf16_f32 v52, v52, v53
	v_cvt_pk_bf16_f32 v53, v54, v55
	s_or_b32 s0, s5, 32
	v_pk_mul_f32 v[154:155], v[152:153], v[68:69]
	v_pk_mul_f32 v[150:151], v[148:149], v[64:65]
	v_sub_u32_e32 v233, v60, v230
	ds_write_b64 v233, v[52:53] offset:640
	v_cvt_pk_bf16_f32 v52, v144, v145
	v_cvt_pk_bf16_f32 v53, v142, v143
	v_or_b32_e32 v66, s0, v180
	v_cvt_pk_bf16_f32 v62, v154, v155
	v_cvt_pk_bf16_f32 v63, v150, v151
	v_sub_u32_e32 v233, v60, v230
	ds_write_b64 v233, v[52:53] offset:768
	v_cvt_pk_bf16_f32 v52, v56, v57
	v_cvt_pk_bf16_f32 v53, v58, v59
	v_lshlrev_b32_e32 v56, 7, v66
	v_mov_b32_e32 v57, v3
	v_sub_u32_e32 v233, v60, v230
	ds_write_b64 v233, v[62:63] offset:512
	v_sub_u32_e32 v233, v124, v236
	ds_write_b64 v233, v[52:53] offset:32
	v_lshl_add_u64 v[60:61], v[88:89], 0, v[56:57]
	global_load_dwordx4 v[52:55], v[60:61], off
	v_lshl_add_u64 v[64:65], v[92:93], 0, v[56:57]
	global_load_dwordx4 v[56:59], v[64:65], off
	s_nop 0
	global_load_dwordx4 v[60:63], v[60:61], off offset:64
	s_nop 0
	global_load_dwordx4 v[76:79], v[64:65], off offset:64
	global_load_dwordx2 v[102:103], v[90:91], off offset:64
	global_load_dwordx2 v[104:105], v[90:91], off offset:3136
	global_load_dwordx2 v[140:141], v[96:97], off offset:64
	global_load_dwordx2 v[146:147], v[96:97], off offset:1600
	global_load_dwordx2 v[156:157], v[96:97], off offset:3136
	global_load_dwordx4 v[162:165], v160, s[8:9] offset:128
	global_load_dwordx4 v[166:169], v160, s[42:43] offset:128
	global_load_dwordx4 v[170:173], v160, s[44:45] offset:128
	global_load_dwordx2 v[178:179], v[90:91], off offset:1600
	s_waitcnt vmcnt(12)
	v_mfma_f32_16x16x32_bf16 v[52:55], v[52:55], v[20:23], 0
	v_lshlrev_b32_e32 v64, 8, v66
	v_mov_b32_e32 v65, v3
	v_lshl_add_u64 v[64:65], v[94:95], 0, v[64:65]
	s_waitcnt vmcnt(11)
	v_mfma_f32_16x16x32_bf16 v[56:59], v[56:59], v[28:31], 0
	global_load_dwordx4 v[80:83], v[64:65], off
	global_load_dwordx4 v[72:75], v[64:65], off offset:64
	global_load_dwordx4 v[68:71], v[64:65], off offset:128
	s_nop 0
	global_load_dwordx4 v[64:67], v[64:65], off offset:192
	s_waitcnt vmcnt(9)
	v_lshlrev_b32_e32 v186, 16, v146
	v_and_b32_e32 v187, 0xffff0000, v146
	v_mfma_f32_16x16x32_bf16 v[174:177], v[60:63], v[24:27], v[52:55]
	v_lshlrev_b32_e32 v188, 16, v147
	v_and_b32_e32 v189, 0xffff0000, v147
	s_waitcnt vmcnt(8)
	v_lshlrev_b32_e32 v146, 16, v157
	v_or_b32_e32 v52, s0, v181
	v_lshlrev_b32_e32 v52, 2, v52
	v_mfma_f32_16x16x32_bf16 v[182:185], v[76:79], v[32:35], v[56:59]
	global_load_dwordx4 v[76:79], v160, s[8:9] offset:3200
	global_load_dwordx4 v[60:63], v52, s[52:53]
	v_lshlrev_b32_e32 v52, 16, v102
	v_and_b32_e32 v53, 0xffff0000, v102
	v_lshlrev_b32_e32 v54, 16, v103
	v_and_b32_e32 v55, 0xffff0000, v103
	v_lshlrev_b32_e32 v56, 16, v140
	v_and_b32_e32 v57, 0xffff0000, v140
	v_lshlrev_b32_e32 v58, 16, v141
	v_and_b32_e32 v59, 0xffff0000, v141
	v_lshlrev_b32_e32 v140, 16, v156
	v_and_b32_e32 v141, 0xffff0000, v156
	v_and_b32_e32 v147, 0xffff0000, v157
	v_xor_b32_e32 v157, 0x80000000, v53
	v_xor_b32_e32 v156, 0x80000000, v52
	v_pk_fma_f32 v[56:57], v[0:1], v[56:57], v[156:157] op_sel_hi:[0,1,1]
	v_xor_b32_e32 v157, 0x80000000, v55
	v_xor_b32_e32 v156, 0x80000000, v54
	v_pk_fma_f32 v[58:59], v[0:1], v[58:59], v[156:157] op_sel_hi:[0,1,1]
	s_waitcnt vmcnt(9)
	v_pk_fma_f32 v[156:157], v[164:165], v[58:59], v[54:55]
	s_waitcnt vmcnt(8)
	v_add_f32_e32 v54, v174, v166
	v_pk_fma_f32 v[158:159], v[162:163], v[56:57], v[52:53]
	v_mul_f32_e64 v52, |v54|, s10
	v_exp_f32_e32 v55, v52
	v_lshlrev_b32_e32 v102, 16, v104
	v_and_b32_e32 v103, 0xffff0000, v104
	v_xor_b32_e32 v53, 0x80000000, v103
	v_xor_b32_e32 v52, 0x80000000, v102
	v_pk_fma_f32 v[190:191], v[0:1], v[140:141], v[52:53] op_sel_hi:[0,1,1]
	v_add_f32_e32 v52, 1.0, v55
	v_cmp_gt_f32_e32 vcc, s75, v52
	v_lshlrev_b32_e32 v104, 16, v105
	v_and_b32_e32 v105, 0xffff0000, v105
	v_cndmask_b32_e64 v55, 0, 32, vcc
	v_ldexp_f32 v52, v52, v55
	v_log_f32_e32 v55, v52
	v_xor_b32_e32 v53, 0x80000000, v105
	v_xor_b32_e32 v52, 0x80000000, v104
	v_pk_fma_f32 v[192:193], v[0:1], v[146:147], v[52:53] op_sel_hi:[0,1,1]
	v_mul_f32_e32 v53, 0x3f317217, v55
	v_fma_f32 v53, v55, s57, -v53
	v_fmac_f32_e32 v53, 0x3377d1cf, v55
	v_fmac_f32_e32 v53, 0x3f317217, v55
	v_cmp_lt_f32_e64 s[0:1], |v55|, s58
	v_max_f32_e64 v52, -v54, 0
	v_cndmask_b32_e32 v54, 0, v243, vcc
	v_cndmask_b32_e64 v53, v55, v53, s[0:1]
	v_add_f32_e32 v140, v175, v167
	v_sub_f32_e32 v53, v53, v54
	v_mul_f32_e64 v141, |v140|, s10
	v_add_f32_e32 v52, v52, v53
	v_exp_f32_e32 v141, v141
	v_sub_f32_e32 v52, -0.5, v52
	v_mul_f32_e32 v52, 0x3fb8aa3b, v52
	v_exp_f32_e32 v85, v52
	global_load_dwordx4 v[56:59], v160, s[46:47] offset:128
	global_load_dwordx4 v[162:165], v160, s[48:49] offset:128
	global_load_dwordx4 v[52:55], v160, s[50:51] offset:128
	v_add_f32_e32 v141, 1.0, v141
	v_cmp_gt_f32_e32 vcc, s75, v141
	s_waitcnt vmcnt(10)
	v_add_f32_e32 v146, v182, v170
	v_mul_f32_e32 v146, 0xbfb8aa3b, v146
	v_cndmask_b32_e64 v147, 0, 32, vcc
	v_ldexp_f32 v141, v141, v147
	v_exp_f32_e32 v146, v146
	v_log_f32_e32 v141, v141
	v_mul_f32_e32 v85, 0xbfb8aa3b, v85
	v_exp_f32_e32 v166, v85
	v_add_f32_e32 v85, 1.0, v146
	v_mul_f32_e32 v146, 0x3f317217, v141
	v_fma_f32 v146, v141, s57, -v146
	v_fmac_f32_e32 v146, 0x3377d1cf, v141
	v_fmac_f32_e32 v146, 0x3f317217, v141
	v_cmp_lt_f32_e64 s[0:1], |v141|, s58
	v_max_f32_e64 v140, -v140, 0
	s_waitcnt vmcnt(8)
; __device__ __forceinline__ void rwkv_prep_item(const Params& p, const Lt& lt, int l, int item) {
;     ...
;         for (int ct = 0; ct < 4; ++ct) {
;             const int crow = h * 64 + ct * 16 + qi;
;             f32x4 aw = {0.f, 0.f, 0.f, 0.f}, aa = aw, ag = aw;
; #pragma unroll
;             for (int ks = 0; ks < 2; ++ks) {
;                 aw = __builtin_amdgcn_mfma_f32_16x16x32_bf16(*(const bf16x8*)(decT + crow * 64 + ks * 32 + quad * 8), fw[ks], aw, 0, 0, 0);
;                 aa = __builtin_amdgcn_mfma_f32_16x16x32_bf16(*(const bf16x8*)(aT + crow * 64 + ks * 32 + quad * 8), fa[ks], aa, 0, 0, 0);
;             }
; #pragma unroll
;             for (int ks = 0; ks < 4; ++ks) ag = __builtin_amdgcn_mfma_f32_16x16x32_bf16(*(const bf16x8*)(gT + crow * 128 + ks * 32 + quad * 8), fg[ks], ag, 0, 0, 0);
;             const int c = h * 64 + ct * 16 + quad * 4;
;             const f32x4 mr = *(const f32x4*)(mu + c), mk = *(const f32x4*)(mu + COL_K + c), mv = *(const f32x4*)(mu + COL_V + c);
;             const f32x4 cr = ld_bf4(pt + c), ck = ld_bf4(pt + COL_K + c), cv = ld_bf4(pt + COL_V + c);
;             const f32x4 qr = ld_bf4(pp + c) * pm, qk = ld_bf4(pp + COL_K + c) * pm, qv = ld_bf4(pp + COL_V + c) * pm;
;             const f32x4 r = cr + (qr - cr) * mr, k = ck + (qk - ck) * mk, v = cv + (qv - cv) * mv;
;             const f32x4 w0v = *(const f32x4*)(w0 + c), a0v = *(const f32x4*)(a0 + c), kkv = *(const f32x4*)(kkp + c), kav = *(const f32x4*)(kap + c), rkv = *(const f32x4*)(rkp + c);
;             f32x4 dec, a, kk, k2;
; #pragma unroll
;             for (int j = 0; j < 4; ++j) {
;                 const float z = -(w0v[j] + aw[j]);
;                 const float sp = fmaxf(z, 0.f) + __logf(1.0f + __expf(-fabsf(z)));
;                 dec[j] = __expf(-__expf(-sp - 0.5f));
;                 a[j] = sigmoidf_(a0v[j] + aa[j]);
;                 kk[j] = k[j] * kkv[j];
;                 nrm += kk[j] * kk[j];
;                 k2[j] = k[j] * (1.0f + (a[j] - 1.0f) * kav[j]);
;                 bon += r[j] * k2[j] * rkv[j];
;             }
;             va[ct] = a; vkk[ct] = kk;
;             { const int cc = ct * 16 + quad * 4; *(f32x4*)(ob + cc * 4) = dec; st_bf4(ob + 512 + cc * 2, k2); st_bf4(ob + 640 + cc * 2, v); st_bf4(ob + 768 + cc * 2, r); }
;             st_bf4((unsigned char*)((bf16_t*)gate + (size_t)t * RW + c), ag);
;         }
	v_mfma_f32_16x16x32_bf16 v[80:83], v[80:83], v[4:7], 0
	v_cndmask_b32_e64 v141, v141, v146, s[0:1]
	v_cndmask_b32_e32 v146, 0, v243, vcc
	v_sub_f32_e32 v141, v141, v146
	v_add_f32_e32 v140, v140, v141
	v_sub_f32_e32 v140, -0.5, v140
	v_mul_f32_e32 v140, 0x3fb8aa3b, v140
	v_add_f32_e32 v146, v176, v168
	v_exp_f32_e32 v141, v140
	v_mul_f32_e64 v140, |v146|, s10
	v_exp_f32_e32 v147, v140
	v_max_f32_e64 v146, -v146, 0
	v_rcp_f32_e32 v140, v85
	v_mul_f32_e32 v85, 0xbfb8aa3b, v141
	v_add_f32_e32 v147, 1.0, v147
	v_cmp_gt_f32_e32 vcc, s75, v147
	v_add_f32_e32 v141, v183, v171
	v_mul_f32_e32 v141, 0xbfb8aa3b, v141
	v_cndmask_b32_e64 v161, 0, 32, vcc
	v_ldexp_f32 v147, v147, v161
	v_log_f32_e32 v147, v147
	v_exp_f32_e32 v141, v141
	v_exp_f32_e32 v167, v85
	s_waitcnt vmcnt(7)
	v_mfma_f32_16x16x32_bf16 v[72:75], v[72:75], v[8:11], v[80:83]
	v_mul_f32_e32 v161, 0x3f317217, v147
	v_fma_f32 v161, v147, s57, -v161
	v_fmac_f32_e32 v161, 0x3377d1cf, v147
	v_fmac_f32_e32 v161, 0x3f317217, v147
	v_cmp_lt_f32_e64 s[0:1], |v147|, s58
	v_add_f32_e32 v85, 1.0, v141
	v_rcp_f32_e32 v141, v85
	v_cndmask_b32_e64 v147, v147, v161, s[0:1]
	v_cndmask_b32_e32 v161, 0, v243, vcc
	v_sub_f32_e32 v147, v147, v161
	v_add_f32_e32 v146, v146, v147
	v_sub_f32_e32 v146, -0.5, v146
	v_mul_f32_e32 v146, 0x3fb8aa3b, v146
	v_exp_f32_e32 v146, v146
	v_add_f32_e32 v161, v184, v172
	v_mul_f32_e32 v161, 0xbfb8aa3b, v161
	v_exp_f32_e32 v161, v161
	v_mul_f32_e32 v85, 0xbfb8aa3b, v146
	v_add_f32_e32 v146, v177, v169
	v_mul_f32_e64 v147, |v146|, s10
	v_exp_f32_e32 v147, v147
	v_max_f32_e64 v146, -v146, 0
	s_waitcnt vmcnt(6)
	v_mfma_f32_16x16x32_bf16 v[68:71], v[68:71], v[12:15], v[72:75]
	v_lshlrev_b32_e32 v172, 16, v178
	v_add_f32_e32 v147, 1.0, v147
	v_cmp_gt_f32_e32 vcc, s75, v147
	v_lshlrev_b32_e32 v170, 16, v179
	v_and_b32_e32 v171, 0xffff0000, v179
	v_cndmask_b32_e64 v168, 0, 32, vcc
	v_ldexp_f32 v147, v147, v168
	v_log_f32_e32 v147, v147
	v_exp_f32_e32 v168, v85
	v_add_f32_e32 v85, 1.0, v161
	v_xor_b32_e32 v176, 0x80000000, v172
	v_mul_f32_e32 v161, 0x3f317217, v147
	v_fma_f32 v161, v147, s57, -v161
	v_fmac_f32_e32 v161, 0x3377d1cf, v147
	v_fmac_f32_e32 v161, 0x3f317217, v147
	v_cmp_lt_f32_e64 s[0:1], |v147|, s58
	s_waitcnt vmcnt(5)
	v_mfma_f32_16x16x32_bf16 v[64:67], v[64:67], v[16:19], v[68:71]
	v_xor_b32_e32 v175, 0x80000000, v171
	v_cndmask_b32_e64 v147, v147, v161, s[0:1]
	v_cndmask_b32_e32 v161, 0, v243, vcc
	v_sub_f32_e32 v147, v147, v161
	v_add_f32_e32 v146, v146, v147
	v_sub_f32_e32 v146, -0.5, v146
	v_mul_f32_e32 v146, 0x3fb8aa3b, v146
	v_exp_f32_e32 v147, v146
	v_add_f32_e32 v146, v185, v173
	v_mul_f32_e32 v146, 0xbfb8aa3b, v146
	v_exp_f32_e32 v161, v146
	v_rcp_f32_e32 v146, v85
	v_mul_f32_e32 v85, 0xbfb8aa3b, v147
	v_exp_f32_e32 v169, v85
	v_add_f32_e32 v85, 1.0, v161
	v_rcp_f32_e32 v147, v85
	v_and_b32_e32 v173, 0xffff0000, v178
	v_xor_b32_e32 v177, 0x80000000, v173
	v_or_b32_e32 v70, 32, v181
	v_xor_b32_e32 v174, 0x80000000, v170
	v_pk_fma_f32 v[176:177], v[0:1], v[186:187], v[176:177] op_sel_hi:[0,1,1]
	s_waitcnt vmcnt(3)
	v_pk_fma_f32 v[60:61], v[60:61], v[190:191], v[102:103]
	v_lshlrev_b32_e32 v102, 2, v70
	v_mov_b32_e32 v103, v3
	v_pk_fma_f32 v[174:175], v[0:1], v[188:189], v[174:175] op_sel_hi:[0,1,1]
	v_pk_fma_f32 v[76:77], v[76:77], v[176:177], v[172:173]
	v_pk_add_f32 v[172:173], v[140:141], -1.0 op_sel_hi:[1,0]
	v_pk_add_f32 v[72:73], v[146:147], -1.0 op_sel_hi:[1,0]
	v_pk_fma_f32 v[62:63], v[62:63], v[192:193], v[104:105]
	v_lshl_add_u64 v[68:69], v[86:87], 0, v[102:103]
	v_lshlrev_b32_e32 v104, 1, v70
	v_mov_b32_e32 v105, v3
	s_waitcnt vmcnt(1)
	v_pk_fma_f32 v[80:81], v[162:163], v[172:173], 1.0 op_sel_hi:[1,1,0]
	v_pk_fma_f32 v[170:171], v[78:79], v[174:175], v[170:171]
	v_pk_fma_f32 v[72:73], v[164:165], v[72:73], 1.0 op_sel_hi:[1,1,0]
	v_sub_u32_e32 v233, v68, v230
	ds_write_b128 v233, v[166:169]
	v_lshl_add_u64 v[68:69], v[86:87], 0, v[104:105]
	v_cvt_pk_bf16_f32 v60, v60, v61
	v_cvt_pk_bf16_f32 v61, v62, v63
	s_or_b32 s0, s5, 48
	v_pk_mul_f32 v[162:163], v[76:77], v[80:81]
	v_pk_mul_f32 v[164:165], v[170:171], v[72:73]
	v_sub_u32_e32 v233, v68, v230
	ds_write_b64 v233, v[60:61] offset:640
	v_cvt_pk_bf16_f32 v60, v158, v159
	v_cvt_pk_bf16_f32 v61, v156, v157
	v_or_b32_e32 v161, s0, v180
	v_cvt_pk_bf16_f32 v70, v162, v163
	v_cvt_pk_bf16_f32 v71, v164, v165
	v_sub_u32_e32 v233, v68, v230
	ds_write_b64 v233, v[60:61] offset:768
	v_cvt_pk_bf16_f32 v60, v64, v65
	v_cvt_pk_bf16_f32 v61, v66, v67
	v_lshlrev_b32_e32 v64, 7, v161
	v_mov_b32_e32 v65, v3
	v_sub_u32_e32 v233, v68, v230
	ds_write_b64 v233, v[70:71] offset:512
	v_sub_u32_e32 v233, v124, v236
	ds_write_b64 v233, v[60:61] offset:64
	v_lshl_add_u64 v[68:69], v[88:89], 0, v[64:65]
	global_load_dwordx4 v[60:63], v[68:69], off
	v_lshl_add_u64 v[70:71], v[92:93], 0, v[64:65]
	global_load_dwordx4 v[64:67], v[70:71], off
	global_load_dwordx4 v[72:75], v[68:69], off offset:64
	global_load_dwordx4 v[80:83], v[70:71], off offset:64
	global_load_dwordx2 v[166:167], v[90:91], off offset:96
	global_load_dwordx2 v[168:169], v[90:91], off offset:1632
	global_load_dwordx2 v[172:173], v[90:91], off offset:3168
	global_load_dwordx2 v[174:175], v[96:97], off offset:96
	global_load_dwordx2 v[176:177], v[96:97], off offset:1632
	v_and_b32_e32 v69, 64, v240
	v_xor_b32_e32 v68, 16, v240
	v_add_u32_e32 v69, 64, v69
	v_cmp_lt_i32_e32 vcc, v68, v69
	v_ashrrev_i32_e32 v85, 31, v84
	global_load_dwordx2 v[178:179], v[96:97], off offset:3168
	v_cndmask_b32_e32 v68, v240, v68, vcc
	v_lshlrev_b32_e32 v182, 2, v68
	v_xor_b32_e32 v68, 32, v240
	v_cmp_lt_i32_e32 vcc, v68, v69
	s_waitcnt vmcnt(4)
; __device__ __forceinline__ float sigmoidf_(float x) { return __builtin_amdgcn_rcpf(1.0f + __expf(-x)); }
; __device__ __forceinline__ f32x4 ld_bf4(const bf16_t* q) { const u32x2 u = *(const u32x2*)q; return (f32x4){bflo(u.x), bfhi(u.x), bflo(u.y), bfhi(u.y)}; }
; __device__ __forceinline__ void rwkv_prep_item(const Params& p, const Lt& lt, int l, int item) {
;     ...
;             for (int ks = 0; ks < 2; ++ks) {
;                 aw = __builtin_amdgcn_mfma_f32_16x16x32_bf16(*(const bf16x8*)(decT + crow * 64 + ks * 32 + quad * 8), fw[ks], aw, 0, 0, 0);
;                 aa = __builtin_amdgcn_mfma_f32_16x16x32_bf16(*(const bf16x8*)(aT + crow * 64 + ks * 32 + quad * 8), fa[ks], aa, 0, 0, 0);
;             }
; #pragma unroll
;             for (int ks = 0; ks < 4; ++ks) ag = __builtin_amdgcn_mfma_f32_16x16x32_bf16(*(const bf16x8*)(gT + crow * 128 + ks * 32 + quad * 8), fg[ks], ag, 0, 0, 0);
;             const int c = h * 64 + ct * 16 + quad * 4;
;             const f32x4 mr = *(const f32x4*)(mu + c), mk = *(const f32x4*)(mu + COL_K + c), mv = *(const f32x4*)(mu + COL_V + c);
;             const f32x4 cr = ld_bf4(pt + c), ck = ld_bf4(pt + COL_K + c), cv = ld_bf4(pt + COL_V + c);
;             const f32x4 qr = ld_bf4(pp + c) * pm, qk = ld_bf4(pp + COL_K + c) * pm, qv = ld_bf4(pp + COL_V + c) * pm;
;             const f32x4 r = cr + (qr - cr) * mr, k = ck + (qk - ck) * mk, v = cv + (qv - cv) * mv;
;             const f32x4 w0v = *(const f32x4*)(w0 + c), a0v = *(const f32x4*)(a0 + c), kkv = *(const f32x4*)(kkp + c), kav = *(const f32x4*)(kap + c), rkv = *(const f32x4*)(rkp + c);
;             f32x4 dec, a, kk, k2;
; #pragma unroll
;             for (int j = 0; j < 4; ++j) {
;                 const float z = -(w0v[j] + aw[j]);
;                 const float sp = fmaxf(z, 0.f) + __logf(1.0f + __expf(-fabsf(z)));
;                 dec[j] = __expf(-__expf(-sp - 0.5f));
;                 a[j] = sigmoidf_(a0v[j] + aa[j]);
;                 kk[j] = k[j] * kkv[j];
;                 nrm += kk[j] * kk[j];
;                 k2[j] = k[j] * (1.0f + (a[j] - 1.0f) * kav[j]);
;                 bon += r[j] * k2[j] * rkv[j];
	v_lshlrev_b32_e32 v204, 16, v168
	v_cndmask_b32_e32 v68, v240, v68, vcc
	v_cmp_eq_u32_e32 vcc, 0, v1
	v_mul_f32_e32 v1, v128, v136
	v_lshlrev_b32_e32 v183, 2, v68
	v_lshlrev_b64 v[68:69], 6, v[84:85]
	v_pk_mul_f32 v[84:85], v[36:37], v[138:139]
	v_fma_f32 v1, v40, v1, 0
	v_mul_f32_e32 v40, v129, v137
	v_pk_mul_f32 v[36:37], v[84:85], v[84:85]
	v_fmac_f32_e32 v1, v41, v40
	v_mul_f32_e32 v40, v98, v134
	v_pk_mul_f32 v[136:137], v[38:39], v[132:133]
	v_fmac_f32_e32 v1, v42, v40
	v_pk_mul_f32 v[38:39], v[136:137], v[136:137]
	v_mul_f32_e32 v40, v99, v135
	v_add_f32_e32 v36, v36, v37
	v_fmac_f32_e32 v1, v43, v40
	v_pk_mul_f32 v[132:133], v[48:49], v[152:153]
	v_mul_f32_e32 v42, v144, v154
	v_add_f32_e32 v36, v38, v36
	v_pk_mul_f32 v[40:41], v[132:133], v[132:133]
	v_fmac_f32_e32 v1, v44, v42
	v_mul_f32_e32 v42, v145, v155
	global_load_dwordx4 v[152:155], v160, s[8:9] offset:192
	v_pk_mul_f32 v[128:129], v[56:57], v[76:77]
	global_load_dwordx4 v[76:79], v160, s[42:43] offset:192
	v_add_f32_e32 v36, v39, v36
	v_fmac_f32_e32 v1, v45, v42
	v_mul_f32_e32 v42, v142, v150
	v_pk_mul_f32 v[134:135], v[50:51], v[148:149]
	v_add_f32_e32 v36, v36, v40
	v_fmac_f32_e32 v1, v46, v42
	v_pk_mul_f32 v[42:43], v[134:135], v[134:135]
	v_mul_f32_e32 v44, v143, v151
	v_add_f32_e32 v36, v41, v36
	v_fmac_f32_e32 v1, v47, v44
	v_mul_f32_e32 v46, v158, v162
	v_add_f32_e32 v36, v42, v36
	v_pk_mul_f32 v[44:45], v[128:129], v[128:129]
	v_fmac_f32_e32 v1, v52, v46
	v_mul_f32_e32 v46, v159, v163
	v_add_f32_e32 v36, v43, v36
	v_fmac_f32_e32 v1, v53, v46
	v_mul_f32_e32 v46, v156, v164
	v_pk_mul_f32 v[138:139], v[58:59], v[170:171]
	v_add_f32_e32 v36, v36, v44
	v_fmac_f32_e32 v1, v54, v46
	v_pk_mul_f32 v[46:47], v[138:139], v[138:139]
	v_add_f32_e32 v36, v45, v36
	v_add_f32_e32 v36, v46, v36
	v_add_f32_e32 v184, v47, v36
	v_mul_f32_e32 v36, v157, v165
	v_fmac_f32_e32 v1, v55, v36
	v_lshlrev_b32_e32 v36, 8, v161
	v_mov_b32_e32 v37, v3
	v_lshl_add_u64 v[36:37], v[94:95], 0, v[36:37]
	v_lshl_add_u64 v[90:91], s[40:41], 0, v[68:69]
	global_load_dwordx4 v[68:71], v160, s[44:45] offset:192
	v_mfma_f32_16x16x32_bf16 v[40:43], v[60:63], v[20:23], 0
	global_load_dwordx4 v[52:55], v[36:37], off
	global_load_dwordx4 v[48:51], v[36:37], off offset:64
	global_load_dwordx4 v[44:47], v[36:37], off offset:128
	s_nop 0
	global_load_dwordx4 v[36:39], v[36:37], off offset:192
	v_lshlrev_b32_e32 v144, 16, v166
	v_and_b32_e32 v145, 0xffff0000, v166
	v_mfma_f32_16x16x32_bf16 v[96:99], v[64:67], v[28:31], 0
	global_load_dwordx4 v[64:67], v160, s[8:9] offset:3264
	global_load_dwordx4 v[56:59], v160, s[46:47] offset:192
	global_load_dwordx4 v[60:63], v160, s[48:49] offset:192
	s_waitcnt vmcnt(12)
	v_lshlrev_b32_e32 v150, 16, v175
	v_and_b32_e32 v151, 0xffff0000, v175
	v_mfma_f32_16x16x32_bf16 v[156:159], v[72:75], v[24:27], v[40:43]
	v_lshlrev_b32_e32 v72, 16, v174
	v_and_b32_e32 v73, 0xffff0000, v174
	v_xor_b32_e32 v75, 0x80000000, v145
	v_xor_b32_e32 v74, 0x80000000, v144
	v_pk_fma_f32 v[174:175], v[0:1], v[72:73], v[74:75] op_sel_hi:[0,1,1]
	global_load_dwordx4 v[72:75], v160, s[50:51] offset:192
	v_or_b32_e32 v40, s0, v181
	v_lshlrev_b32_e32 v142, 16, v167
	v_and_b32_e32 v143, 0xffff0000, v167
	v_xor_b32_e32 v161, 0x80000000, v143
	v_xor_b32_e32 v160, 0x80000000, v142
	v_lshlrev_b32_e32 v164, 16, v169
	v_and_b32_e32 v148, 0xffff0000, v169
	v_pk_fma_f32 v[150:151], v[0:1], v[150:151], v[160:161] op_sel_hi:[0,1,1]
	v_and_b32_e32 v162, 0xffff0000, v168
	s_waitcnt vmcnt(12)
	v_lshlrev_b32_e32 v168, 16, v177
	v_and_b32_e32 v169, 0xffff0000, v177
	v_lshlrev_b32_e32 v40, 2, v40
	global_load_dwordx4 v[40:43], v40, s[52:53]
	v_mfma_f32_16x16x32_bf16 v[80:83], v[80:83], v[32:35], v[96:99]
	v_lshlrev_b32_e32 v166, 16, v176
	v_and_b32_e32 v167, 0xffff0000, v176
	s_waitcnt vmcnt(12)
	v_lshlrev_b32_e32 v170, 16, v178
	v_lshlrev_b32_e32 v96, 16, v172
	v_and_b32_e32 v97, 0xffff0000, v172
	v_lshlrev_b32_e32 v98, 16, v173
	v_and_b32_e32 v99, 0xffff0000, v173
	v_and_b32_e32 v171, 0xffff0000, v178
	v_lshlrev_b32_e32 v172, 16, v179
	v_and_b32_e32 v173, 0xffff0000, v179
	v_xor_b32_e32 v161, 0x80000000, v99
	v_xor_b32_e32 v160, 0x80000000, v98
	v_pk_fma_f32 v[160:161], v[0:1], v[172:173], v[160:161] op_sel_hi:[0,1,1]
	v_mov_b32_e32 v163, v205
	s_waitcnt vmcnt(8)
	v_mfma_f32_16x16x32_bf16 v[52:55], v[52:55], v[4:7], 0
	v_add_f32_e32 v76, v156, v76
	v_mul_f32_e64 v149, |v76|, s10
	v_exp_f32_e32 v149, v149
	v_pk_fma_f32 v[142:143], v[154:155], v[150:151], v[142:143]
	v_xor_b32_e32 v151, 0x80000000, v148
	v_xor_b32_e32 v150, 0x80000000, v164
	v_add_f32_e32 v149, 1.0, v149
	v_cmp_gt_f32_e64 s[0:1], s75, v149
	v_pk_fma_f32 v[144:145], v[152:153], v[174:175], v[144:145]
	v_pk_fma_f32 v[152:153], v[0:1], v[168:169], v[150:151] op_sel_hi:[0,1,1]
	v_cndmask_b32_e64 v156, 0, 32, s[0:1]
	v_ldexp_f32 v149, v149, v156
	v_log_f32_e32 v149, v149
	s_waitcnt vmcnt(2)
; __device__ __forceinline__ float quad_sum(float v) { v += xor16(v); v += xor32(v); return v; }
; __device__ __forceinline__ float sigmoidf_(float x) { return __builtin_amdgcn_rcpf(1.0f + __expf(-x)); }
; __device__ __forceinline__ void st_bf4(unsigned char* q, f32x4 v) { u32x2 w; w.x = cvt_pk_bf16(v[0], v[1]); w.y = cvt_pk_bf16(v[2], v[3]); *(u32x2*)q = w; }
; __device__ __forceinline__ void rwkv_prep_item(const Params& p, const Lt& lt, int l, int item) {
;     ...
;             const f32x4 r = cr + (qr - cr) * mr, k = ck + (qk - ck) * mk, v = cv + (qv - cv) * mv;
;             const f32x4 w0v = *(const f32x4*)(w0 + c), a0v = *(const f32x4*)(a0 + c), kkv = *(const f32x4*)(kkp + c), kav = *(const f32x4*)(kap + c), rkv = *(const f32x4*)(rkp + c);
;             f32x4 dec, a, kk, k2;
; #pragma unroll
;             for (int j = 0; j < 4; ++j) {
;                 const float z = -(w0v[j] + aw[j]);
;                 const float sp = fmaxf(z, 0.f) + __logf(1.0f + __expf(-fabsf(z)));
;                 dec[j] = __expf(-__expf(-sp - 0.5f));
;                 a[j] = sigmoidf_(a0v[j] + aa[j]);
;                 kk[j] = k[j] * kkv[j];
;                 nrm += kk[j] * kk[j];
;                 k2[j] = k[j] * (1.0f + (a[j] - 1.0f) * kav[j]);
;                 bon += r[j] * k2[j] * rkv[j];
;             }
;             va[ct] = a; vkk[ct] = kk;
;             { const int cc = ct * 16 + quad * 4; *(f32x4*)(ob + cc * 4) = dec; st_bf4(ob + 512 + cc * 2, k2); st_bf4(ob + 640 + cc * 2, v); st_bf4(ob + 768 + cc * 2, r); }
;             st_bf4((unsigned char*)((bf16_t*)gate + (size_t)t * RW + c), ag);
;         }
;         nrm = quad_sum(nrm); bon = quad_sum(bon);
	v_mov_b32_e32 v169, v60
	v_add_f32_e32 v60, v157, v77
	v_mov_b32_e32 v168, v64
	v_mul_f32_e64 v64, |v60|, s10
	v_exp_f32_e32 v64, v64
	v_mul_f32_e32 v156, 0x3f317217, v149
	v_fma_f32 v156, v149, s57, -v156
	v_fmac_f32_e32 v156, 0x3377d1cf, v149
	v_fmac_f32_e32 v156, 0x3f317217, v149
	v_cmp_lt_f32_e64 s[4:5], |v149|, s58
	v_add_f32_e32 v64, 1.0, v64
	v_add_f32_e32 v68, v80, v68
	v_cndmask_b32_e64 v149, v149, v156, s[4:5]
	v_cndmask_b32_e64 v156, 0, v243, s[0:1]
	v_cmp_gt_f32_e64 s[0:1], s75, v64
	v_mul_f32_e32 v68, 0xbfb8aa3b, v68
	v_exp_f32_e32 v68, v68
	v_cndmask_b32_e64 v77, 0, 32, s[0:1]
	v_ldexp_f32 v64, v64, v77
	v_log_f32_e32 v64, v64
	v_add_f32_e32 v68, 1.0, v68
	v_max_f32_e64 v60, -v60, 0
	v_rcp_f32_e32 v68, v68
	v_mul_f32_e32 v80, 0x3f317217, v64
	v_fma_f32 v80, v64, s57, -v80
	v_fmac_f32_e32 v80, 0x3377d1cf, v64
	v_fmac_f32_e32 v80, 0x3f317217, v64
	v_cmp_lt_f32_e64 s[4:5], |v64|, s58
	v_xor_b32_e32 v151, 0x80000000, v162
	v_xor_b32_e32 v150, 0x80000000, v204
	v_cndmask_b32_e64 v64, v64, v80, s[4:5]
	v_cndmask_b32_e64 v80, 0, v243, s[0:1]
	v_sub_f32_e32 v64, v64, v80
	v_add_f32_e32 v60, v60, v64
	v_add_f32_e32 v64, v81, v69
	v_mul_f32_e32 v64, 0xbfb8aa3b, v64
	v_sub_f32_e32 v60, -0.5, v60
	v_exp_f32_e32 v64, v64
	v_mul_f32_e32 v60, 0x3fb8aa3b, v60
	v_pk_fma_f32 v[154:155], v[0:1], v[166:167], v[150:151] op_sel_hi:[0,1,1]
	v_exp_f32_e32 v60, v60
	v_add_f32_e32 v167, -1.0, v68
	v_mov_b32_e32 v166, v154
	v_sub_f32_e32 v149, v149, v156
	v_pk_fma_f32 v[156:157], v[168:169], v[166:167], v[204:205]
	v_add_f32_e32 v64, 1.0, v64
	v_mul_f32_e32 v56, v56, v156
	v_pk_mul_f32 v[156:157], v[156:157], v[156:157] op_sel:[0,1] op_sel_hi:[1,0]
	v_xor_b32_e32 v151, 0x80000000, v97
	v_xor_b32_e32 v150, 0x80000000, v96
	v_mul_f32_e32 v77, v144, v156
	v_rcp_f32_e32 v69, v64
	v_mul_f32_e32 v60, 0xbfb8aa3b, v60
	v_add_f32_e32 v64, v158, v78
	v_pk_fma_f32 v[150:151], v[0:1], v[170:171], v[150:151] op_sel_hi:[0,1,1]
	s_waitcnt vmcnt(1)
	v_fmac_f32_e32 v1, v72, v77
	v_exp_f32_e32 v77, v60
	v_mov_b32_e32 v60, v65
	v_mul_f32_e64 v65, |v64|, s10
	v_exp_f32_e32 v65, v65
	v_max_f32_e64 v64, -v64, 0
	v_add_f32_e32 v81, -1.0, v69
	v_mov_b32_e32 v80, v155
	v_add_f32_e32 v65, 1.0, v65
	v_cmp_gt_f32_e64 s[0:1], s75, v65
	v_pk_fma_f32 v[60:61], v[60:61], v[80:81], v[162:163]
	v_mov_b32_e32 v81, v62
	v_cndmask_b32_e64 v72, 0, 32, s[0:1]
	v_ldexp_f32 v65, v65, v72
	v_log_f32_e32 v65, v65
	v_mul_f32_e32 v57, v57, v60
	v_pk_mul_f32 v[60:61], v[60:61], v[60:61] op_sel:[0,1] op_sel_hi:[1,0]
	v_max_f32_e64 v76, -v76, 0
	v_mul_f32_e32 v72, 0x3f317217, v65
	v_fma_f32 v72, v65, s57, -v72
	v_fmac_f32_e32 v72, 0x3377d1cf, v65
	v_fmac_f32_e32 v72, 0x3f317217, v65
	v_cmp_lt_f32_e64 s[4:5], |v65|, s58
	v_mul_f32_e32 v61, v145, v60
	v_fmac_f32_e32 v1, v73, v61
	v_cndmask_b32_e64 v65, v65, v72, s[4:5]
	v_cndmask_b32_e64 v72, 0, v243, s[0:1]
	v_sub_f32_e32 v65, v65, v72
	v_add_f32_e32 v64, v64, v65
	v_sub_f32_e32 v64, -0.5, v64
	v_mul_f32_e32 v64, 0x3fb8aa3b, v64
	v_add_f32_e32 v65, v82, v70
	v_exp_f32_e32 v70, v64
	v_mul_f32_e32 v65, 0xbfb8aa3b, v65
	v_exp_f32_e32 v65, v65
	v_add_f32_e32 v76, v76, v149
	v_mul_f32_e32 v61, 0xbfb8aa3b, v70
	v_exp_f32_e32 v78, v61
	v_add_f32_e32 v61, v159, v79
	v_mul_f32_e64 v62, |v61|, s10
	v_exp_f32_e32 v62, v62
	v_add_f32_e32 v64, 1.0, v65
	v_max_f32_e64 v61, -v61, 0
	v_sub_f32_e32 v76, -0.5, v76
	v_add_f32_e32 v62, 1.0, v62
	v_cmp_gt_f32_e64 s[0:1], s75, v62
	v_mfma_f32_16x16x32_bf16 v[48:51], v[48:51], v[8:11], v[52:55]
	v_mul_f32_e32 v76, 0x3fb8aa3b, v76
	v_cndmask_b32_e64 v65, 0, 32, s[0:1]
	v_ldexp_f32 v62, v62, v65
	v_log_f32_e32 v62, v62
	v_exp_f32_e32 v76, v76
	v_rcp_f32_e32 v64, v64
	v_mfma_f32_16x16x32_bf16 v[44:47], v[44:47], v[12:15], v[48:51]
	v_mul_f32_e32 v65, 0x3f317217, v62
	v_fma_f32 v65, v62, s57, -v65
	v_fmac_f32_e32 v65, 0x3377d1cf, v62
	v_fmac_f32_e32 v65, 0x3f317217, v62
	v_cmp_lt_f32_e64 s[4:5], |v62|, s58
	v_mul_f32_e32 v76, 0xbfb8aa3b, v76
	v_exp_f32_e32 v76, v76
	v_cndmask_b32_e64 v62, v62, v65, s[4:5]
	v_cndmask_b32_e64 v65, 0, v243, s[0:1]
	v_sub_f32_e32 v62, v62, v65
	v_add_f32_e32 v61, v61, v62
	v_add_f32_e32 v62, v83, v71
	v_mul_f32_e32 v62, 0xbfb8aa3b, v62
	v_exp_f32_e32 v62, v62
	v_sub_f32_e32 v61, -0.5, v61
	v_mul_f32_e32 v61, 0x3fb8aa3b, v61
	v_exp_f32_e32 v61, v61
	v_add_f32_e32 v62, 1.0, v62
	v_rcp_f32_e32 v65, v62
	v_add_f32_e32 v73, -1.0, v64
	v_mul_f32_e32 v61, 0xbfb8aa3b, v61
	v_mov_b32_e32 v80, v66
	v_mov_b32_e32 v72, v152
	v_mov_b32_e32 v165, v205
	v_exp_f32_e32 v79, v61
	v_fmac_f32_e32 v184, v56, v56
	v_pk_fma_f32 v[72:73], v[80:81], v[72:73], v[164:165]
	v_add_f32_e32 v71, -1.0, v65
	v_mov_b32_e32 v62, v67
	v_mov_b32_e32 v70, v153
	v_mov_b32_e32 v149, v205
	v_mfma_f32_16x16x32_bf16 v[36:39], v[36:39], v[16:19], v[44:47]
	v_fmac_f32_e32 v184, v57, v57
	v_mul_f32_e32 v58, v58, v72
	v_pk_fma_f32 v[52:53], v[62:63], v[70:71], v[148:149]
	v_or_b32_e32 v46, 48, v181
	s_waitcnt vmcnt(0)
	v_pk_fma_f32 v[40:41], v[40:41], v[150:151], v[96:97]
	v_lshlrev_b32_e32 v96, 2, v46
	v_mov_b32_e32 v97, v3
	v_fmac_f32_e32 v184, v58, v58
	v_pk_mul_f32 v[72:73], v[72:73], v[72:73] op_sel:[0,1] op_sel_hi:[1,0]
	v_mul_f32_e32 v59, v59, v52
	v_pk_mul_f32 v[48:49], v[52:53], v[52:53] op_sel:[0,1] op_sel_hi:[1,0]
	v_pk_fma_f32 v[42:43], v[42:43], v[160:161], v[98:99]
	v_lshl_add_u64 v[44:45], v[86:87], 0, v[96:97]
	v_lshlrev_b32_e32 v98, 1, v46
	v_mov_b32_e32 v99, v3
	v_fmac_f32_e32 v184, v59, v59
	v_sub_u32_e32 v233, v44, v230
	ds_write_b128 v233, v[76:79]
	v_lshl_add_u64 v[44:45], v[86:87], 0, v[98:99]
	v_cvt_pk_bf16_f32 v46, v156, v60
	v_cvt_pk_bf16_f32 v47, v72, v48
	v_sub_u32_e32 v233, v44, v230
	ds_write_b64 v233, v[46:47] offset:512
	ds_bpermute_b32 v46, v182, v184
	v_cvt_pk_bf16_f32 v40, v40, v41
	v_cvt_pk_bf16_f32 v41, v42, v43
	v_mul_f32_e32 v66, v142, v72
	v_fmac_f32_e32 v1, v74, v66
	s_waitcnt lgkmcnt(0)
; __device__ __forceinline__ float quad_sum(float v) { v += xor16(v); v += xor32(v); return v; }
; __device__ __forceinline__ void st_bf4(unsigned char* q, f32x4 v) { u32x2 w; w.x = cvt_pk_bf16(v[0], v[1]); w.y = cvt_pk_bf16(v[2], v[3]); *(u32x2*)q = w; }
; __device__ __forceinline__ void rwkv_prep_item(const Params& p, const Lt& lt, int l, int item) {
;     ...
;             { const int cc = ct * 16 + quad * 4; *(f32x4*)(ob + cc * 4) = dec; st_bf4(ob + 512 + cc * 2, k2); st_bf4(ob + 640 + cc * 2, v); st_bf4(ob + 768 + cc * 2, r); }
;             st_bf4((unsigned char*)((bf16_t*)gate + (size_t)t * RW + c), ag);
;         }
;         nrm = quad_sum(nrm); bon = quad_sum(bon);
;         const float inv = rsqrtf(fmaxf(nrm, 1e-24f));
; #pragma unroll
;         for (int ct = 0; ct < 4; ++ct) {
;             const int cc = ct * 16 + quad * 4;
;             const f32x4 kkn = vkk[ct] * inv;
;             st_bf4(ob + 256 + cc * 2, -kkn);
;             st_bf4(ob + 384 + cc * 2, kkn * va[ct]);
;         }
;         if (quad == 0) bonus[(size_t)t * 16 + h] = bon;
	v_add_f32_e32 v42, v184, v46
	ds_bpermute_b32 v43, v183, v42
	v_mul_f32_e32 v49, v143, v48
	v_fmac_f32_e32 v1, v75, v49
	v_cvt_pk_bf16_f32 v36, v36, v37
	v_cvt_pk_bf16_f32 v37, v38, v39
	s_waitcnt lgkmcnt(0)
	v_add_f32_e32 v38, v42, v43
	ds_bpermute_b32 v39, v182, v1
	v_max_f32_e32 v38, 0x179abe15, v38
	v_rsq_f32_e32 v38, v38
	v_sub_u32_e32 v233, v44, v230
	ds_write_b64 v233, v[40:41] offset:640
	v_cvt_pk_bf16_f32 v40, v144, v145
	v_cvt_pk_bf16_f32 v41, v142, v143
	v_sub_u32_e32 v233, v44, v230
	ds_write_b64 v233, v[40:41] offset:768
	s_waitcnt lgkmcnt(0)
	v_pk_mul_f32 v[40:41], v[84:85], v[38:39] op_sel_hi:[1,0]
	v_pk_mul_f32 v[42:43], v[136:137], v[38:39] op_sel_hi:[1,0]
	v_sub_u32_e32 v233, v124, v236
	ds_write_b64 v233, v[36:37] offset:96
	v_add_f32_e32 v1, v1, v39
	v_xor_b32_e32 v37, 0x80000000, v43
	v_xor_b32_e32 v39, 0x80000000, v42
	v_xor_b32_e32 v44, 0x80000000, v41
	v_xor_b32_e32 v45, 0x80000000, v40
	v_pk_mul_f32 v[42:43], v[120:121], v[42:43]
	v_pk_mul_f32 v[40:41], v[100:101], v[40:41]
	v_cvt_pk_bf16_f32 v44, v45, v44
	v_cvt_pk_bf16_f32 v40, v40, v41
	v_cvt_pk_bf16_f32 v41, v42, v43
	v_cvt_pk_bf16_f32 v45, v39, v37
	v_sub_u32_e32 v233, v122, v230
	ds_write_b64 v233, v[40:41] offset:384
	v_pk_mul_f32 v[40:41], v[132:133], v[38:39] op_sel_hi:[1,0]
	v_pk_mul_f32 v[42:43], v[134:135], v[38:39] op_sel_hi:[1,0]
	v_sub_u32_e32 v233, v122, v230
	ds_write_b64 v233, v[44:45] offset:256
	v_xor_b32_e32 v37, 0x80000000, v43
	v_xor_b32_e32 v39, 0x80000000, v42
	v_xor_b32_e32 v44, 0x80000000, v41
	v_xor_b32_e32 v45, 0x80000000, v40
	v_pk_mul_f32 v[42:43], v[130:131], v[42:43]
	v_pk_mul_f32 v[40:41], v[126:127], v[40:41]
	v_cvt_pk_bf16_f32 v44, v45, v44
	v_cvt_pk_bf16_f32 v40, v40, v41
	v_cvt_pk_bf16_f32 v41, v42, v43
	v_cvt_pk_bf16_f32 v45, v39, v37
	v_sub_u32_e32 v233, v122, v230
	ds_write_b64 v233, v[40:41] offset:416
	v_pk_mul_f32 v[40:41], v[128:129], v[38:39] op_sel_hi:[1,0]
	v_pk_mul_f32 v[42:43], v[138:139], v[38:39] op_sel_hi:[1,0]
	ds_bpermute_b32 v36, v183, v1
	v_sub_u32_e32 v233, v122, v230
	ds_write_b64 v233, v[44:45] offset:288
	v_xor_b32_e32 v37, 0x80000000, v43
	v_xor_b32_e32 v39, 0x80000000, v42
	v_xor_b32_e32 v44, 0x80000000, v41
	v_xor_b32_e32 v45, 0x80000000, v40
	v_pk_mul_f32 v[42:43], v[146:147], v[42:43]
	v_pk_mul_f32 v[40:41], v[140:141], v[40:41]
	v_cvt_pk_bf16_f32 v44, v45, v44
	v_cvt_pk_bf16_f32 v40, v40, v41
	v_cvt_pk_bf16_f32 v41, v42, v43
	v_cvt_pk_bf16_f32 v45, v39, v37
	v_sub_u32_e32 v233, v122, v230
	ds_write_b64 v233, v[40:41] offset:448
	v_pk_mul_f32 v[40:41], v[56:57], v[38:39] op_sel_hi:[1,0]
	v_pk_mul_f32 v[38:39], v[58:59], v[38:39] op_sel_hi:[1,0]
	v_sub_u32_e32 v233, v122, v230
	ds_write_b64 v233, v[44:45] offset:320
	v_xor_b32_e32 v37, 0x80000000, v39
	v_xor_b32_e32 v43, 0x80000000, v38
	v_xor_b32_e32 v42, 0x80000000, v41
	v_xor_b32_e32 v44, 0x80000000, v40
	v_pk_mul_f32 v[38:39], v[64:65], v[38:39]
	v_pk_mul_f32 v[40:41], v[68:69], v[40:41]
	v_cvt_pk_bf16_f32 v42, v44, v42
	v_cvt_pk_bf16_f32 v43, v43, v37
	v_cvt_pk_bf16_f32 v40, v40, v41
	v_cvt_pk_bf16_f32 v41, v38, v39
	v_sub_u32_e32 v233, v122, v230
	ds_write_b64 v233, v[42:43] offset:352
	v_sub_u32_e32 v233, v122, v230
	ds_write_b64 v233, v[40:41] offset:480
	s_waitcnt lgkmcnt(0)
	v_mov_b32_e32 v228, v234
	v_mov_b32_e32 v229, v235
	ds_read_b128 v[210:213], v226 offset:0
	ds_read_b128 v[214:217], v226 offset:1040
	ds_read_b128 v[218:221], v226 offset:2080
	ds_read_b128 v[222:225], v226 offset:3120
	s_waitcnt lgkmcnt(3)
	global_store_dwordx4 v[228:229], v[210:213], off
	v_lshl_add_u64 v[228:229], v[228:229], 0, v[194:195]
	s_waitcnt lgkmcnt(2)
	global_store_dwordx4 v[228:229], v[214:217], off
	v_lshl_add_u64 v[228:229], v[228:229], 0, v[194:195]
	s_waitcnt lgkmcnt(1)
	global_store_dwordx4 v[228:229], v[218:221], off
	v_lshl_add_u64 v[228:229], v[228:229], 0, v[194:195]
	s_waitcnt lgkmcnt(0)
	global_store_dwordx4 v[228:229], v[222:225], off
	v_lshl_add_u64 v[228:229], v[228:229], 0, v[194:195]
	ds_read_b128 v[210:213], v226 offset:4160
	ds_read_b128 v[214:217], v226 offset:5200
	ds_read_b128 v[218:221], v226 offset:6240
	ds_read_b128 v[222:225], v226 offset:7280
	s_waitcnt lgkmcnt(3)
	global_store_dwordx4 v[228:229], v[210:213], off
	v_lshl_add_u64 v[228:229], v[228:229], 0, v[194:195]
	s_waitcnt lgkmcnt(2)
	global_store_dwordx4 v[228:229], v[214:217], off
	v_lshl_add_u64 v[228:229], v[228:229], 0, v[194:195]
	s_waitcnt lgkmcnt(1)
	global_store_dwordx4 v[228:229], v[218:221], off
	v_lshl_add_u64 v[228:229], v[228:229], 0, v[194:195]
	s_waitcnt lgkmcnt(0)
	global_store_dwordx4 v[228:229], v[222:225], off
	v_lshl_add_u64 v[228:229], v[228:229], 0, v[194:195]
	ds_read_b128 v[210:213], v226 offset:8320
	ds_read_b128 v[214:217], v226 offset:9360
	ds_read_b128 v[218:221], v226 offset:10400
	ds_read_b128 v[222:225], v226 offset:11440
	s_waitcnt lgkmcnt(3)
	global_store_dwordx4 v[228:229], v[210:213], off
	v_lshl_add_u64 v[228:229], v[228:229], 0, v[194:195]
	s_waitcnt lgkmcnt(2)
	global_store_dwordx4 v[228:229], v[214:217], off
	v_lshl_add_u64 v[228:229], v[228:229], 0, v[194:195]
	s_waitcnt lgkmcnt(1)
	global_store_dwordx4 v[228:229], v[218:221], off
	v_lshl_add_u64 v[228:229], v[228:229], 0, v[194:195]
	s_waitcnt lgkmcnt(0)
	global_store_dwordx4 v[228:229], v[222:225], off
	v_lshl_add_u64 v[228:229], v[228:229], 0, v[194:195]
	ds_read_b128 v[210:213], v226 offset:12480
	ds_read_b128 v[214:217], v226 offset:13520
	ds_read_b128 v[218:221], v226 offset:14560
	ds_read_b128 v[222:225], v226 offset:15600
	s_waitcnt lgkmcnt(3)
	global_store_dwordx4 v[228:229], v[210:213], off
	v_lshl_add_u64 v[228:229], v[228:229], 0, v[194:195]
	s_waitcnt lgkmcnt(2)
	global_store_dwordx4 v[228:229], v[214:217], off
	v_lshl_add_u64 v[228:229], v[228:229], 0, v[194:195]
	s_waitcnt lgkmcnt(1)
	global_store_dwordx4 v[228:229], v[218:221], off
	v_lshl_add_u64 v[228:229], v[228:229], 0, v[194:195]
	s_waitcnt lgkmcnt(0)
	global_store_dwordx4 v[228:229], v[222:225], off
	v_lshl_add_u64 v[228:229], v[228:229], 0, v[194:195]
	v_lshl_add_u64 v[234:235], v[234:235], 0, v[198:199]
	s_and_saveexec_b64 s[0:1], vcc
	s_cbranch_execz .LBB0_345
	s_lshl_b32 s10, s56, 2
	v_lshl_add_u64 v[38:39], v[90:91], 0, s[10:11]
	s_waitcnt lgkmcnt(0)
	v_add_f32_e32 v1, v1, v36
	global_store_dword v[38:39], v1, off
; __device__ __forceinline__ f32x4 ld_bf4(const bf16_t* q) { const u32x2 u = *(const u32x2*)q; return (f32x4){bflo(u.x), bfhi(u.x), bflo(u.y), bfhi(u.y)}; }
; __device__ __forceinline__ void rwkv_prep_item(const Params& p, const Lt& lt, int l, int item) {
;     ...
;         unsigned char* ob = opnd + (size_t)t * OPTB + h * OPB;
; #pragma unroll
;         for (int ct = 0; ct < 4; ++ct) {
;             const int crow = h * 64 + ct * 16 + qi;
;             f32x4 aw = {0.f, 0.f, 0.f, 0.f}, aa = aw, ag = aw;
; #pragma unroll
;             for (int ks = 0; ks < 2; ++ks) {
;                 aw = __builtin_amdgcn_mfma_f32_16x16x32_bf16(*(const bf16x8*)(decT + crow * 64 + ks * 32 + quad * 8), fw[ks], aw, 0, 0, 0);
;                 aa = __builtin_amdgcn_mfma_f32_16x16x32_bf16(*(const bf16x8*)(aT + crow * 64 + ks * 32 + quad * 8), fa[ks], aa, 0, 0, 0);
;             }
; #pragma unroll
;             for (int ks = 0; ks < 4; ++ks) ag = __builtin_amdgcn_mfma_f32_16x16x32_bf16(*(const bf16x8*)(gT + crow * 128 + ks * 32 + quad * 8), fg[ks], ag, 0, 0, 0);
;             const int c = h * 64 + ct * 16 + quad * 4;
;             const f32x4 mr = *(const f32x4*)(mu + c), mk = *(const f32x4*)(mu + COL_K + c), mv = *(const f32x4*)(mu + COL_V + c);
;             const f32x4 cr = ld_bf4(pt + c), ck = ld_bf4(pt + COL_K + c), cv = ld_bf4(pt + COL_V + c);
;             const f32x4 qr = ld_bf4(pp + c) * pm, qk = ld_bf4(pp + COL_K + c) * pm, qv = ld_bf4(pp + COL_V + c) * pm;
;             const f32x4 r = cr + (qr - cr) * mr, k = ck + (qk - ck) * mk, v = cv + (qv - cv) * mv;
.LBB0_345:
	s_or_b64 exec, exec, s[0:1]
	s_add_i32 s0, s56, 1
	s_mul_i32 s10, s0, 0x380
	v_lshl_add_u64 v[120:121], v[118:119], 0, s[10:11]
	s_lshl_b32 s10, s0, 6
	v_or_b32_e32 v40, s10, v180
	s_waitcnt lgkmcnt(0)
	v_lshlrev_b32_e32 v36, 7, v40
	v_mov_b32_e32 v37, v3
	v_lshl_add_u64 v[38:39], v[88:89], 0, v[36:37]
	v_lshl_add_u64 v[36:37], v[92:93], 0, v[36:37]
	global_load_dwordx4 v[52:55], v[38:39], off
	global_load_dwordx4 v[56:59], v[36:37], off
	global_load_dwordx4 v[60:63], v[38:39], off offset:64
	global_load_dwordx4 v[68:71], v[36:37], off offset:64
	v_or_b32_e32 v72, s10, v181
	v_lshlrev_b32_e32 v36, 8, v40
	v_mov_b32_e32 v37, v3
	v_lshlrev_b32_e32 v140, 1, v72
	v_mov_b32_e32 v141, v3
	v_lshl_add_u64 v[36:37], v[94:95], 0, v[36:37]
	v_lshlrev_b32_e32 v184, 2, v72
	v_lshl_add_u64 v[134:135], v[114:115], 0, v[140:141]
	global_load_dwordx4 v[48:51], v[36:37], off
	global_load_dwordx4 v[44:47], v[36:37], off offset:64
	global_load_dwordx4 v[40:43], v[36:37], off offset:128
	s_nop 0
	global_load_dwordx4 v[36:39], v[36:37], off offset:192
	v_lshl_add_u64 v[132:133], v[110:111], 0, v[140:141]
	v_mov_b32_e32 v1, v0
	v_mov_b32_e32 v100, v0
	v_mov_b32_e32 v101, v0
	s_mov_b32 s57, 0xbfb8aa3b
	s_mov_b32 s58, 0x3f317217
	s_mov_b32 s59, 0x7f800000
	v_lshl_add_u64 v[140:141], v[116:117], 0, v[140:141]
	s_waitcnt vmcnt(7)
	v_mfma_f32_16x16x32_bf16 v[52:55], v[52:55], v[20:23], 0
	s_waitcnt vmcnt(6)
	v_mfma_f32_16x16x32_bf16 v[56:59], v[56:59], v[28:31], 0
	s_waitcnt vmcnt(5)
	v_mfma_f32_16x16x32_bf16 v[64:67], v[60:63], v[24:27], v[52:55]
	s_waitcnt vmcnt(4)
	v_mfma_f32_16x16x32_bf16 v[56:59], v[68:71], v[32:35], v[56:59]
	global_load_dwordx4 v[68:71], v184, s[8:9]
	global_load_dwordx4 v[60:63], v184, s[8:9] offset:3072
	global_load_dwordx4 v[52:55], v184, s[52:53]
	global_load_dwordx2 v[72:73], v[134:135], off
	global_load_dwordx2 v[126:127], v[134:135], off offset:1536
	global_load_dwordx2 v[76:77], v[134:135], off offset:3072
	s_waitcnt vmcnt(9)
	v_mfma_f32_16x16x32_bf16 v[48:51], v[48:51], v[4:7], 0
	global_load_dwordx2 v[80:81], v[132:133], off offset:1536
	s_waitcnt vmcnt(3)
	v_lshlrev_b32_e32 v74, 16, v72
	s_waitcnt vmcnt(1)
	v_lshlrev_b32_e32 v130, 16, v76
	v_and_b32_e32 v131, 0xffff0000, v76
	v_lshlrev_b32_e32 v142, 16, v77
	v_and_b32_e32 v143, 0xffff0000, v77
	global_load_dwordx2 v[76:77], v[132:133], off
	v_and_b32_e32 v75, 0xffff0000, v72
	v_xor_b32_e32 v85, 0x80000000, v75
	v_xor_b32_e32 v84, 0x80000000, v74
	v_lshlrev_b32_e32 v72, 16, v73
	v_and_b32_e32 v73, 0xffff0000, v73
	v_mfma_f32_16x16x32_bf16 v[44:47], v[44:47], v[8:11], v[48:51]
	s_waitcnt vmcnt(1)
	v_lshlrev_b32_e32 v128, 16, v80
	v_and_b32_e32 v129, 0xffff0000, v80
	v_lshlrev_b32_e32 v136, 16, v81
	v_and_b32_e32 v137, 0xffff0000, v81
	global_load_dwordx2 v[80:81], v[132:133], off offset:3072
	v_mfma_f32_16x16x32_bf16 v[40:43], v[40:43], v[12:15], v[44:47]
	s_waitcnt vmcnt(1)
	v_lshlrev_b32_e32 v78, 16, v76
	v_and_b32_e32 v79, 0xffff0000, v76
	v_pk_fma_f32 v[78:79], v[0:1], v[78:79], v[84:85]
	v_lshlrev_b32_e32 v76, 16, v77
	v_and_b32_e32 v77, 0xffff0000, v77
	v_xor_b32_e32 v85, 0x80000000, v73
	v_xor_b32_e32 v84, 0x80000000, v72
	v_pk_fma_f32 v[146:147], v[68:69], v[78:79], v[74:75]
	v_xor_b32_e32 v69, 0x80000000, v131
	v_xor_b32_e32 v68, 0x80000000, v130
	v_pk_fma_f32 v[76:77], v[100:101], v[76:77], v[84:85]
	v_mfma_f32_16x16x32_bf16 v[36:39], v[36:39], v[16:19], v[40:43]
	v_fma_f32 v144, v70, v76, v72
	v_fma_f32 v145, v71, v77, v73
	v_lshl_add_u64 v[44:45], v[120:121], 0, v[112:113]
	s_waitcnt vmcnt(0)
	v_lshlrev_b32_e32 v82, 16, v80
	v_and_b32_e32 v83, 0xffff0000, v80
	v_lshlrev_b32_e32 v80, 16, v81
	v_and_b32_e32 v81, 0xffff0000, v81
	v_cvt_pk_bf16_f32 v36, v36, v37
	v_cvt_pk_bf16_f32 v37, v38, v39
	v_pk_fma_f32 v[148:149], v[0:1], v[82:83], v[68:69]
	v_xor_b32_e32 v69, 0x80000000, v143
	v_xor_b32_e32 v68, 0x80000000, v142
	v_pk_fma_f32 v[150:151], v[100:101], v[80:81], v[68:69]
	global_load_dwordx4 v[84:87], v184, s[42:43]
	global_load_dwordx4 v[80:83], v184, s[44:45]
	global_load_dwordx4 v[68:71], v184, s[46:47]
	global_load_dwordx4 v[76:79], v184, s[48:49]
	global_load_dwordx4 v[72:75], v184, s[50:51]
	v_pk_fma_f32 v[42:43], v[52:53], v[148:149], v[130:131]
	v_lshl_add_u64 v[130:131], v[120:121], 0, v[2:3]
	v_pk_fma_f32 v[40:41], v[54:55], v[150:151], v[142:143]
	v_cvt_pk_bf16_f32 v42, v42, v43
	v_cvt_pk_bf16_f32 v43, v40, v41
	v_cvt_pk_bf16_f32 v40, v146, v147
	v_cvt_pk_bf16_f32 v41, v144, v145
	v_sub_u32_e32 v233, v130, v231
	ds_write_b64 v233, v[42:43] offset:640
	v_sub_u32_e32 v233, v130, v231
	ds_write_b64 v233, v[40:41] offset:768
	s_waitcnt vmcnt(4)
	v_add_f32_e32 v64, v64, v84
	v_max_f32_e64 v84, -v64, 0
	v_mul_f32_e64 v64, |v64|, s57
	s_waitcnt vmcnt(3)
; __device__ __forceinline__ float sigmoidf_(float x) { return __builtin_amdgcn_rcpf(1.0f + __expf(-x)); }
; __device__ __forceinline__ void st_bf4(unsigned char* q, f32x4 v) { u32x2 w; w.x = cvt_pk_bf16(v[0], v[1]); w.y = cvt_pk_bf16(v[2], v[3]); *(u32x2*)q = w; }
; __device__ __forceinline__ void rwkv_prep_item(const Params& p, const Lt& lt, int l, int item) {
;     ...
;             const f32x4 r = cr + (qr - cr) * mr, k = ck + (qk - ck) * mk, v = cv + (qv - cv) * mv;
;             const f32x4 w0v = *(const f32x4*)(w0 + c), a0v = *(const f32x4*)(a0 + c), kkv = *(const f32x4*)(kkp + c), kav = *(const f32x4*)(kap + c), rkv = *(const f32x4*)(rkp + c);
;             f32x4 dec, a, kk, k2;
; #pragma unroll
;             for (int j = 0; j < 4; ++j) {
;                 const float z = -(w0v[j] + aw[j]);
;                 const float sp = fmaxf(z, 0.f) + __logf(1.0f + __expf(-fabsf(z)));
;                 dec[j] = __expf(-__expf(-sp - 0.5f));
;                 a[j] = sigmoidf_(a0v[j] + aa[j]);
;                 kk[j] = k[j] * kkv[j];
;                 nrm += kk[j] * kk[j];
;                 k2[j] = k[j] * (1.0f + (a[j] - 1.0f) * kav[j]);
;                 bon += r[j] * k2[j] * rkv[j];
;             }
;             va[ct] = a; vkk[ct] = kk;
;             { const int cc = ct * 16 + quad * 4; *(f32x4*)(ob + cc * 4) = dec; st_bf4(ob + 512 + cc * 2, k2); st_bf4(ob + 640 + cc * 2, v); st_bf4(ob + 768 + cc * 2, r); }
;             st_bf4((unsigned char*)((bf16_t*)gate + (size_t)t * RW + c), ag);
;         }
	v_add_f32_e32 v56, v56, v80
	v_exp_f32_e32 v64, v64
	v_mul_f32_e32 v56, 0xbfb8aa3b, v56
	v_exp_f32_e32 v56, v56
	v_add_f32_e32 v64, 1.0, v64
	v_cmp_gt_f32_e64 s[0:1], s75, v64
	v_add_f32_e32 v56, 1.0, v56
	s_nop 0
	v_cndmask_b32_e64 v122, 0, 32, s[0:1]
	v_ldexp_f32 v64, v64, v122
	v_log_f32_e32 v64, v64
	s_nop 0
	v_mul_f32_e32 v122, 0x3f317217, v64
	v_cmp_lt_f32_e64 s[4:5], |v64|, s59
	v_fma_f32 v122, v64, s58, -v122
	v_fmac_f32_e32 v122, 0x3377d1cf, v64
	v_fmac_f32_e32 v122, 0x3f317217, v64
	v_cndmask_b32_e64 v64, v64, v122, s[4:5]
	v_cndmask_b32_e64 v122, 0, v243, s[0:1]
	v_sub_f32_e32 v64, v64, v122
	v_rcp_f32_e32 v122, v56
	v_add_f32_e32 v56, v65, v85
	v_max_f32_e64 v65, -v56, 0
	v_mul_f32_e64 v56, |v56|, s57
	v_add_f32_e32 v64, v84, v64
	v_exp_f32_e32 v56, v56
	v_sub_f32_e32 v64, -0.5, v64
	v_mul_f32_e32 v64, 0x3fb8aa3b, v64
	v_exp_f32_e32 v64, v64
	v_add_f32_e32 v56, 1.0, v56
	v_cmp_gt_f32_e64 s[0:1], s75, v56
	v_mul_f32_e32 v64, 0xbfb8aa3b, v64
	s_nop 0
	v_cndmask_b32_e64 v80, 0, 32, s[0:1]
	v_ldexp_f32 v56, v56, v80
	v_exp_f32_e32 v64, v64
	v_log_f32_e32 v56, v56
	s_nop 0
	v_mul_f32_e32 v80, 0x3f317217, v56
	v_cmp_lt_f32_e64 s[4:5], |v56|, s59
	v_fma_f32 v80, v56, s58, -v80
	v_fmac_f32_e32 v80, 0x3377d1cf, v56
	v_fmac_f32_e32 v80, 0x3f317217, v56
	v_cndmask_b32_e64 v56, v56, v80, s[4:5]
	v_cndmask_b32_e64 v80, 0, v243, s[0:1]
	v_sub_f32_e32 v56, v56, v80
	v_add_f32_e32 v56, v65, v56
	v_sub_f32_e32 v56, -0.5, v56
	v_mul_f32_e32 v56, 0x3fb8aa3b, v56
	v_exp_f32_e32 v56, v56
	s_nop 0
	v_mul_f32_e32 v56, 0xbfb8aa3b, v56
	v_exp_f32_e32 v65, v56
	v_add_f32_e32 v56, v57, v81
	v_mul_f32_e32 v56, 0xbfb8aa3b, v56
	v_exp_f32_e32 v56, v56
	s_nop 0
	v_add_f32_e32 v56, 1.0, v56
	v_rcp_f32_e32 v123, v56
	v_add_f32_e32 v56, v66, v86
	v_max_f32_e64 v57, -v56, 0
	v_mul_f32_e64 v56, |v56|, s57
	v_exp_f32_e32 v56, v56
	s_nop 0
	v_add_f32_e32 v56, 1.0, v56
	v_cmp_gt_f32_e64 s[0:1], s75, v56
	s_nop 1
	v_cndmask_b32_e64 v66, 0, 32, s[0:1]
	v_ldexp_f32 v56, v56, v66
	v_log_f32_e32 v56, v56
	s_nop 0
	v_mul_f32_e32 v66, 0x3f317217, v56
	v_cmp_lt_f32_e64 s[4:5], |v56|, s59
	v_fma_f32 v66, v56, s58, -v66
	v_fmac_f32_e32 v66, 0x3377d1cf, v56
	v_fmac_f32_e32 v66, 0x3f317217, v56
	v_cndmask_b32_e64 v56, v56, v66, s[4:5]
	v_cndmask_b32_e64 v66, 0, v243, s[0:1]
	v_sub_f32_e32 v56, v56, v66
	v_add_f32_e32 v56, v57, v56
	v_sub_f32_e32 v56, -0.5, v56
	v_mul_f32_e32 v56, 0x3fb8aa3b, v56
	v_exp_f32_e32 v56, v56
	s_nop 0
	v_mul_f32_e32 v56, 0xbfb8aa3b, v56
	v_exp_f32_e32 v66, v56
	v_add_f32_e32 v56, v58, v82
	v_mul_f32_e32 v56, 0xbfb8aa3b, v56
	v_exp_f32_e32 v56, v56
	s_nop 0
	v_add_f32_e32 v56, 1.0, v56
	v_rcp_f32_e32 v124, v56
	v_add_f32_e32 v56, v67, v87
	v_max_f32_e64 v57, -v56, 0
	v_mul_f32_e64 v56, |v56|, s57
	v_exp_f32_e32 v56, v56
	s_nop 0
	v_add_f32_e32 v56, 1.0, v56
	v_cmp_gt_f32_e64 s[0:1], s75, v56
	s_nop 1
	v_cndmask_b32_e64 v58, 0, 32, s[0:1]
	v_ldexp_f32 v56, v56, v58
	v_log_f32_e32 v56, v56
	s_nop 0
	v_mul_f32_e32 v58, 0x3f317217, v56
	v_cmp_lt_f32_e64 s[4:5], |v56|, s59
	v_fma_f32 v58, v56, s58, -v58
	v_fmac_f32_e32 v58, 0x3377d1cf, v56
	v_fmac_f32_e32 v58, 0x3f317217, v56
	v_cndmask_b32_e64 v56, v56, v58, s[4:5]
	v_cndmask_b32_e64 v58, 0, v243, s[0:1]
	s_or_b32 s0, s10, 16
	v_sub_f32_e32 v56, v56, v58
	v_lshlrev_b32_e32 v58, 16, v126
	v_add_f32_e32 v56, v57, v56
	v_xor_b32_e32 v82, 0x80000000, v58
	v_and_b32_e32 v57, 0xffff0000, v127
	v_sub_f32_e32 v56, -0.5, v56
	v_xor_b32_e32 v81, 0x80000000, v57
	v_mul_f32_e32 v56, 0x3fb8aa3b, v56
	v_exp_f32_e32 v56, v56
	s_nop 0
	v_mul_f32_e32 v56, 0xbfb8aa3b, v56
	v_exp_f32_e32 v67, v56
	v_add_f32_e32 v56, v59, v83
	v_and_b32_e32 v59, 0xffff0000, v126
	v_mul_f32_e32 v56, 0xbfb8aa3b, v56
	v_xor_b32_e32 v83, 0x80000000, v59
	v_exp_f32_e32 v56, v56
	v_pk_fma_f32 v[82:83], v[0:1], v[128:129], v[82:83]
	v_sub_u32_e32 v233, v44, v231
	ds_write_b128 v233, v[64:67]
	v_pk_fma_f32 v[58:59], v[60:61], v[82:83], v[58:59]
	v_pk_add_f32 v[60:61], v[122:123], -1.0 op_sel_hi:[1,0]
	v_add_f32_e32 v56, 1.0, v56
	s_waitcnt vmcnt(1)
	v_pk_fma_f32 v[60:61], v[76:77], v[60:61], 1.0 op_sel_hi:[1,1,0]
	v_rcp_f32_e32 v125, v56
	v_lshlrev_b32_e32 v56, 16, v127
	v_pk_mul_f32 v[126:127], v[68:69], v[58:59]
	v_pk_mul_f32 v[58:59], v[58:59], v[60:61]
	v_xor_b32_e32 v80, 0x80000000, v56
	v_mul_f32_e32 v60, v146, v58
	s_waitcnt vmcnt(0)
	v_fma_f32 v185, v72, v60, 0
	v_mul_f32_e32 v60, v147, v59
	v_pk_fma_f32 v[80:81], v[100:101], v[136:137], v[80:81]
	v_fmac_f32_e32 v185, v73, v60
	v_pk_add_f32 v[60:61], v[124:125], -1.0 op_sel_hi:[1,0]
	v_pk_fma_f32 v[56:57], v[62:63], v[80:81], v[56:57]
	v_pk_fma_f32 v[60:61], v[78:79], v[60:61], 1.0 op_sel_hi:[1,1,0]
	v_cvt_pk_bf16_f32 v44, v58, v59
	v_pk_mul_f32 v[60:61], v[56:57], v[60:61]
	v_pk_mul_f32 v[128:129], v[70:71], v[56:57]
	v_cvt_pk_bf16_f32 v45, v60, v61
	v_sub_u32_e32 v233, v130, v231
	ds_write_b64 v233, v[44:45] offset:512
	v_or_b32_e32 v44, s0, v180
	v_mul_f32_e32 v62, v144, v60
	v_sub_u32_e32 v233, v140, v237
	ds_write_b64 v233, v[36:37]
	v_lshlrev_b32_e32 v36, 7, v44
	v_mov_b32_e32 v37, v3
	v_fmac_f32_e32 v185, v74, v62
	v_mul_f32_e32 v56, v145, v61
	v_lshl_add_u64 v[38:39], v[88:89], 0, v[36:37]
	v_fmac_f32_e32 v185, v75, v56
	v_lshl_add_u64 v[36:37], v[92:93], 0, v[36:37]
	global_load_dwordx4 v[40:43], v[38:39], off
	global_load_dwordx4 v[56:59], v[36:37], off
	global_load_dwordx4 v[60:63], v[38:39], off offset:64
	global_load_dwordx4 v[68:71], v[36:37], off offset:64
	v_lshlrev_b32_e32 v36, 8, v44
	v_mov_b32_e32 v37, v3
	v_lshl_add_u64 v[36:37], v[94:95], 0, v[36:37]
	global_load_dwordx4 v[52:55], v[36:37], off
	global_load_dwordx4 v[48:51], v[36:37], off offset:64
	global_load_dwordx4 v[44:47], v[36:37], off offset:128
	s_nop 0
	global_load_dwordx4 v[36:39], v[36:37], off offset:192
	v_pk_mul_f32 v[136:137], v[126:127], v[126:127]
	v_pk_mul_f32 v[138:139], v[128:129], v[128:129]
	s_waitcnt vmcnt(7)
; __device__ __forceinline__ float sigmoidf_(float x) { return __builtin_amdgcn_rcpf(1.0f + __expf(-x)); }
; __device__ __forceinline__ f32x4 ld_bf4(const bf16_t* q) { const u32x2 u = *(const u32x2*)q; return (f32x4){bflo(u.x), bfhi(u.x), bflo(u.y), bfhi(u.y)}; }
; __device__ __forceinline__ void rwkv_prep_item(const Params& p, const Lt& lt, int l, int item) {
;     ...
;             for (int ks = 0; ks < 2; ++ks) {
;                 aw = __builtin_amdgcn_mfma_f32_16x16x32_bf16(*(const bf16x8*)(decT + crow * 64 + ks * 32 + quad * 8), fw[ks], aw, 0, 0, 0);
;                 aa = __builtin_amdgcn_mfma_f32_16x16x32_bf16(*(const bf16x8*)(aT + crow * 64 + ks * 32 + quad * 8), fa[ks], aa, 0, 0, 0);
;             }
; #pragma unroll
;             for (int ks = 0; ks < 4; ++ks) ag = __builtin_amdgcn_mfma_f32_16x16x32_bf16(*(const bf16x8*)(gT + crow * 128 + ks * 32 + quad * 8), fg[ks], ag, 0, 0, 0);
;             const int c = h * 64 + ct * 16 + quad * 4;
;             const f32x4 mr = *(const f32x4*)(mu + c), mk = *(const f32x4*)(mu + COL_K + c), mv = *(const f32x4*)(mu + COL_V + c);
;             const f32x4 cr = ld_bf4(pt + c), ck = ld_bf4(pt + COL_K + c), cv = ld_bf4(pt + COL_V + c);
;             const f32x4 qr = ld_bf4(pp + c) * pm, qk = ld_bf4(pp + COL_K + c) * pm, qv = ld_bf4(pp + COL_V + c) * pm;
;             const f32x4 r = cr + (qr - cr) * mr, k = ck + (qk - ck) * mk, v = cv + (qv - cv) * mv;
;             const f32x4 w0v = *(const f32x4*)(w0 + c), a0v = *(const f32x4*)(a0 + c), kkv = *(const f32x4*)(kkp + c), kav = *(const f32x4*)(kap + c), rkv = *(const f32x4*)(rkp + c);
;             f32x4 dec, a, kk, k2;
; #pragma unroll
;             for (int j = 0; j < 4; ++j) {
;                 const float z = -(w0v[j] + aw[j]);
;                 const float sp = fmaxf(z, 0.f) + __logf(1.0f + __expf(-fabsf(z)));
;                 dec[j] = __expf(-__expf(-sp - 0.5f));
;                 a[j] = sigmoidf_(a0v[j] + aa[j]);
	v_mfma_f32_16x16x32_bf16 v[40:43], v[40:43], v[20:23], 0
	s_waitcnt vmcnt(6)
	v_mfma_f32_16x16x32_bf16 v[56:59], v[56:59], v[28:31], 0
	s_waitcnt vmcnt(5)
	v_mfma_f32_16x16x32_bf16 v[64:67], v[60:63], v[24:27], v[40:43]
	s_nop 3
	v_or_b32_e32 v40, s0, v181
	v_lshlrev_b32_e32 v40, 2, v40
	s_waitcnt vmcnt(4)
	v_mfma_f32_16x16x32_bf16 v[60:63], v[68:71], v[32:35], v[56:59]
	global_load_dwordx4 v[68:71], v184, s[8:9] offset:64
	s_nop 1
	global_load_dwordx4 v[56:59], v184, s[8:9] offset:3136
	s_nop 0
	global_load_dwordx4 v[40:43], v40, s[52:53]
	s_nop 0
	global_load_dwordx2 v[72:73], v[134:135], off offset:32
	global_load_dwordx2 v[146:147], v[134:135], off offset:1568
	global_load_dwordx2 v[76:77], v[134:135], off offset:3104
	s_waitcnt vmcnt(9)
	v_mfma_f32_16x16x32_bf16 v[52:55], v[52:55], v[4:7], 0
	global_load_dwordx2 v[80:81], v[132:133], off offset:1568
	s_waitcnt vmcnt(3)
	v_lshlrev_b32_e32 v74, 16, v72
	s_waitcnt vmcnt(1)
	v_lshlrev_b32_e32 v154, 16, v76
	v_and_b32_e32 v155, 0xffff0000, v76
	v_lshlrev_b32_e32 v156, 16, v77
	v_and_b32_e32 v157, 0xffff0000, v77
	global_load_dwordx2 v[76:77], v[132:133], off offset:32
	v_and_b32_e32 v75, 0xffff0000, v72
	v_xor_b32_e32 v85, 0x80000000, v75
	v_xor_b32_e32 v84, 0x80000000, v74
	v_lshlrev_b32_e32 v72, 16, v73
	v_and_b32_e32 v73, 0xffff0000, v73
	v_mfma_f32_16x16x32_bf16 v[48:51], v[48:51], v[8:11], v[52:55]
	s_waitcnt vmcnt(1)
	v_lshlrev_b32_e32 v148, 16, v80
	v_and_b32_e32 v149, 0xffff0000, v80
	v_lshlrev_b32_e32 v150, 16, v81
	v_and_b32_e32 v151, 0xffff0000, v81
	global_load_dwordx2 v[80:81], v[132:133], off offset:3104
	v_mfma_f32_16x16x32_bf16 v[44:47], v[44:47], v[12:15], v[48:51]
	s_waitcnt vmcnt(1)
	v_lshlrev_b32_e32 v78, 16, v76
	v_and_b32_e32 v79, 0xffff0000, v76
	v_pk_fma_f32 v[78:79], v[0:1], v[78:79], v[84:85]
	v_lshlrev_b32_e32 v76, 16, v77
	v_and_b32_e32 v77, 0xffff0000, v77
	v_xor_b32_e32 v85, 0x80000000, v73
	v_xor_b32_e32 v84, 0x80000000, v72
	v_pk_fma_f32 v[160:161], v[68:69], v[78:79], v[74:75]
	v_xor_b32_e32 v69, 0x80000000, v155
	v_xor_b32_e32 v68, 0x80000000, v154
	v_pk_fma_f32 v[76:77], v[100:101], v[76:77], v[84:85]
	v_mfma_f32_16x16x32_bf16 v[36:39], v[36:39], v[16:19], v[44:47]
	v_fma_f32 v158, v70, v76, v72
	v_fma_f32 v159, v71, v77, v73
	s_waitcnt vmcnt(0)
	v_lshlrev_b32_e32 v82, 16, v80
	v_and_b32_e32 v83, 0xffff0000, v80
	v_lshlrev_b32_e32 v80, 16, v81
	v_and_b32_e32 v81, 0xffff0000, v81
	v_lshl_add_u64 v[44:45], v[120:121], 0, v[106:107]
	v_cvt_pk_bf16_f32 v36, v36, v37
	v_cvt_pk_bf16_f32 v37, v38, v39
	v_pk_fma_f32 v[162:163], v[0:1], v[82:83], v[68:69]
	v_xor_b32_e32 v69, 0x80000000, v157
	v_xor_b32_e32 v68, 0x80000000, v156
	v_pk_fma_f32 v[164:165], v[100:101], v[80:81], v[68:69]
	global_load_dwordx4 v[84:87], v184, s[42:43] offset:64
	global_load_dwordx4 v[80:83], v184, s[44:45] offset:64
	global_load_dwordx4 v[72:75], v184, s[46:47] offset:64
	global_load_dwordx4 v[76:79], v184, s[48:49] offset:64
	global_load_dwordx4 v[68:71], v184, s[50:51] offset:64
	v_pk_fma_f32 v[40:41], v[40:41], v[162:163], v[154:155]
	v_pk_fma_f32 v[42:43], v[42:43], v[164:165], v[156:157]
	v_cvt_pk_bf16_f32 v40, v40, v41
	v_cvt_pk_bf16_f32 v41, v42, v43
	s_waitcnt vmcnt(4)
	v_add_f32_e32 v64, v64, v84
	v_max_f32_e64 v84, -v64, 0
	v_mul_f32_e64 v64, |v64|, s57
	s_waitcnt vmcnt(3)
	v_add_f32_e32 v60, v60, v80
	v_exp_f32_e32 v64, v64
	v_mul_f32_e32 v60, 0xbfb8aa3b, v60
	v_exp_f32_e32 v60, v60
	v_add_f32_e32 v64, 1.0, v64
	v_cmp_gt_f32_e64 s[0:1], s75, v64
	v_add_f32_e32 v60, 1.0, v60
	s_nop 0
	v_cndmask_b32_e64 v142, 0, 32, s[0:1]
	v_ldexp_f32 v64, v64, v142
	v_log_f32_e32 v64, v64
	s_nop 0
	v_mul_f32_e32 v142, 0x3f317217, v64
	v_cmp_lt_f32_e64 s[4:5], |v64|, s59
	v_fma_f32 v142, v64, s58, -v142
	v_fmac_f32_e32 v142, 0x3377d1cf, v64
	v_fmac_f32_e32 v142, 0x3f317217, v64
	v_cndmask_b32_e64 v64, v64, v142, s[4:5]
	v_cndmask_b32_e64 v142, 0, v243, s[0:1]
	v_sub_f32_e32 v64, v64, v142
	v_rcp_f32_e32 v142, v60
	v_add_f32_e32 v60, v65, v85
	v_max_f32_e64 v65, -v60, 0
	v_mul_f32_e64 v60, |v60|, s57
	v_add_f32_e32 v64, v84, v64
	v_exp_f32_e32 v60, v60
	v_sub_f32_e32 v64, -0.5, v64
	v_mul_f32_e32 v64, 0x3fb8aa3b, v64
	v_exp_f32_e32 v64, v64
	v_add_f32_e32 v60, 1.0, v60
	v_cmp_gt_f32_e64 s[0:1], s75, v60
	v_mul_f32_e32 v64, 0xbfb8aa3b, v64
	s_nop 0
	v_cndmask_b32_e64 v80, 0, 32, s[0:1]
	v_ldexp_f32 v60, v60, v80
	v_exp_f32_e32 v64, v64
	v_log_f32_e32 v60, v60
	s_nop 0
	v_mul_f32_e32 v80, 0x3f317217, v60
	v_cmp_lt_f32_e64 s[4:5], |v60|, s59
	v_fma_f32 v80, v60, s58, -v80
	v_fmac_f32_e32 v80, 0x3377d1cf, v60
	v_fmac_f32_e32 v80, 0x3f317217, v60
	v_cndmask_b32_e64 v60, v60, v80, s[4:5]
	v_cndmask_b32_e64 v80, 0, v243, s[0:1]
	v_sub_f32_e32 v60, v60, v80
	v_add_f32_e32 v60, v65, v60
	v_sub_f32_e32 v60, -0.5, v60
	v_mul_f32_e32 v60, 0x3fb8aa3b, v60
	v_exp_f32_e32 v60, v60
	s_nop 0
	v_mul_f32_e32 v60, 0xbfb8aa3b, v60
	v_exp_f32_e32 v65, v60
	v_add_f32_e32 v60, v61, v81
	v_mul_f32_e32 v60, 0xbfb8aa3b, v60
	v_exp_f32_e32 v60, v60
	s_nop 0
	v_add_f32_e32 v60, 1.0, v60
	v_rcp_f32_e32 v143, v60
	v_add_f32_e32 v60, v66, v86
	v_max_f32_e64 v61, -v60, 0
	v_mul_f32_e64 v60, |v60|, s57
	v_exp_f32_e32 v60, v60
	s_nop 0
	v_add_f32_e32 v60, 1.0, v60
	v_cmp_gt_f32_e64 s[0:1], s75, v60
	s_nop 1
	v_cndmask_b32_e64 v66, 0, 32, s[0:1]
	v_ldexp_f32 v60, v60, v66
	v_log_f32_e32 v60, v60
	s_nop 0
	v_mul_f32_e32 v66, 0x3f317217, v60
	v_cmp_lt_f32_e64 s[4:5], |v60|, s59
	v_fma_f32 v66, v60, s58, -v66
	v_fmac_f32_e32 v66, 0x3377d1cf, v60
	v_fmac_f32_e32 v66, 0x3f317217, v60
	v_cndmask_b32_e64 v60, v60, v66, s[4:5]
	v_cndmask_b32_e64 v66, 0, v243, s[0:1]
	v_sub_f32_e32 v60, v60, v66
	v_add_f32_e32 v60, v61, v60
; __device__ __forceinline__ float sigmoidf_(float x) { return __builtin_amdgcn_rcpf(1.0f + __expf(-x)); }
; __device__ __forceinline__ void st_bf4(unsigned char* q, f32x4 v) { u32x2 w; w.x = cvt_pk_bf16(v[0], v[1]); w.y = cvt_pk_bf16(v[2], v[3]); *(u32x2*)q = w; }
; __device__ __forceinline__ void rwkv_prep_item(const Params& p, const Lt& lt, int l, int item) {
;     ...
;             for (int j = 0; j < 4; ++j) {
;                 const float z = -(w0v[j] + aw[j]);
;                 const float sp = fmaxf(z, 0.f) + __logf(1.0f + __expf(-fabsf(z)));
;                 dec[j] = __expf(-__expf(-sp - 0.5f));
;                 a[j] = sigmoidf_(a0v[j] + aa[j]);
;                 kk[j] = k[j] * kkv[j];
;                 nrm += kk[j] * kk[j];
;                 k2[j] = k[j] * (1.0f + (a[j] - 1.0f) * kav[j]);
;                 bon += r[j] * k2[j] * rkv[j];
;             }
;             va[ct] = a; vkk[ct] = kk;
;             { const int cc = ct * 16 + quad * 4; *(f32x4*)(ob + cc * 4) = dec; st_bf4(ob + 512 + cc * 2, k2); st_bf4(ob + 640 + cc * 2, v); st_bf4(ob + 768 + cc * 2, r); }
;             st_bf4((unsigned char*)((bf16_t*)gate + (size_t)t * RW + c), ag);
;         }
	v_sub_f32_e32 v60, -0.5, v60
	v_mul_f32_e32 v60, 0x3fb8aa3b, v60
	v_exp_f32_e32 v60, v60
	s_nop 0
	v_mul_f32_e32 v60, 0xbfb8aa3b, v60
	v_exp_f32_e32 v66, v60
	v_add_f32_e32 v60, v62, v82
	v_mul_f32_e32 v60, 0xbfb8aa3b, v60
	v_exp_f32_e32 v60, v60
	s_nop 0
	v_add_f32_e32 v60, 1.0, v60
	v_rcp_f32_e32 v144, v60
	v_add_f32_e32 v60, v67, v87
	v_max_f32_e64 v61, -v60, 0
	v_mul_f32_e64 v60, |v60|, s57
	v_exp_f32_e32 v60, v60
	s_nop 0
	v_add_f32_e32 v60, 1.0, v60
	v_cmp_gt_f32_e64 s[0:1], s75, v60
	s_nop 1
	v_cndmask_b32_e64 v62, 0, 32, s[0:1]
	v_ldexp_f32 v60, v60, v62
	v_log_f32_e32 v60, v60
	s_nop 0
	v_mul_f32_e32 v62, 0x3f317217, v60
	v_cmp_lt_f32_e64 s[4:5], |v60|, s59
	v_fma_f32 v62, v60, s58, -v62
	v_fmac_f32_e32 v62, 0x3377d1cf, v60
	v_fmac_f32_e32 v62, 0x3f317217, v60
	v_cndmask_b32_e64 v60, v60, v62, s[4:5]
	v_cndmask_b32_e64 v62, 0, v243, s[0:1]
	v_sub_f32_e32 v60, v60, v62
	v_add_f32_e32 v60, v61, v60
	v_sub_f32_e32 v60, -0.5, v60
	v_mul_f32_e32 v60, 0x3fb8aa3b, v60
	v_exp_f32_e32 v60, v60
	v_and_b32_e32 v61, 0xffff0000, v147
	v_lshlrev_b32_e32 v62, 16, v146
	v_xor_b32_e32 v81, 0x80000000, v61
	v_mul_f32_e32 v60, 0xbfb8aa3b, v60
	v_exp_f32_e32 v67, v60
	v_add_f32_e32 v60, v63, v83
	v_mul_f32_e32 v60, 0xbfb8aa3b, v60
	v_exp_f32_e32 v60, v60
	v_and_b32_e32 v63, 0xffff0000, v146
	v_xor_b32_e32 v83, 0x80000000, v63
	v_xor_b32_e32 v82, 0x80000000, v62
	v_add_f32_e32 v60, 1.0, v60
	v_rcp_f32_e32 v145, v60
	v_lshlrev_b32_e32 v60, 16, v147
	v_xor_b32_e32 v80, 0x80000000, v60
	v_pk_fma_f32 v[80:81], v[100:101], v[150:151], v[80:81]
	v_pk_fma_f32 v[82:83], v[0:1], v[148:149], v[82:83]
	v_pk_fma_f32 v[58:59], v[58:59], v[80:81], v[60:61]
	v_pk_fma_f32 v[56:57], v[56:57], v[82:83], v[62:63]
	v_pk_add_f32 v[62:63], v[142:143], -1.0 op_sel_hi:[1,0]
	v_pk_add_f32 v[60:61], v[144:145], -1.0 op_sel_hi:[1,0]
	s_waitcnt vmcnt(1)
	v_pk_fma_f32 v[62:63], v[76:77], v[62:63], 1.0 op_sel_hi:[1,1,0]
	v_pk_fma_f32 v[60:61], v[78:79], v[60:61], 1.0 op_sel_hi:[1,1,0]
	v_pk_mul_f32 v[146:147], v[72:73], v[56:57]
	v_pk_mul_f32 v[56:57], v[56:57], v[62:63]
	v_pk_mul_f32 v[60:61], v[58:59], v[60:61]
	v_sub_u32_e32 v233, v44, v231
	ds_write_b128 v233, v[64:67]
	v_lshl_add_u64 v[44:45], v[120:121], 0, v[108:109]
	v_mul_f32_e32 v62, v160, v56
	v_cvt_pk_bf16_f32 v46, v56, v57
	v_cvt_pk_bf16_f32 v47, v60, v61
	v_sub_u32_e32 v233, v44, v231
	ds_write_b64 v233, v[40:41] offset:640
	v_cvt_pk_bf16_f32 v40, v160, v161
	v_cvt_pk_bf16_f32 v41, v158, v159
	s_or_b32 s0, s10, 32
	s_waitcnt vmcnt(0)
	v_fmac_f32_e32 v185, v68, v62
	v_mul_f32_e32 v62, v161, v57
	v_sub_u32_e32 v233, v44, v231
	ds_write_b64 v233, v[46:47] offset:512
	v_sub_u32_e32 v233, v44, v231
	ds_write_b64 v233, v[40:41] offset:768
	v_or_b32_e32 v44, s0, v180
	v_fmac_f32_e32 v185, v69, v62
	v_mul_f32_e32 v62, v158, v60
	v_sub_u32_e32 v233, v140, v237
	ds_write_b64 v233, v[36:37] offset:32
	v_lshlrev_b32_e32 v36, 7, v44
	v_mov_b32_e32 v37, v3
	v_fmac_f32_e32 v185, v70, v62
	v_pk_mul_f32 v[148:149], v[74:75], v[58:59]
	v_mul_f32_e32 v58, v159, v61
	v_lshl_add_u64 v[38:39], v[88:89], 0, v[36:37]
	v_fmac_f32_e32 v185, v71, v58
	v_lshl_add_u64 v[36:37], v[92:93], 0, v[36:37]
	global_load_dwordx4 v[40:43], v[38:39], off
	global_load_dwordx4 v[56:59], v[36:37], off
	global_load_dwordx4 v[60:63], v[38:39], off offset:64
	global_load_dwordx4 v[68:71], v[36:37], off offset:64
	v_lshlrev_b32_e32 v36, 8, v44
	v_mov_b32_e32 v37, v3
	v_lshl_add_u64 v[36:37], v[94:95], 0, v[36:37]
	global_load_dwordx4 v[52:55], v[36:37], off
	global_load_dwordx4 v[48:51], v[36:37], off offset:64
	global_load_dwordx4 v[44:47], v[36:37], off offset:128
	s_nop 0
	global_load_dwordx4 v[36:39], v[36:37], off offset:192
	v_pk_mul_f32 v[150:151], v[146:147], v[146:147]
	v_pk_mul_f32 v[152:153], v[148:149], v[148:149]
	s_waitcnt vmcnt(7)
	v_mfma_f32_16x16x32_bf16 v[40:43], v[40:43], v[20:23], 0
	s_waitcnt vmcnt(6)
	v_mfma_f32_16x16x32_bf16 v[56:59], v[56:59], v[28:31], 0
	s_waitcnt vmcnt(5)
	v_mfma_f32_16x16x32_bf16 v[64:67], v[60:63], v[24:27], v[40:43]
	s_nop 3
	v_or_b32_e32 v40, s0, v181
	v_lshlrev_b32_e32 v40, 2, v40
	s_waitcnt vmcnt(4)
	v_mfma_f32_16x16x32_bf16 v[60:63], v[68:71], v[32:35], v[56:59]
	global_load_dwordx4 v[68:71], v184, s[8:9] offset:128
	s_nop 1
	global_load_dwordx4 v[56:59], v184, s[8:9] offset:3200
	s_nop 0
	global_load_dwordx4 v[40:43], v40, s[52:53]
	s_nop 0
	global_load_dwordx2 v[72:73], v[134:135], off offset:64
	global_load_dwordx2 v[158:159], v[134:135], off offset:1600
	global_load_dwordx2 v[76:77], v[134:135], off offset:3136
	s_waitcnt vmcnt(9)
	v_mfma_f32_16x16x32_bf16 v[52:55], v[52:55], v[4:7], 0
	global_load_dwordx2 v[80:81], v[132:133], off offset:1600
	s_waitcnt vmcnt(3)
	v_lshlrev_b32_e32 v74, 16, v72
	s_waitcnt vmcnt(1)
	v_lshlrev_b32_e32 v166, 16, v76
	v_and_b32_e32 v167, 0xffff0000, v76
	v_lshlrev_b32_e32 v168, 16, v77
	v_and_b32_e32 v169, 0xffff0000, v77
	global_load_dwordx2 v[76:77], v[132:133], off offset:64
	v_and_b32_e32 v75, 0xffff0000, v72
	v_xor_b32_e32 v85, 0x80000000, v75
	v_xor_b32_e32 v84, 0x80000000, v74
	v_lshlrev_b32_e32 v72, 16, v73
	v_and_b32_e32 v73, 0xffff0000, v73
	v_mfma_f32_16x16x32_bf16 v[48:51], v[48:51], v[8:11], v[52:55]
	s_waitcnt vmcnt(1)
	v_lshlrev_b32_e32 v160, 16, v80
	v_and_b32_e32 v161, 0xffff0000, v80
	v_lshlrev_b32_e32 v162, 16, v81
	v_and_b32_e32 v163, 0xffff0000, v81
	global_load_dwordx2 v[80:81], v[132:133], off offset:3136
	v_mfma_f32_16x16x32_bf16 v[44:47], v[44:47], v[12:15], v[48:51]
	s_waitcnt vmcnt(1)
; __device__ __forceinline__ float sigmoidf_(float x) { return __builtin_amdgcn_rcpf(1.0f + __expf(-x)); }
; __device__ __forceinline__ f32x4 ld_bf4(const bf16_t* q) { const u32x2 u = *(const u32x2*)q; return (f32x4){bflo(u.x), bfhi(u.x), bflo(u.y), bfhi(u.y)}; }
; __device__ __forceinline__ void rwkv_prep_item(const Params& p, const Lt& lt, int l, int item) {
;     ...
;             const int c = h * 64 + ct * 16 + quad * 4;
;             const f32x4 mr = *(const f32x4*)(mu + c), mk = *(const f32x4*)(mu + COL_K + c), mv = *(const f32x4*)(mu + COL_V + c);
;             const f32x4 cr = ld_bf4(pt + c), ck = ld_bf4(pt + COL_K + c), cv = ld_bf4(pt + COL_V + c);
;             const f32x4 qr = ld_bf4(pp + c) * pm, qk = ld_bf4(pp + COL_K + c) * pm, qv = ld_bf4(pp + COL_V + c) * pm;
;             const f32x4 r = cr + (qr - cr) * mr, k = ck + (qk - ck) * mk, v = cv + (qv - cv) * mv;
;             const f32x4 w0v = *(const f32x4*)(w0 + c), a0v = *(const f32x4*)(a0 + c), kkv = *(const f32x4*)(kkp + c), kav = *(const f32x4*)(kap + c), rkv = *(const f32x4*)(rkp + c);
;             f32x4 dec, a, kk, k2;
; #pragma unroll
;             for (int j = 0; j < 4; ++j) {
;                 const float z = -(w0v[j] + aw[j]);
;                 const float sp = fmaxf(z, 0.f) + __logf(1.0f + __expf(-fabsf(z)));
;                 dec[j] = __expf(-__expf(-sp - 0.5f));
;                 a[j] = sigmoidf_(a0v[j] + aa[j]);
	v_lshlrev_b32_e32 v78, 16, v76
	v_and_b32_e32 v79, 0xffff0000, v76
	v_pk_fma_f32 v[78:79], v[0:1], v[78:79], v[84:85]
	v_lshlrev_b32_e32 v76, 16, v77
	v_and_b32_e32 v77, 0xffff0000, v77
	v_xor_b32_e32 v85, 0x80000000, v73
	v_xor_b32_e32 v84, 0x80000000, v72
	v_pk_fma_f32 v[172:173], v[68:69], v[78:79], v[74:75]
	v_xor_b32_e32 v69, 0x80000000, v167
	v_xor_b32_e32 v68, 0x80000000, v166
	v_pk_fma_f32 v[76:77], v[100:101], v[76:77], v[84:85]
	v_mfma_f32_16x16x32_bf16 v[36:39], v[36:39], v[16:19], v[44:47]
	v_fma_f32 v170, v70, v76, v72
	v_fma_f32 v171, v71, v77, v73
	s_waitcnt vmcnt(0)
	v_lshlrev_b32_e32 v82, 16, v80
	v_and_b32_e32 v83, 0xffff0000, v80
	v_lshlrev_b32_e32 v80, 16, v81
	v_and_b32_e32 v81, 0xffff0000, v81
	v_lshl_add_u64 v[44:45], v[120:121], 0, v[102:103]
	v_cvt_pk_bf16_f32 v36, v36, v37
	v_cvt_pk_bf16_f32 v37, v38, v39
	v_pk_fma_f32 v[174:175], v[0:1], v[82:83], v[68:69]
	v_xor_b32_e32 v69, 0x80000000, v169
	v_xor_b32_e32 v68, 0x80000000, v168
	v_pk_fma_f32 v[176:177], v[100:101], v[80:81], v[68:69]
	global_load_dwordx4 v[84:87], v184, s[42:43] offset:128
	global_load_dwordx4 v[80:83], v184, s[44:45] offset:128
	global_load_dwordx4 v[72:75], v184, s[46:47] offset:128
	global_load_dwordx4 v[76:79], v184, s[48:49] offset:128
	global_load_dwordx4 v[68:71], v184, s[50:51] offset:128
	v_pk_fma_f32 v[40:41], v[40:41], v[174:175], v[166:167]
	v_pk_fma_f32 v[42:43], v[42:43], v[176:177], v[168:169]
	v_cvt_pk_bf16_f32 v40, v40, v41
	v_cvt_pk_bf16_f32 v41, v42, v43
	s_waitcnt vmcnt(4)
	v_add_f32_e32 v64, v64, v84
	v_max_f32_e64 v84, -v64, 0
	v_mul_f32_e64 v64, |v64|, s57
	s_waitcnt vmcnt(3)
	v_add_f32_e32 v60, v60, v80
	v_exp_f32_e32 v64, v64
	v_mul_f32_e32 v60, 0xbfb8aa3b, v60
	v_exp_f32_e32 v60, v60
	v_add_f32_e32 v64, 1.0, v64
	v_cmp_gt_f32_e64 s[0:1], s75, v64
	v_add_f32_e32 v60, 1.0, v60
	s_nop 0
	v_cndmask_b32_e64 v154, 0, 32, s[0:1]
	v_ldexp_f32 v64, v64, v154
	v_log_f32_e32 v64, v64
	s_nop 0
	v_mul_f32_e32 v154, 0x3f317217, v64
	v_cmp_lt_f32_e64 s[4:5], |v64|, s59
	v_fma_f32 v154, v64, s58, -v154
	v_fmac_f32_e32 v154, 0x3377d1cf, v64
	v_fmac_f32_e32 v154, 0x3f317217, v64
	v_cndmask_b32_e64 v64, v64, v154, s[4:5]
	v_cndmask_b32_e64 v154, 0, v243, s[0:1]
	v_sub_f32_e32 v64, v64, v154
	v_rcp_f32_e32 v154, v60
	v_add_f32_e32 v60, v65, v85
	v_max_f32_e64 v65, -v60, 0
	v_mul_f32_e64 v60, |v60|, s57
	v_add_f32_e32 v64, v84, v64
	v_exp_f32_e32 v60, v60
	v_sub_f32_e32 v64, -0.5, v64
	v_mul_f32_e32 v64, 0x3fb8aa3b, v64
	v_exp_f32_e32 v64, v64
	v_add_f32_e32 v60, 1.0, v60
	v_cmp_gt_f32_e64 s[0:1], s75, v60
	v_mul_f32_e32 v64, 0xbfb8aa3b, v64
	s_nop 0
	v_cndmask_b32_e64 v80, 0, 32, s[0:1]
	v_ldexp_f32 v60, v60, v80
	v_exp_f32_e32 v64, v64
	v_log_f32_e32 v60, v60
	s_nop 0
	v_mul_f32_e32 v80, 0x3f317217, v60
	v_fma_f32 v80, v60, s58, -v80
	v_fmac_f32_e32 v80, 0x3377d1cf, v60
	v_fmac_f32_e32 v80, 0x3f317217, v60
	v_cmp_lt_f32_e64 s[4:5], |v60|, s59
	s_nop 1
	v_cndmask_b32_e64 v60, v60, v80, s[4:5]
	v_cndmask_b32_e64 v80, 0, v243, s[0:1]
	v_sub_f32_e32 v60, v60, v80
	v_add_f32_e32 v60, v65, v60
	v_sub_f32_e32 v60, -0.5, v60
	v_mul_f32_e32 v60, 0x3fb8aa3b, v60
	v_exp_f32_e32 v60, v60
	s_nop 0
	v_mul_f32_e32 v60, 0xbfb8aa3b, v60
	v_exp_f32_e32 v65, v60
	v_add_f32_e32 v60, v61, v81
	v_mul_f32_e32 v60, 0xbfb8aa3b, v60
	v_exp_f32_e32 v60, v60
	s_nop 0
	v_add_f32_e32 v60, 1.0, v60
	v_rcp_f32_e32 v155, v60
	v_add_f32_e32 v60, v66, v86
	v_max_f32_e64 v61, -v60, 0
	v_mul_f32_e64 v60, |v60|, s57
	v_exp_f32_e32 v60, v60
	s_nop 0
	v_add_f32_e32 v60, 1.0, v60
	v_cmp_gt_f32_e64 s[0:1], s75, v60
	s_nop 1
	v_cndmask_b32_e64 v66, 0, 32, s[0:1]
	v_ldexp_f32 v60, v60, v66
	v_log_f32_e32 v60, v60
	s_nop 0
	v_mul_f32_e32 v66, 0x3f317217, v60
	v_fma_f32 v66, v60, s58, -v66
	v_fmac_f32_e32 v66, 0x3377d1cf, v60
	v_fmac_f32_e32 v66, 0x3f317217, v60
	v_cmp_lt_f32_e64 s[4:5], |v60|, s59
	s_nop 1
	v_cndmask_b32_e64 v60, v60, v66, s[4:5]
	v_cndmask_b32_e64 v66, 0, v243, s[0:1]
	v_sub_f32_e32 v60, v60, v66
	v_add_f32_e32 v60, v61, v60
	v_sub_f32_e32 v60, -0.5, v60
	v_mul_f32_e32 v60, 0x3fb8aa3b, v60
	v_exp_f32_e32 v60, v60
	s_nop 0
	v_mul_f32_e32 v60, 0xbfb8aa3b, v60
	v_exp_f32_e32 v66, v60
	v_add_f32_e32 v60, v62, v82
	v_mul_f32_e32 v60, 0xbfb8aa3b, v60
	v_exp_f32_e32 v60, v60
	s_nop 0
	v_add_f32_e32 v60, 1.0, v60
	v_rcp_f32_e32 v156, v60
	v_add_f32_e32 v60, v67, v87
	v_max_f32_e64 v61, -v60, 0
	v_mul_f32_e64 v60, |v60|, s57
	v_exp_f32_e32 v60, v60
	s_nop 0
	v_add_f32_e32 v60, 1.0, v60
	v_cmp_gt_f32_e64 s[0:1], s75, v60
	s_nop 1
	v_cndmask_b32_e64 v62, 0, 32, s[0:1]
	v_ldexp_f32 v60, v60, v62
	v_log_f32_e32 v60, v60
	s_nop 0
	v_mul_f32_e32 v62, 0x3f317217, v60
	v_fma_f32 v62, v60, s58, -v62
	v_fmac_f32_e32 v62, 0x3377d1cf, v60
	v_fmac_f32_e32 v62, 0x3f317217, v60
	v_cmp_lt_f32_e64 s[4:5], |v60|, s59
	s_nop 1
	v_cndmask_b32_e64 v60, v60, v62, s[4:5]
	v_cndmask_b32_e64 v62, 0, v243, s[0:1]
	v_sub_f32_e32 v60, v60, v62
	v_add_f32_e32 v60, v61, v60
	v_sub_f32_e32 v60, -0.5, v60
	v_mul_f32_e32 v60, 0x3fb8aa3b, v60
	v_exp_f32_e32 v60, v60
	v_and_b32_e32 v61, 0xffff0000, v159
	v_lshlrev_b32_e32 v62, 16, v158
	v_xor_b32_e32 v81, 0x80000000, v61
	v_mul_f32_e32 v60, 0xbfb8aa3b, v60
	v_exp_f32_e32 v67, v60
	v_add_f32_e32 v60, v63, v83
	v_mul_f32_e32 v60, 0xbfb8aa3b, v60
	v_exp_f32_e32 v60, v60
	v_and_b32_e32 v63, 0xffff0000, v158
	v_xor_b32_e32 v83, 0x80000000, v63
	v_xor_b32_e32 v82, 0x80000000, v62
	v_add_f32_e32 v60, 1.0, v60
	v_rcp_f32_e32 v157, v60
	v_lshlrev_b32_e32 v60, 16, v159
	v_xor_b32_e32 v80, 0x80000000, v60
	v_pk_fma_f32 v[80:81], v[100:101], v[162:163], v[80:81]
	v_pk_fma_f32 v[82:83], v[0:1], v[160:161], v[82:83]
	v_pk_fma_f32 v[58:59], v[58:59], v[80:81], v[60:61]
	v_pk_fma_f32 v[56:57], v[56:57], v[82:83], v[62:63]
	v_pk_add_f32 v[62:63], v[154:155], -1.0 op_sel_hi:[1,0]
	v_pk_add_f32 v[60:61], v[156:157], -1.0 op_sel_hi:[1,0]
	s_waitcnt vmcnt(1)
; __device__ __forceinline__ float sigmoidf_(float x) { return __builtin_amdgcn_rcpf(1.0f + __expf(-x)); }
; __device__ __forceinline__ void st_bf4(unsigned char* q, f32x4 v) { u32x2 w; w.x = cvt_pk_bf16(v[0], v[1]); w.y = cvt_pk_bf16(v[2], v[3]); *(u32x2*)q = w; }
; __device__ __forceinline__ void rwkv_prep_item(const Params& p, const Lt& lt, int l, int item) {
;     ...
;             for (int j = 0; j < 4; ++j) {
;                 const float z = -(w0v[j] + aw[j]);
;                 const float sp = fmaxf(z, 0.f) + __logf(1.0f + __expf(-fabsf(z)));
;                 dec[j] = __expf(-__expf(-sp - 0.5f));
;                 a[j] = sigmoidf_(a0v[j] + aa[j]);
;                 kk[j] = k[j] * kkv[j];
;                 nrm += kk[j] * kk[j];
;                 k2[j] = k[j] * (1.0f + (a[j] - 1.0f) * kav[j]);
;                 bon += r[j] * k2[j] * rkv[j];
;             }
;             va[ct] = a; vkk[ct] = kk;
;             { const int cc = ct * 16 + quad * 4; *(f32x4*)(ob + cc * 4) = dec; st_bf4(ob + 512 + cc * 2, k2); st_bf4(ob + 640 + cc * 2, v); st_bf4(ob + 768 + cc * 2, r); }
;             st_bf4((unsigned char*)((bf16_t*)gate + (size_t)t * RW + c), ag);
;         }
	v_pk_fma_f32 v[62:63], v[76:77], v[62:63], 1.0 op_sel_hi:[1,1,0]
	v_pk_fma_f32 v[60:61], v[78:79], v[60:61], 1.0 op_sel_hi:[1,1,0]
	v_pk_mul_f32 v[158:159], v[72:73], v[56:57]
	v_pk_mul_f32 v[56:57], v[56:57], v[62:63]
	v_pk_mul_f32 v[60:61], v[58:59], v[60:61]
	v_sub_u32_e32 v233, v44, v231
	ds_write_b128 v233, v[64:67]
	v_lshl_add_u64 v[44:45], v[120:121], 0, v[104:105]
	v_mul_f32_e32 v62, v172, v56
	v_cvt_pk_bf16_f32 v46, v56, v57
	v_cvt_pk_bf16_f32 v47, v60, v61
	v_sub_u32_e32 v233, v44, v231
	ds_write_b64 v233, v[40:41] offset:640
	v_cvt_pk_bf16_f32 v40, v172, v173
	v_cvt_pk_bf16_f32 v41, v170, v171
	s_or_b32 s0, s10, 48
	s_waitcnt vmcnt(0)
	v_fmac_f32_e32 v185, v68, v62
	v_mul_f32_e32 v62, v173, v57
	v_sub_u32_e32 v233, v44, v231
	ds_write_b64 v233, v[46:47] offset:512
	v_sub_u32_e32 v233, v44, v231
	ds_write_b64 v233, v[40:41] offset:768
	v_or_b32_e32 v44, s0, v180
	v_fmac_f32_e32 v185, v69, v62
	v_mul_f32_e32 v62, v170, v60
	v_sub_u32_e32 v233, v140, v237
	ds_write_b64 v233, v[36:37] offset:64
	v_lshlrev_b32_e32 v36, 7, v44
	v_mov_b32_e32 v37, v3
	v_fmac_f32_e32 v185, v70, v62
	v_pk_mul_f32 v[160:161], v[74:75], v[58:59]
	v_mul_f32_e32 v58, v171, v61
	v_lshl_add_u64 v[38:39], v[88:89], 0, v[36:37]
	v_fmac_f32_e32 v185, v71, v58
	v_lshl_add_u64 v[36:37], v[92:93], 0, v[36:37]
	global_load_dwordx4 v[40:43], v[38:39], off
	global_load_dwordx4 v[56:59], v[36:37], off
	global_load_dwordx4 v[60:63], v[38:39], off offset:64
	global_load_dwordx4 v[68:71], v[36:37], off offset:64
	v_lshlrev_b32_e32 v36, 8, v44
	v_mov_b32_e32 v37, v3
	v_lshl_add_u64 v[36:37], v[94:95], 0, v[36:37]
	global_load_dwordx4 v[52:55], v[36:37], off
	global_load_dwordx4 v[48:51], v[36:37], off offset:64
	global_load_dwordx4 v[44:47], v[36:37], off offset:128
	s_nop 0
	global_load_dwordx4 v[36:39], v[36:37], off offset:192
	v_pk_mul_f32 v[162:163], v[158:159], v[158:159]
	v_pk_mul_f32 v[164:165], v[160:161], v[160:161]
	s_waitcnt vmcnt(7)
	v_mfma_f32_16x16x32_bf16 v[40:43], v[40:43], v[20:23], 0
	s_waitcnt vmcnt(6)
	v_mfma_f32_16x16x32_bf16 v[56:59], v[56:59], v[28:31], 0
	s_waitcnt vmcnt(5)
	v_mfma_f32_16x16x32_bf16 v[64:67], v[60:63], v[24:27], v[40:43]
	s_nop 3
	v_or_b32_e32 v40, s0, v181
	v_lshlrev_b32_e32 v40, 2, v40
	s_waitcnt vmcnt(4)
	v_mfma_f32_16x16x32_bf16 v[60:63], v[68:71], v[32:35], v[56:59]
	global_load_dwordx4 v[68:71], v184, s[8:9] offset:192
	s_nop 1
	global_load_dwordx4 v[56:59], v184, s[8:9] offset:3264
	s_nop 0
	global_load_dwordx4 v[40:43], v40, s[52:53]
	s_nop 0
	global_load_dwordx2 v[72:73], v[134:135], off offset:96
	global_load_dwordx2 v[174:175], v[134:135], off offset:1632
	global_load_dwordx2 v[76:77], v[134:135], off offset:3168
	s_waitcnt vmcnt(9)
	v_mfma_f32_16x16x32_bf16 v[52:55], v[52:55], v[4:7], 0
	global_load_dwordx2 v[80:81], v[132:133], off offset:1632
	s_waitcnt vmcnt(3)
	v_lshlrev_b32_e32 v74, 16, v72
	s_waitcnt vmcnt(1)
	v_lshlrev_b32_e32 v134, 16, v76
	v_and_b32_e32 v135, 0xffff0000, v76
	v_lshlrev_b32_e32 v166, 16, v77
	v_and_b32_e32 v167, 0xffff0000, v77
	global_load_dwordx2 v[76:77], v[132:133], off offset:96
	v_and_b32_e32 v75, 0xffff0000, v72
	v_xor_b32_e32 v85, 0x80000000, v75
	v_xor_b32_e32 v84, 0x80000000, v74
	v_lshlrev_b32_e32 v72, 16, v73
	v_and_b32_e32 v73, 0xffff0000, v73
	v_mfma_f32_16x16x32_bf16 v[48:51], v[48:51], v[8:11], v[52:55]
	s_waitcnt vmcnt(1)
	v_lshlrev_b32_e32 v176, 16, v80
	v_and_b32_e32 v177, 0xffff0000, v80
	v_lshlrev_b32_e32 v178, 16, v81
	v_and_b32_e32 v179, 0xffff0000, v81
	global_load_dwordx2 v[80:81], v[132:133], off offset:3168
	v_mfma_f32_16x16x32_bf16 v[44:47], v[44:47], v[12:15], v[48:51]
	s_waitcnt vmcnt(1)
	v_lshlrev_b32_e32 v78, 16, v76
	v_and_b32_e32 v79, 0xffff0000, v76
	v_pk_fma_f32 v[78:79], v[0:1], v[78:79], v[84:85]
	v_lshlrev_b32_e32 v76, 16, v77
	v_and_b32_e32 v77, 0xffff0000, v77
	v_xor_b32_e32 v85, 0x80000000, v73
	v_xor_b32_e32 v84, 0x80000000, v72
	v_pk_fma_f32 v[168:169], v[68:69], v[78:79], v[74:75]
	v_xor_b32_e32 v69, 0x80000000, v135
	v_xor_b32_e32 v68, 0x80000000, v134
	v_pk_fma_f32 v[76:77], v[100:101], v[76:77], v[84:85]
	v_mfma_f32_16x16x32_bf16 v[36:39], v[36:39], v[16:19], v[44:47]
	v_fma_f32 v132, v70, v76, v72
	v_fma_f32 v133, v71, v77, v73
	s_waitcnt vmcnt(0)
	v_lshlrev_b32_e32 v82, 16, v80
	v_and_b32_e32 v83, 0xffff0000, v80
	v_lshlrev_b32_e32 v80, 16, v81
	v_and_b32_e32 v81, 0xffff0000, v81
	v_pk_fma_f32 v[170:171], v[0:1], v[82:83], v[68:69]
	v_xor_b32_e32 v69, 0x80000000, v167
	v_xor_b32_e32 v68, 0x80000000, v166
	v_pk_fma_f32 v[172:173], v[100:101], v[80:81], v[68:69]
	global_load_dwordx4 v[76:79], v184, s[42:43] offset:192
	global_load_dwordx4 v[84:87], v184, s[44:45] offset:192
	global_load_dwordx4 v[72:75], v184, s[46:47] offset:192
	global_load_dwordx4 v[80:83], v184, s[48:49] offset:192
	global_load_dwordx4 v[68:71], v184, s[50:51] offset:192
	v_pk_fma_f32 v[42:43], v[42:43], v[172:173], v[166:167]
	v_pk_fma_f32 v[40:41], v[40:41], v[170:171], v[134:135]
	v_lshl_add_u64 v[44:45], v[120:121], 0, v[96:97]
	v_cvt_pk_bf16_f32 v40, v40, v41
	v_cvt_pk_bf16_f32 v41, v42, v43
	v_cvt_pk_bf16_f32 v36, v36, v37
	v_cvt_pk_bf16_f32 v37, v38, v39
	s_waitcnt vmcnt(4)
	v_add_f32_e32 v64, v64, v76
	v_max_f32_e64 v76, -v64, 0
	v_mul_f32_e64 v64, |v64|, s57
	v_exp_f32_e32 v64, v64
	v_add_f32_e32 v65, v65, v77
	v_add_f32_e32 v66, v66, v78
	v_add_f32_e32 v67, v67, v79
	v_add_f32_e32 v64, 1.0, v64
	v_cmp_gt_f32_e64 s[0:1], s75, v64
	s_waitcnt vmcnt(3)
; __device__ __forceinline__ float quad_sum(float v) { v += xor16(v); v += xor32(v); return v; }
; __device__ __forceinline__ float sigmoidf_(float x) { return __builtin_amdgcn_rcpf(1.0f + __expf(-x)); }
; __device__ __forceinline__ void st_bf4(unsigned char* q, f32x4 v) { u32x2 w; w.x = cvt_pk_bf16(v[0], v[1]); w.y = cvt_pk_bf16(v[2], v[3]); *(u32x2*)q = w; }
; __device__ __forceinline__ void rwkv_prep_item(const Params& p, const Lt& lt, int l, int item) {
;     ...
;             const f32x4 r = cr + (qr - cr) * mr, k = ck + (qk - ck) * mk, v = cv + (qv - cv) * mv;
;             const f32x4 w0v = *(const f32x4*)(w0 + c), a0v = *(const f32x4*)(a0 + c), kkv = *(const f32x4*)(kkp + c), kav = *(const f32x4*)(kap + c), rkv = *(const f32x4*)(rkp + c);
;             f32x4 dec, a, kk, k2;
; #pragma unroll
;             for (int j = 0; j < 4; ++j) {
;                 const float z = -(w0v[j] + aw[j]);
;                 const float sp = fmaxf(z, 0.f) + __logf(1.0f + __expf(-fabsf(z)));
;                 dec[j] = __expf(-__expf(-sp - 0.5f));
;                 a[j] = sigmoidf_(a0v[j] + aa[j]);
;                 kk[j] = k[j] * kkv[j];
;                 nrm += kk[j] * kk[j];
;                 k2[j] = k[j] * (1.0f + (a[j] - 1.0f) * kav[j]);
;                 bon += r[j] * k2[j] * rkv[j];
;             }
;             va[ct] = a; vkk[ct] = kk;
;             { const int cc = ct * 16 + quad * 4; *(f32x4*)(ob + cc * 4) = dec; st_bf4(ob + 512 + cc * 2, k2); st_bf4(ob + 640 + cc * 2, v); st_bf4(ob + 768 + cc * 2, r); }
;             st_bf4((unsigned char*)((bf16_t*)gate + (size_t)t * RW + c), ag);
;         }
;         nrm = quad_sum(nrm); bon = quad_sum(bon);
	v_add_f32_e32 v60, v60, v84
	v_add_f32_e32 v61, v61, v85
	v_cndmask_b32_e64 v184, 0, 32, s[0:1]
	v_ldexp_f32 v64, v64, v184
	v_log_f32_e32 v64, v64
	v_mul_f32_e32 v60, 0xbfb8aa3b, v60
	v_mul_f32_e32 v61, 0xbfb8aa3b, v61
	v_exp_f32_e32 v60, v60
	v_mul_f32_e32 v184, 0x3f317217, v64
	v_fma_f32 v184, v64, s58, -v184
	v_fmac_f32_e32 v184, 0x3377d1cf, v64
	v_fmac_f32_e32 v184, 0x3f317217, v64
	v_cmp_lt_f32_e64 s[4:5], |v64|, s59
	v_exp_f32_e32 v61, v61
	v_add_f32_e32 v62, v62, v86
	v_cndmask_b32_e64 v64, v64, v184, s[4:5]
	v_cndmask_b32_e64 v184, 0, v243, s[0:1]
	v_sub_f32_e32 v64, v64, v184
	v_add_f32_e32 v64, v76, v64
	v_max_f32_e64 v76, -v65, 0
	v_mul_f32_e64 v65, |v65|, s57
	v_exp_f32_e32 v65, v65
	v_add_f32_e32 v63, v63, v87
	v_add_f32_e32 v60, 1.0, v60
	v_add_f32_e32 v61, 1.0, v61
	v_add_f32_e32 v65, 1.0, v65
	v_cmp_gt_f32_e64 s[0:1], s75, v65
	v_mul_f32_e32 v62, 0xbfb8aa3b, v62
	v_mul_f32_e32 v63, 0xbfb8aa3b, v63
	v_cndmask_b32_e64 v77, 0, 32, s[0:1]
	v_ldexp_f32 v65, v65, v77
	v_log_f32_e32 v65, v65
	v_rcp_f32_e32 v60, v60
	v_rcp_f32_e32 v61, v61
	v_exp_f32_e32 v62, v62
	v_mul_f32_e32 v77, 0x3f317217, v65
	v_fma_f32 v77, v65, s58, -v77
	v_fmac_f32_e32 v77, 0x3377d1cf, v65
	v_fmac_f32_e32 v77, 0x3f317217, v65
	v_cmp_lt_f32_e64 s[4:5], |v65|, s59
	v_exp_f32_e32 v63, v63
	v_lshlrev_b32_e32 v78, 16, v174
	v_cndmask_b32_e64 v65, v65, v77, s[4:5]
	v_cndmask_b32_e64 v77, 0, v243, s[0:1]
	v_sub_f32_e32 v65, v65, v77
	v_add_f32_e32 v65, v76, v65
	v_max_f32_e64 v76, -v66, 0
	v_mul_f32_e64 v66, |v66|, s57
	v_exp_f32_e32 v66, v66
	v_and_b32_e32 v79, 0xffff0000, v174
	v_xor_b32_e32 v87, 0x80000000, v79
	v_xor_b32_e32 v86, 0x80000000, v78
	v_add_f32_e32 v66, 1.0, v66
	v_cmp_gt_f32_e64 s[0:1], s75, v66
	v_pk_fma_f32 v[86:87], v[0:1], v[176:177], v[86:87]
	v_add_f32_e32 v62, 1.0, v62
	v_cndmask_b32_e64 v77, 0, 32, s[0:1]
	v_ldexp_f32 v66, v66, v77
	v_log_f32_e32 v66, v66
	v_add_f32_e32 v63, 1.0, v63
	v_pk_fma_f32 v[78:79], v[56:57], v[86:87], v[78:79]
	v_pk_add_f32 v[86:87], v[60:61], -1.0 op_sel_hi:[1,0]
	v_mul_f32_e32 v77, 0x3f317217, v66
	v_fma_f32 v77, v66, s58, -v77
	v_fmac_f32_e32 v77, 0x3377d1cf, v66
	v_fmac_f32_e32 v77, 0x3f317217, v66
	v_cmp_lt_f32_e64 s[4:5], |v66|, s59
	v_rcp_f32_e32 v62, v62
	v_rcp_f32_e32 v63, v63
	v_cndmask_b32_e64 v66, v66, v77, s[4:5]
	v_cndmask_b32_e64 v77, 0, v243, s[0:1]
	v_sub_f32_e32 v66, v66, v77
	v_add_f32_e32 v66, v76, v66
	v_max_f32_e64 v76, -v67, 0
	v_mul_f32_e64 v67, |v67|, s57
	v_exp_f32_e32 v67, v67
	s_waitcnt vmcnt(1)
	v_pk_fma_f32 v[80:81], v[80:81], v[86:87], 1.0 op_sel_hi:[1,1,0]
	v_pk_mul_f32 v[56:57], v[72:73], v[78:79]
	v_pk_mul_f32 v[78:79], v[78:79], v[80:81]
	v_add_f32_e32 v67, 1.0, v67
	v_cmp_gt_f32_e64 s[0:1], s75, v67
	v_mul_f32_e32 v80, v168, v78
	s_waitcnt vmcnt(0)
	v_fmac_f32_e32 v185, v68, v80
	v_cndmask_b32_e64 v77, 0, 32, s[0:1]
	v_ldexp_f32 v67, v67, v77
	v_log_f32_e32 v67, v67
	v_mul_f32_e32 v68, v169, v79
	v_fmac_f32_e32 v185, v69, v68
	v_pk_add_f32 v[68:69], v[62:63], -1.0 op_sel_hi:[1,0]
	v_mul_f32_e32 v77, 0x3f317217, v67
	v_fma_f32 v77, v67, s58, -v77
	v_fmac_f32_e32 v77, 0x3377d1cf, v67
	v_fmac_f32_e32 v77, 0x3f317217, v67
	v_cmp_lt_f32_e64 s[4:5], |v67|, s59
	v_pk_fma_f32 v[68:69], v[82:83], v[68:69], 1.0 op_sel_hi:[1,1,0]
	v_sub_f32_e32 v64, -0.5, v64
	v_cndmask_b32_e64 v67, v67, v77, s[4:5]
	v_cndmask_b32_e64 v77, 0, v243, s[0:1]
	v_sub_f32_e32 v67, v67, v77
	v_add_f32_e32 v67, v76, v67
	v_lshlrev_b32_e32 v76, 16, v175
	v_and_b32_e32 v77, 0xffff0000, v175
	v_xor_b32_e32 v85, 0x80000000, v77
	v_xor_b32_e32 v84, 0x80000000, v76
	v_pk_fma_f32 v[84:85], v[100:101], v[178:179], v[84:85]
	v_sub_f32_e32 v65, -0.5, v65
	v_pk_fma_f32 v[58:59], v[58:59], v[84:85], v[76:77]
	v_sub_f32_e32 v66, -0.5, v66
	v_pk_mul_f32 v[68:69], v[58:59], v[68:69]
	v_sub_f32_e32 v67, -0.5, v67
	v_mul_f32_e32 v76, v132, v68
	v_fmac_f32_e32 v185, v70, v76
	v_add_f32_e32 v70, v136, v137
	v_add_f32_e32 v70, v138, v70
	v_add_f32_e32 v70, v139, v70
	v_mul_f32_e32 v64, 0x3fb8aa3b, v64
	v_mul_f32_e32 v65, 0x3fb8aa3b, v65
	v_mul_f32_e32 v66, 0x3fb8aa3b, v66
	v_mul_f32_e32 v67, 0x3fb8aa3b, v67
	v_add_f32_e32 v70, v70, v150
	v_exp_f32_e32 v64, v64
	v_exp_f32_e32 v65, v65
	v_exp_f32_e32 v66, v66
	v_exp_f32_e32 v67, v67
	v_add_f32_e32 v70, v151, v70
	v_add_f32_e32 v70, v152, v70
	v_add_f32_e32 v70, v153, v70
	v_add_f32_e32 v70, v70, v162
	v_mul_f32_e32 v64, 0xbfb8aa3b, v64
	v_mul_f32_e32 v65, 0xbfb8aa3b, v65
	v_mul_f32_e32 v66, 0xbfb8aa3b, v66
	v_mul_f32_e32 v67, 0xbfb8aa3b, v67
	v_add_f32_e32 v70, v163, v70
	v_exp_f32_e32 v64, v64
	v_exp_f32_e32 v65, v65
	v_exp_f32_e32 v66, v66
	v_exp_f32_e32 v67, v67
	v_add_f32_e32 v70, v164, v70
	v_pk_mul_f32 v[72:73], v[56:57], v[56:57]
	v_add_f32_e32 v70, v165, v70
	v_pk_mul_f32 v[58:59], v[74:75], v[58:59]
	v_add_f32_e32 v70, v70, v72
	v_pk_mul_f32 v[74:75], v[58:59], v[58:59]
	v_add_f32_e32 v70, v73, v70
	v_add_f32_e32 v70, v74, v70
	v_sub_u32_e32 v233, v44, v231
	ds_write_b128 v233, v[64:67]
	v_lshl_add_u64 v[44:45], v[120:121], 0, v[98:99]
	v_add_f32_e32 v70, v75, v70
	v_cvt_pk_bf16_f32 v46, v78, v79
	v_cvt_pk_bf16_f32 v47, v68, v69
	v_sub_u32_e32 v233, v44, v231
	ds_write_b64 v233, v[40:41] offset:640
	v_cvt_pk_bf16_f32 v40, v168, v169
	v_cvt_pk_bf16_f32 v41, v132, v133
	v_sub_u32_e32 v233, v44, v231
	ds_write_b64 v233, v[46:47] offset:512
	v_sub_u32_e32 v233, v44, v231
	ds_write_b64 v233, v[40:41] offset:768
	v_sub_u32_e32 v233, v140, v237
	ds_write_b64 v233, v[36:37] offset:96
	ds_bpermute_b32 v36, v182, v70
	v_mul_f32_e32 v72, v133, v69
	v_fmac_f32_e32 v185, v71, v72
	s_waitcnt lgkmcnt(0)
	v_add_f32_e32 v36, v70, v36
	ds_bpermute_b32 v37, v183, v36
	s_waitcnt lgkmcnt(0)
; __device__ __forceinline__ float quad_sum(float v) { v += xor16(v); v += xor32(v); return v; }
; __device__ __forceinline__ void st_bf4(unsigned char* q, f32x4 v) { u32x2 w; w.x = cvt_pk_bf16(v[0], v[1]); w.y = cvt_pk_bf16(v[2], v[3]); *(u32x2*)q = w; }
; __device__ __forceinline__ void rwkv_prep_item(const Params& p, const Lt& lt, int l, int item) {
;     ...
;         nrm = quad_sum(nrm); bon = quad_sum(bon);
;         const float inv = rsqrtf(fmaxf(nrm, 1e-24f));
; #pragma unroll
;         for (int ct = 0; ct < 4; ++ct) {
;             const int cc = ct * 16 + quad * 4;
;             const f32x4 kkn = vkk[ct] * inv;
;             st_bf4(ob + 256 + cc * 2, -kkn);
;             st_bf4(ob + 384 + cc * 2, kkn * va[ct]);
;         }
;         if (quad == 0) bonus[(size_t)t * 16 + h] = bon;
	v_add_f32_e32 v38, v36, v37
	v_max_f32_e32 v38, 0x179abe15, v38
	v_rsq_f32_e32 v38, v38
	ds_bpermute_b32 v36, v182, v185
	v_pk_mul_f32 v[40:41], v[126:127], v[38:39] op_sel_hi:[1,0]
	v_pk_mul_f32 v[42:43], v[128:129], v[38:39] op_sel_hi:[1,0]
	v_xor_b32_e32 v44, 0x80000000, v41
	v_xor_b32_e32 v39, 0x80000000, v43
	v_xor_b32_e32 v45, 0x80000000, v42
	v_xor_b32_e32 v46, 0x80000000, v40
	v_pk_mul_f32 v[42:43], v[124:125], v[42:43]
	v_pk_mul_f32 v[40:41], v[122:123], v[40:41]
	v_cvt_pk_bf16_f32 v44, v46, v44
	v_cvt_pk_bf16_f32 v40, v40, v41
	v_cvt_pk_bf16_f32 v41, v42, v43
	v_cvt_pk_bf16_f32 v45, v45, v39
	v_sub_u32_e32 v233, v130, v231
	ds_write_b64 v233, v[40:41] offset:384
	v_pk_mul_f32 v[40:41], v[146:147], v[38:39] op_sel_hi:[1,0]
	v_pk_mul_f32 v[42:43], v[148:149], v[38:39] op_sel_hi:[1,0]
	v_sub_u32_e32 v233, v130, v231
	ds_write_b64 v233, v[44:45] offset:256
	v_xor_b32_e32 v39, 0x80000000, v43
	v_xor_b32_e32 v45, 0x80000000, v42
	v_xor_b32_e32 v44, 0x80000000, v41
	v_xor_b32_e32 v46, 0x80000000, v40
	v_pk_mul_f32 v[42:43], v[144:145], v[42:43]
	v_pk_mul_f32 v[40:41], v[142:143], v[40:41]
	s_waitcnt lgkmcnt(0)
	v_add_f32_e32 v36, v185, v36
	v_cvt_pk_bf16_f32 v40, v40, v41
	v_cvt_pk_bf16_f32 v41, v42, v43
	v_cvt_pk_bf16_f32 v44, v46, v44
	v_cvt_pk_bf16_f32 v45, v45, v39
	v_sub_u32_e32 v233, v130, v231
	ds_write_b64 v233, v[40:41] offset:416
	v_pk_mul_f32 v[40:41], v[158:159], v[38:39] op_sel_hi:[1,0]
	v_pk_mul_f32 v[42:43], v[160:161], v[38:39] op_sel_hi:[1,0]
	ds_bpermute_b32 v37, v183, v36
	v_sub_u32_e32 v233, v130, v231
	ds_write_b64 v233, v[44:45] offset:288
	v_xor_b32_e32 v39, 0x80000000, v43
	v_xor_b32_e32 v45, 0x80000000, v42
	v_xor_b32_e32 v44, 0x80000000, v41
	v_xor_b32_e32 v46, 0x80000000, v40
	v_pk_mul_f32 v[42:43], v[156:157], v[42:43]
	v_pk_mul_f32 v[40:41], v[154:155], v[40:41]
	v_cvt_pk_bf16_f32 v44, v46, v44
	v_cvt_pk_bf16_f32 v40, v40, v41
	v_cvt_pk_bf16_f32 v41, v42, v43
	v_cvt_pk_bf16_f32 v45, v45, v39
	v_sub_u32_e32 v233, v130, v231
	ds_write_b64 v233, v[40:41] offset:448
	v_pk_mul_f32 v[40:41], v[56:57], v[38:39] op_sel_hi:[1,0]
	v_pk_mul_f32 v[38:39], v[58:59], v[38:39] op_sel_hi:[1,0]
	v_sub_u32_e32 v233, v130, v231
	ds_write_b64 v233, v[44:45] offset:320
	v_xor_b32_e32 v43, 0x80000000, v39
	v_xor_b32_e32 v44, 0x80000000, v38
	v_xor_b32_e32 v42, 0x80000000, v41
	v_xor_b32_e32 v45, 0x80000000, v40
	v_pk_mul_f32 v[38:39], v[62:63], v[38:39]
	v_pk_mul_f32 v[40:41], v[60:61], v[40:41]
	v_cvt_pk_bf16_f32 v42, v45, v42
	v_cvt_pk_bf16_f32 v43, v44, v43
	v_cvt_pk_bf16_f32 v40, v40, v41
	v_cvt_pk_bf16_f32 v41, v38, v39
	v_sub_u32_e32 v233, v130, v231
	ds_write_b64 v233, v[42:43] offset:352
	v_sub_u32_e32 v233, v130, v231
	ds_write_b64 v233, v[40:41] offset:480
	s_waitcnt lgkmcnt(0)
	v_mov_b32_e32 v228, v234
	v_mov_b32_e32 v229, v235
	ds_read_b128 v[210:213], v226 offset:0
	ds_read_b128 v[214:217], v226 offset:1040
	ds_read_b128 v[218:221], v226 offset:2080
	ds_read_b128 v[222:225], v226 offset:3120
	s_waitcnt lgkmcnt(3)
	global_store_dwordx4 v[228:229], v[210:213], off
	v_lshl_add_u64 v[228:229], v[228:229], 0, v[194:195]
	s_waitcnt lgkmcnt(2)
	global_store_dwordx4 v[228:229], v[214:217], off
	v_lshl_add_u64 v[228:229], v[228:229], 0, v[194:195]
	s_waitcnt lgkmcnt(1)
	global_store_dwordx4 v[228:229], v[218:221], off
	v_lshl_add_u64 v[228:229], v[228:229], 0, v[194:195]
	s_waitcnt lgkmcnt(0)
	global_store_dwordx4 v[228:229], v[222:225], off
	v_lshl_add_u64 v[228:229], v[228:229], 0, v[194:195]
	ds_read_b128 v[210:213], v226 offset:4160
	ds_read_b128 v[214:217], v226 offset:5200
	ds_read_b128 v[218:221], v226 offset:6240
	ds_read_b128 v[222:225], v226 offset:7280
	s_waitcnt lgkmcnt(3)
	global_store_dwordx4 v[228:229], v[210:213], off
	v_lshl_add_u64 v[228:229], v[228:229], 0, v[194:195]
	s_waitcnt lgkmcnt(2)
	global_store_dwordx4 v[228:229], v[214:217], off
	v_lshl_add_u64 v[228:229], v[228:229], 0, v[194:195]
	s_waitcnt lgkmcnt(1)
	global_store_dwordx4 v[228:229], v[218:221], off
	v_lshl_add_u64 v[228:229], v[228:229], 0, v[194:195]
	s_waitcnt lgkmcnt(0)
	global_store_dwordx4 v[228:229], v[222:225], off
	v_lshl_add_u64 v[228:229], v[228:229], 0, v[194:195]
	ds_read_b128 v[210:213], v226 offset:8320
	ds_read_b128 v[214:217], v226 offset:9360
	ds_read_b128 v[218:221], v226 offset:10400
	ds_read_b128 v[222:225], v226 offset:11440
	s_waitcnt lgkmcnt(3)
	global_store_dwordx4 v[228:229], v[210:213], off
	v_lshl_add_u64 v[228:229], v[228:229], 0, v[194:195]
	s_waitcnt lgkmcnt(2)
	global_store_dwordx4 v[228:229], v[214:217], off
	v_lshl_add_u64 v[228:229], v[228:229], 0, v[194:195]
	s_waitcnt lgkmcnt(1)
	global_store_dwordx4 v[228:229], v[218:221], off
	v_lshl_add_u64 v[228:229], v[228:229], 0, v[194:195]
	s_waitcnt lgkmcnt(0)
	global_store_dwordx4 v[228:229], v[222:225], off
	v_lshl_add_u64 v[228:229], v[228:229], 0, v[194:195]
	ds_read_b128 v[210:213], v226 offset:12480
	ds_read_b128 v[214:217], v226 offset:13520
	ds_read_b128 v[218:221], v226 offset:14560
	ds_read_b128 v[222:225], v226 offset:15600
	s_waitcnt lgkmcnt(3)
	global_store_dwordx4 v[228:229], v[210:213], off
	v_lshl_add_u64 v[228:229], v[228:229], 0, v[194:195]
	s_waitcnt lgkmcnt(2)
	global_store_dwordx4 v[228:229], v[214:217], off
	v_lshl_add_u64 v[228:229], v[228:229], 0, v[194:195]
	s_waitcnt lgkmcnt(1)
	global_store_dwordx4 v[228:229], v[218:221], off
	v_lshl_add_u64 v[228:229], v[228:229], 0, v[194:195]
	s_waitcnt lgkmcnt(0)
	global_store_dwordx4 v[228:229], v[222:225], off
	v_lshl_add_u64 v[228:229], v[228:229], 0, v[194:195]
	v_lshl_add_u64 v[234:235], v[234:235], 0, v[198:199]
	s_and_saveexec_b64 s[0:1], vcc
	s_cbranch_execz .LBB0_347
	s_lshl_b32 s10, s56, 2
	v_lshl_add_u64 v[38:39], v[90:91], 0, s[10:11]
	s_waitcnt lgkmcnt(0)
	v_add_f32_e32 v36, v36, v37
	global_store_dword v[38:39], v36, off offset:4
; __device__ __forceinline__ f32x4 ld_bf4(const bf16_t* q) { const u32x2 u = *(const u32x2*)q; return (f32x4){bflo(u.x), bfhi(u.x), bflo(u.y), bfhi(u.y)}; }
; __device__ __forceinline__ void rwkv_prep_item(const Params& p, const Lt& lt, int l, int item) {
;     ...
;         unsigned char* ob = opnd + (size_t)t * OPTB + h * OPB;
; #pragma unroll
;         for (int ct = 0; ct < 4; ++ct) {
;             const int crow = h * 64 + ct * 16 + qi;
;             f32x4 aw = {0.f, 0.f, 0.f, 0.f}, aa = aw, ag = aw;
; #pragma unroll
;             for (int ks = 0; ks < 2; ++ks) {
;                 aw = __builtin_amdgcn_mfma_f32_16x16x32_bf16(*(const bf16x8*)(decT + crow * 64 + ks * 32 + quad * 8), fw[ks], aw, 0, 0, 0);
;                 aa = __builtin_amdgcn_mfma_f32_16x16x32_bf16(*(const bf16x8*)(aT + crow * 64 + ks * 32 + quad * 8), fa[ks], aa, 0, 0, 0);
;             }
; #pragma unroll
;             for (int ks = 0; ks < 4; ++ks) ag = __builtin_amdgcn_mfma_f32_16x16x32_bf16(*(const bf16x8*)(gT + crow * 128 + ks * 32 + quad * 8), fg[ks], ag, 0, 0, 0);
;             const int c = h * 64 + ct * 16 + quad * 4;
;             const f32x4 mr = *(const f32x4*)(mu + c), mk = *(const f32x4*)(mu + COL_K + c), mv = *(const f32x4*)(mu + COL_V + c);
;             const f32x4 cr = ld_bf4(pt + c), ck = ld_bf4(pt + COL_K + c), cv = ld_bf4(pt + COL_V + c);
;             const f32x4 qr = ld_bf4(pp + c) * pm, qk = ld_bf4(pp + COL_K + c) * pm, qv = ld_bf4(pp + COL_V + c) * pm;
;             const f32x4 r = cr + (qr - cr) * mr, k = ck + (qk - ck) * mk, v = cv + (qv - cv) * mv;
.LBB0_347:
	s_or_b64 exec, exec, s[0:1]
	s_add_i32 s0, s56, 2
	s_mul_i32 s10, s0, 0x380
	v_lshl_add_u64 v[118:119], v[118:119], 0, s[10:11]
	s_lshl_b32 s10, s0, 6
	v_or_b32_e32 v40, s10, v180
	v_lshlrev_b32_e32 v36, 7, v40
	s_waitcnt lgkmcnt(0)
	v_mov_b32_e32 v37, v3
	v_lshl_add_u64 v[38:39], v[88:89], 0, v[36:37]
	v_lshl_add_u64 v[36:37], v[92:93], 0, v[36:37]
	global_load_dwordx4 v[52:55], v[38:39], off
	global_load_dwordx4 v[56:59], v[36:37], off
	global_load_dwordx4 v[60:63], v[38:39], off offset:64
	global_load_dwordx4 v[68:71], v[36:37], off offset:64
	v_or_b32_e32 v72, s10, v181
	v_lshlrev_b32_e32 v36, 8, v40
	v_mov_b32_e32 v37, v3
	v_lshlrev_b32_e32 v132, 1, v72
	v_mov_b32_e32 v133, v3
	v_lshl_add_u64 v[36:37], v[94:95], 0, v[36:37]
	v_lshlrev_b32_e32 v158, 2, v72
	v_lshl_add_u64 v[126:127], v[114:115], 0, v[132:133]
	global_load_dwordx4 v[48:51], v[36:37], off
	global_load_dwordx4 v[44:47], v[36:37], off offset:64
	global_load_dwordx4 v[40:43], v[36:37], off offset:128
	s_nop 0
	global_load_dwordx4 v[36:39], v[36:37], off offset:192
	v_lshl_add_u64 v[124:125], v[110:111], 0, v[132:133]
	v_lshl_add_u64 v[116:117], v[116:117], 0, v[132:133]
	s_waitcnt vmcnt(7)
	v_mfma_f32_16x16x32_bf16 v[52:55], v[52:55], v[20:23], 0
	s_waitcnt vmcnt(6)
	v_mfma_f32_16x16x32_bf16 v[56:59], v[56:59], v[28:31], 0
	s_waitcnt vmcnt(5)
	v_mfma_f32_16x16x32_bf16 v[64:67], v[60:63], v[24:27], v[52:55]
	s_waitcnt vmcnt(4)
	v_mfma_f32_16x16x32_bf16 v[56:59], v[68:71], v[32:35], v[56:59]
	global_load_dwordx4 v[68:71], v158, s[8:9]
	global_load_dwordx4 v[60:63], v158, s[8:9] offset:3072
	global_load_dwordx4 v[52:55], v158, s[52:53]
	global_load_dwordx2 v[72:73], v[126:127], off
	global_load_dwordx2 v[120:121], v[126:127], off offset:1536
	global_load_dwordx2 v[76:77], v[126:127], off offset:3072
	s_waitcnt vmcnt(9)
	v_mfma_f32_16x16x32_bf16 v[48:51], v[48:51], v[4:7], 0
	global_load_dwordx2 v[80:81], v[124:125], off offset:1536
	s_waitcnt vmcnt(3)
	v_lshlrev_b32_e32 v74, 16, v72
	s_waitcnt vmcnt(1)
	v_lshlrev_b32_e32 v134, 16, v76
	v_and_b32_e32 v135, 0xffff0000, v76
	v_lshlrev_b32_e32 v136, 16, v77
	v_and_b32_e32 v137, 0xffff0000, v77
	global_load_dwordx2 v[76:77], v[124:125], off
	v_and_b32_e32 v75, 0xffff0000, v72
	v_xor_b32_e32 v85, 0x80000000, v75
	v_xor_b32_e32 v84, 0x80000000, v74
	v_lshlrev_b32_e32 v72, 16, v73
	v_and_b32_e32 v73, 0xffff0000, v73
	v_mfma_f32_16x16x32_bf16 v[44:47], v[44:47], v[8:11], v[48:51]
	s_waitcnt vmcnt(1)
	v_lshlrev_b32_e32 v122, 16, v80
	v_and_b32_e32 v123, 0xffff0000, v80
	v_lshlrev_b32_e32 v128, 16, v81
	v_and_b32_e32 v129, 0xffff0000, v81
	global_load_dwordx2 v[80:81], v[124:125], off offset:3072
	v_mfma_f32_16x16x32_bf16 v[40:43], v[40:43], v[12:15], v[44:47]
	s_waitcnt vmcnt(1)
	v_lshlrev_b32_e32 v78, 16, v76
	v_and_b32_e32 v79, 0xffff0000, v76
	v_pk_fma_f32 v[78:79], v[0:1], v[78:79], v[84:85]
	v_lshlrev_b32_e32 v76, 16, v77
	v_and_b32_e32 v77, 0xffff0000, v77
	v_xor_b32_e32 v85, 0x80000000, v73
	v_xor_b32_e32 v84, 0x80000000, v72
	v_pk_fma_f32 v[140:141], v[68:69], v[78:79], v[74:75]
	v_xor_b32_e32 v69, 0x80000000, v135
	v_xor_b32_e32 v68, 0x80000000, v134
	v_pk_fma_f32 v[76:77], v[100:101], v[76:77], v[84:85]
	v_mfma_f32_16x16x32_bf16 v[36:39], v[36:39], v[16:19], v[40:43]
	v_fma_f32 v138, v70, v76, v72
	v_fma_f32 v139, v71, v77, v73
	v_lshl_add_u64 v[44:45], v[118:119], 0, v[112:113]
	v_lshl_add_u64 v[112:113], v[118:119], 0, v[2:3]
	s_waitcnt vmcnt(0)
	v_lshlrev_b32_e32 v82, 16, v80
	v_and_b32_e32 v83, 0xffff0000, v80
	v_lshlrev_b32_e32 v80, 16, v81
	v_and_b32_e32 v81, 0xffff0000, v81
	v_cvt_pk_bf16_f32 v36, v36, v37
	v_cvt_pk_bf16_f32 v37, v38, v39
	v_pk_fma_f32 v[142:143], v[0:1], v[82:83], v[68:69]
	v_xor_b32_e32 v69, 0x80000000, v137
	v_xor_b32_e32 v68, 0x80000000, v136
	v_pk_fma_f32 v[144:145], v[100:101], v[80:81], v[68:69]
	global_load_dwordx4 v[84:87], v158, s[42:43]
	global_load_dwordx4 v[80:83], v158, s[44:45]
	global_load_dwordx4 v[68:71], v158, s[46:47]
	global_load_dwordx4 v[76:79], v158, s[48:49]
	global_load_dwordx4 v[72:75], v158, s[50:51]
	v_pk_fma_f32 v[42:43], v[52:53], v[142:143], v[134:135]
	v_pk_fma_f32 v[40:41], v[54:55], v[144:145], v[136:137]
	v_cvt_pk_bf16_f32 v42, v42, v43
	v_cvt_pk_bf16_f32 v43, v40, v41
	v_cvt_pk_bf16_f32 v40, v140, v141
	v_cvt_pk_bf16_f32 v41, v138, v139
	v_sub_u32_e32 v233, v112, v232
	ds_write_b64 v233, v[42:43] offset:640
	v_sub_u32_e32 v233, v112, v232
	ds_write_b64 v233, v[40:41] offset:768
	s_waitcnt vmcnt(4)
	v_add_f32_e32 v64, v64, v84
	v_max_f32_e64 v84, -v64, 0
	v_mul_f32_e64 v64, |v64|, s57
	s_waitcnt vmcnt(3)
; __device__ __forceinline__ float sigmoidf_(float x) { return __builtin_amdgcn_rcpf(1.0f + __expf(-x)); }
; __device__ __forceinline__ void st_bf4(unsigned char* q, f32x4 v) { u32x2 w; w.x = cvt_pk_bf16(v[0], v[1]); w.y = cvt_pk_bf16(v[2], v[3]); *(u32x2*)q = w; }
; __device__ __forceinline__ void rwkv_prep_item(const Params& p, const Lt& lt, int l, int item) {
;     ...
;             const f32x4 r = cr + (qr - cr) * mr, k = ck + (qk - ck) * mk, v = cv + (qv - cv) * mv;
;             const f32x4 w0v = *(const f32x4*)(w0 + c), a0v = *(const f32x4*)(a0 + c), kkv = *(const f32x4*)(kkp + c), kav = *(const f32x4*)(kap + c), rkv = *(const f32x4*)(rkp + c);
;             f32x4 dec, a, kk, k2;
; #pragma unroll
;             for (int j = 0; j < 4; ++j) {
;                 const float z = -(w0v[j] + aw[j]);
;                 const float sp = fmaxf(z, 0.f) + __logf(1.0f + __expf(-fabsf(z)));
;                 dec[j] = __expf(-__expf(-sp - 0.5f));
;                 a[j] = sigmoidf_(a0v[j] + aa[j]);
;                 kk[j] = k[j] * kkv[j];
;                 nrm += kk[j] * kk[j];
;                 k2[j] = k[j] * (1.0f + (a[j] - 1.0f) * kav[j]);
;                 bon += r[j] * k2[j] * rkv[j];
;             }
;             va[ct] = a; vkk[ct] = kk;
;             { const int cc = ct * 16 + quad * 4; *(f32x4*)(ob + cc * 4) = dec; st_bf4(ob + 512 + cc * 2, k2); st_bf4(ob + 640 + cc * 2, v); st_bf4(ob + 768 + cc * 2, r); }
;             st_bf4((unsigned char*)((bf16_t*)gate + (size_t)t * RW + c), ag);
;         }
	v_add_f32_e32 v56, v56, v80
	v_exp_f32_e32 v64, v64
	v_mul_f32_e32 v56, 0xbfb8aa3b, v56
	v_exp_f32_e32 v56, v56
	v_add_f32_e32 v64, 1.0, v64
	v_cmp_gt_f32_e64 s[0:1], s75, v64
	v_add_f32_e32 v56, 1.0, v56
	s_nop 0
	v_cndmask_b32_e64 v110, 0, 32, s[0:1]
	v_ldexp_f32 v64, v64, v110
	v_log_f32_e32 v64, v64
	s_nop 0
	v_mul_f32_e32 v110, 0x3f317217, v64
	v_cmp_lt_f32_e64 s[4:5], |v64|, s59
	v_fma_f32 v110, v64, s58, -v110
	v_fmac_f32_e32 v110, 0x3377d1cf, v64
	v_fmac_f32_e32 v110, 0x3f317217, v64
	v_cndmask_b32_e64 v64, v64, v110, s[4:5]
	v_cndmask_b32_e64 v110, 0, v243, s[0:1]
	v_sub_f32_e32 v64, v64, v110
	v_rcp_f32_e32 v110, v56
	v_add_f32_e32 v56, v65, v85
	v_max_f32_e64 v65, -v56, 0
	v_mul_f32_e64 v56, |v56|, s57
	v_add_f32_e32 v64, v84, v64
	v_exp_f32_e32 v56, v56
	v_sub_f32_e32 v64, -0.5, v64
	v_mul_f32_e32 v64, 0x3fb8aa3b, v64
	v_exp_f32_e32 v64, v64
	v_add_f32_e32 v56, 1.0, v56
	v_cmp_gt_f32_e64 s[0:1], s75, v56
	v_mul_f32_e32 v64, 0xbfb8aa3b, v64
	s_nop 0
	v_cndmask_b32_e64 v80, 0, 32, s[0:1]
	v_ldexp_f32 v56, v56, v80
	v_exp_f32_e32 v64, v64
	v_log_f32_e32 v56, v56
	s_nop 0
	v_mul_f32_e32 v80, 0x3f317217, v56
	v_cmp_lt_f32_e64 s[4:5], |v56|, s59
	v_fma_f32 v80, v56, s58, -v80
	v_fmac_f32_e32 v80, 0x3377d1cf, v56
	v_fmac_f32_e32 v80, 0x3f317217, v56
	v_cndmask_b32_e64 v56, v56, v80, s[4:5]
	v_cndmask_b32_e64 v80, 0, v243, s[0:1]
	v_sub_f32_e32 v56, v56, v80
	v_add_f32_e32 v56, v65, v56
	v_sub_f32_e32 v56, -0.5, v56
	v_mul_f32_e32 v56, 0x3fb8aa3b, v56
	v_exp_f32_e32 v56, v56
	s_nop 0
	v_mul_f32_e32 v56, 0xbfb8aa3b, v56
	v_exp_f32_e32 v65, v56
	v_add_f32_e32 v56, v57, v81
	v_mul_f32_e32 v56, 0xbfb8aa3b, v56
	v_exp_f32_e32 v56, v56
	s_nop 0
	v_add_f32_e32 v56, 1.0, v56
	v_rcp_f32_e32 v111, v56
	v_add_f32_e32 v56, v66, v86
	v_max_f32_e64 v57, -v56, 0
	v_mul_f32_e64 v56, |v56|, s57
	v_exp_f32_e32 v56, v56
	s_nop 0
	v_add_f32_e32 v56, 1.0, v56
	v_cmp_gt_f32_e64 s[0:1], s75, v56
	s_nop 1
	v_cndmask_b32_e64 v66, 0, 32, s[0:1]
	v_ldexp_f32 v56, v56, v66
	v_log_f32_e32 v56, v56
	s_nop 0
	v_mul_f32_e32 v66, 0x3f317217, v56
	v_cmp_lt_f32_e64 s[4:5], |v56|, s59
	v_fma_f32 v66, v56, s58, -v66
	v_fmac_f32_e32 v66, 0x3377d1cf, v56
	v_fmac_f32_e32 v66, 0x3f317217, v56
	v_cndmask_b32_e64 v56, v56, v66, s[4:5]
	v_cndmask_b32_e64 v66, 0, v243, s[0:1]
	v_sub_f32_e32 v56, v56, v66
	v_add_f32_e32 v56, v57, v56
	v_sub_f32_e32 v56, -0.5, v56
	v_mul_f32_e32 v56, 0x3fb8aa3b, v56
	v_exp_f32_e32 v56, v56
	s_nop 0
	v_mul_f32_e32 v56, 0xbfb8aa3b, v56
	v_exp_f32_e32 v66, v56
	v_add_f32_e32 v56, v58, v82
	v_mul_f32_e32 v56, 0xbfb8aa3b, v56
	v_exp_f32_e32 v56, v56
	s_nop 0
	v_add_f32_e32 v56, 1.0, v56
	v_rcp_f32_e32 v114, v56
	v_add_f32_e32 v56, v67, v87
	v_max_f32_e64 v57, -v56, 0
	v_mul_f32_e64 v56, |v56|, s57
	v_exp_f32_e32 v56, v56
	s_nop 0
	v_add_f32_e32 v56, 1.0, v56
	v_cmp_gt_f32_e64 s[0:1], s75, v56
	s_nop 1
	v_cndmask_b32_e64 v58, 0, 32, s[0:1]
	v_ldexp_f32 v56, v56, v58
	v_log_f32_e32 v56, v56
	s_nop 0
	v_mul_f32_e32 v58, 0x3f317217, v56
	v_cmp_lt_f32_e64 s[4:5], |v56|, s59
	v_fma_f32 v58, v56, s58, -v58
	v_fmac_f32_e32 v58, 0x3377d1cf, v56
	v_fmac_f32_e32 v58, 0x3f317217, v56
	v_cndmask_b32_e64 v56, v56, v58, s[4:5]
	v_cndmask_b32_e64 v58, 0, v243, s[0:1]
	s_or_b32 s0, s10, 16
	v_sub_f32_e32 v56, v56, v58
	v_lshlrev_b32_e32 v58, 16, v120
	v_add_f32_e32 v56, v57, v56
	v_xor_b32_e32 v82, 0x80000000, v58
	v_and_b32_e32 v57, 0xffff0000, v121
	v_sub_f32_e32 v56, -0.5, v56
	v_xor_b32_e32 v81, 0x80000000, v57
	v_mul_f32_e32 v56, 0x3fb8aa3b, v56
	v_exp_f32_e32 v56, v56
	s_nop 0
	v_mul_f32_e32 v56, 0xbfb8aa3b, v56
	v_exp_f32_e32 v67, v56
	v_add_f32_e32 v56, v59, v83
	v_and_b32_e32 v59, 0xffff0000, v120
	v_mul_f32_e32 v56, 0xbfb8aa3b, v56
	v_xor_b32_e32 v83, 0x80000000, v59
	v_exp_f32_e32 v56, v56
	v_pk_fma_f32 v[82:83], v[0:1], v[122:123], v[82:83]
	v_sub_u32_e32 v233, v44, v232
	ds_write_b128 v233, v[64:67]
	v_pk_fma_f32 v[58:59], v[60:61], v[82:83], v[58:59]
	v_pk_add_f32 v[60:61], v[110:111], -1.0 op_sel_hi:[1,0]
	v_add_f32_e32 v56, 1.0, v56
	s_waitcnt vmcnt(1)
	v_pk_fma_f32 v[60:61], v[76:77], v[60:61], 1.0 op_sel_hi:[1,1,0]
	v_rcp_f32_e32 v115, v56
	v_lshlrev_b32_e32 v56, 16, v121
	v_pk_mul_f32 v[120:121], v[68:69], v[58:59]
	v_pk_mul_f32 v[58:59], v[58:59], v[60:61]
	v_xor_b32_e32 v80, 0x80000000, v56
	v_mul_f32_e32 v60, v140, v58
	s_waitcnt vmcnt(0)
	v_fma_f32 v159, v72, v60, 0
	v_mul_f32_e32 v60, v141, v59
	v_pk_fma_f32 v[80:81], v[100:101], v[128:129], v[80:81]
	v_fmac_f32_e32 v159, v73, v60
	v_pk_add_f32 v[60:61], v[114:115], -1.0 op_sel_hi:[1,0]
	v_pk_fma_f32 v[56:57], v[62:63], v[80:81], v[56:57]
	v_pk_fma_f32 v[60:61], v[78:79], v[60:61], 1.0 op_sel_hi:[1,1,0]
	v_cvt_pk_bf16_f32 v44, v58, v59
	v_pk_mul_f32 v[60:61], v[56:57], v[60:61]
	v_pk_mul_f32 v[122:123], v[70:71], v[56:57]
	v_cvt_pk_bf16_f32 v45, v60, v61
	v_sub_u32_e32 v233, v112, v232
	ds_write_b64 v233, v[44:45] offset:512
	v_or_b32_e32 v44, s0, v180
	v_mul_f32_e32 v62, v138, v60
	v_lshlrev_b32_e32 v2, 7, v44
	v_fmac_f32_e32 v159, v74, v62
	v_mul_f32_e32 v56, v139, v61
	v_sub_u32_e32 v233, v116, v227
	ds_write_b64 v233, v[36:37]
	v_lshl_add_u64 v[36:37], v[88:89], 0, v[2:3]
	v_fmac_f32_e32 v159, v75, v56
	v_lshl_add_u64 v[38:39], v[92:93], 0, v[2:3]
	global_load_dwordx4 v[40:43], v[36:37], off
	global_load_dwordx4 v[56:59], v[38:39], off
	global_load_dwordx4 v[60:63], v[36:37], off offset:64
	global_load_dwordx4 v[68:71], v[38:39], off offset:64
	v_lshlrev_b32_e32 v2, 8, v44
	v_lshl_add_u64 v[36:37], v[94:95], 0, v[2:3]
	v_or_b32_e32 v2, s0, v181
	v_lshlrev_b32_e32 v2, 2, v2
	global_load_dwordx4 v[52:55], v[36:37], off
	global_load_dwordx4 v[48:51], v[36:37], off offset:64
	global_load_dwordx4 v[44:47], v[36:37], off offset:128
	s_nop 0
	global_load_dwordx4 v[36:39], v[36:37], off offset:192
	v_pk_mul_f32 v[128:129], v[120:121], v[120:121]
	v_pk_mul_f32 v[130:131], v[122:123], v[122:123]
	s_waitcnt vmcnt(7)
; __device__ __forceinline__ float sigmoidf_(float x) { return __builtin_amdgcn_rcpf(1.0f + __expf(-x)); }
; __device__ __forceinline__ f32x4 ld_bf4(const bf16_t* q) { const u32x2 u = *(const u32x2*)q; return (f32x4){bflo(u.x), bfhi(u.x), bflo(u.y), bfhi(u.y)}; }
; __device__ __forceinline__ void rwkv_prep_item(const Params& p, const Lt& lt, int l, int item) {
;     ...
;             for (int ks = 0; ks < 2; ++ks) {
;                 aw = __builtin_amdgcn_mfma_f32_16x16x32_bf16(*(const bf16x8*)(decT + crow * 64 + ks * 32 + quad * 8), fw[ks], aw, 0, 0, 0);
;                 aa = __builtin_amdgcn_mfma_f32_16x16x32_bf16(*(const bf16x8*)(aT + crow * 64 + ks * 32 + quad * 8), fa[ks], aa, 0, 0, 0);
;             }
; #pragma unroll
;             for (int ks = 0; ks < 4; ++ks) ag = __builtin_amdgcn_mfma_f32_16x16x32_bf16(*(const bf16x8*)(gT + crow * 128 + ks * 32 + quad * 8), fg[ks], ag, 0, 0, 0);
;             const int c = h * 64 + ct * 16 + quad * 4;
;             const f32x4 mr = *(const f32x4*)(mu + c), mk = *(const f32x4*)(mu + COL_K + c), mv = *(const f32x4*)(mu + COL_V + c);
;             const f32x4 cr = ld_bf4(pt + c), ck = ld_bf4(pt + COL_K + c), cv = ld_bf4(pt + COL_V + c);
;             const f32x4 qr = ld_bf4(pp + c) * pm, qk = ld_bf4(pp + COL_K + c) * pm, qv = ld_bf4(pp + COL_V + c) * pm;
;             const f32x4 r = cr + (qr - cr) * mr, k = ck + (qk - ck) * mk, v = cv + (qv - cv) * mv;
;             const f32x4 w0v = *(const f32x4*)(w0 + c), a0v = *(const f32x4*)(a0 + c), kkv = *(const f32x4*)(kkp + c), kav = *(const f32x4*)(kap + c), rkv = *(const f32x4*)(rkp + c);
;             f32x4 dec, a, kk, k2;
; #pragma unroll
;             for (int j = 0; j < 4; ++j) {
;                 const float z = -(w0v[j] + aw[j]);
;                 const float sp = fmaxf(z, 0.f) + __logf(1.0f + __expf(-fabsf(z)));
;                 dec[j] = __expf(-__expf(-sp - 0.5f));
;                 a[j] = sigmoidf_(a0v[j] + aa[j]);
	v_mfma_f32_16x16x32_bf16 v[40:43], v[40:43], v[20:23], 0
	s_waitcnt vmcnt(6)
	v_mfma_f32_16x16x32_bf16 v[56:59], v[56:59], v[28:31], 0
	s_waitcnt vmcnt(5)
	v_mfma_f32_16x16x32_bf16 v[64:67], v[60:63], v[24:27], v[40:43]
	s_waitcnt vmcnt(4)
	v_mfma_f32_16x16x32_bf16 v[60:63], v[68:71], v[32:35], v[56:59]
	global_load_dwordx4 v[68:71], v158, s[8:9] offset:64
	s_nop 2
	global_load_dwordx4 v[56:59], v158, s[8:9] offset:3136
	global_load_dwordx4 v[40:43], v2, s[52:53]
	global_load_dwordx2 v[72:73], v[126:127], off offset:32
	global_load_dwordx2 v[136:137], v[126:127], off offset:1568
	global_load_dwordx2 v[76:77], v[126:127], off offset:3104
	s_waitcnt vmcnt(9)
	v_mfma_f32_16x16x32_bf16 v[52:55], v[52:55], v[4:7], 0
	global_load_dwordx2 v[80:81], v[124:125], off offset:1568
	s_waitcnt vmcnt(3)
	v_lshlrev_b32_e32 v74, 16, v72
	s_waitcnt vmcnt(1)
	v_lshlrev_b32_e32 v144, 16, v76
	v_and_b32_e32 v145, 0xffff0000, v76
	v_lshlrev_b32_e32 v146, 16, v77
	v_and_b32_e32 v147, 0xffff0000, v77
	global_load_dwordx2 v[76:77], v[124:125], off offset:32
	v_and_b32_e32 v75, 0xffff0000, v72
	v_xor_b32_e32 v85, 0x80000000, v75
	v_xor_b32_e32 v84, 0x80000000, v74
	v_lshlrev_b32_e32 v72, 16, v73
	v_and_b32_e32 v73, 0xffff0000, v73
	v_mfma_f32_16x16x32_bf16 v[48:51], v[48:51], v[8:11], v[52:55]
	s_waitcnt vmcnt(1)
	v_lshlrev_b32_e32 v138, 16, v80
	v_and_b32_e32 v139, 0xffff0000, v80
	v_lshlrev_b32_e32 v140, 16, v81
	v_and_b32_e32 v141, 0xffff0000, v81
	global_load_dwordx2 v[80:81], v[124:125], off offset:3104
	v_mfma_f32_16x16x32_bf16 v[44:47], v[44:47], v[12:15], v[48:51]
	s_waitcnt vmcnt(1)
	v_lshlrev_b32_e32 v78, 16, v76
	v_and_b32_e32 v79, 0xffff0000, v76
	v_pk_fma_f32 v[78:79], v[0:1], v[78:79], v[84:85]
	v_lshlrev_b32_e32 v76, 16, v77
	v_and_b32_e32 v77, 0xffff0000, v77
	v_xor_b32_e32 v85, 0x80000000, v73
	v_xor_b32_e32 v84, 0x80000000, v72
	v_pk_fma_f32 v[150:151], v[68:69], v[78:79], v[74:75]
	v_xor_b32_e32 v69, 0x80000000, v145
	v_xor_b32_e32 v68, 0x80000000, v144
	v_pk_fma_f32 v[76:77], v[100:101], v[76:77], v[84:85]
	v_mfma_f32_16x16x32_bf16 v[36:39], v[36:39], v[16:19], v[44:47]
	v_fma_f32 v148, v70, v76, v72
	v_fma_f32 v149, v71, v77, v73
	s_waitcnt vmcnt(0)
	v_lshlrev_b32_e32 v82, 16, v80
	v_and_b32_e32 v83, 0xffff0000, v80
	v_lshlrev_b32_e32 v80, 16, v81
	v_and_b32_e32 v81, 0xffff0000, v81
	v_lshl_add_u64 v[44:45], v[118:119], 0, v[106:107]
	v_cvt_pk_bf16_f32 v36, v36, v37
	v_cvt_pk_bf16_f32 v37, v38, v39
	v_pk_fma_f32 v[152:153], v[0:1], v[82:83], v[68:69]
	v_xor_b32_e32 v69, 0x80000000, v147
	v_xor_b32_e32 v68, 0x80000000, v146
	v_pk_fma_f32 v[154:155], v[100:101], v[80:81], v[68:69]
	global_load_dwordx4 v[84:87], v158, s[42:43] offset:64
	global_load_dwordx4 v[80:83], v158, s[44:45] offset:64
	global_load_dwordx4 v[72:75], v158, s[46:47] offset:64
	global_load_dwordx4 v[76:79], v158, s[48:49] offset:64
	global_load_dwordx4 v[68:71], v158, s[50:51] offset:64
	v_pk_fma_f32 v[40:41], v[40:41], v[152:153], v[144:145]
	v_pk_fma_f32 v[42:43], v[42:43], v[154:155], v[146:147]
	v_cvt_pk_bf16_f32 v40, v40, v41
	v_cvt_pk_bf16_f32 v41, v42, v43
	s_waitcnt vmcnt(4)
	v_add_f32_e32 v2, v64, v84
	v_max_f32_e64 v64, -v2, 0
	v_mul_f32_e64 v2, |v2|, s57
	v_exp_f32_e32 v2, v2
	s_nop 0
	v_add_f32_e32 v2, 1.0, v2
	v_cmp_gt_f32_e64 s[0:1], s75, v2
	s_nop 1
	v_cndmask_b32_e64 v84, 0, 32, s[0:1]
	v_ldexp_f32 v2, v2, v84
	v_log_f32_e32 v2, v2
	s_nop 0
	v_mul_f32_e32 v84, 0x3f317217, v2
	v_cmp_lt_f32_e64 s[4:5], |v2|, s59
	v_fma_f32 v84, v2, s58, -v84
	v_fmac_f32_e32 v84, 0x3377d1cf, v2
	v_fmac_f32_e32 v84, 0x3f317217, v2
	v_cndmask_b32_e64 v2, v2, v84, s[4:5]
	v_cndmask_b32_e64 v84, 0, v243, s[0:1]
	v_sub_f32_e32 v2, v2, v84
	v_add_f32_e32 v2, v64, v2
	v_sub_f32_e32 v2, -0.5, v2
	v_mul_f32_e32 v2, 0x3fb8aa3b, v2
	v_exp_f32_e32 v2, v2
	s_nop 0
	v_mul_f32_e32 v2, 0xbfb8aa3b, v2
	v_exp_f32_e32 v64, v2
	s_waitcnt vmcnt(3)
	v_add_f32_e32 v2, v60, v80
	v_mul_f32_e32 v2, 0xbfb8aa3b, v2
	v_exp_f32_e32 v2, v2
	s_nop 0
	v_add_f32_e32 v2, 1.0, v2
	v_rcp_f32_e32 v132, v2
	v_add_f32_e32 v2, v65, v85
	v_max_f32_e64 v60, -v2, 0
	v_mul_f32_e64 v2, |v2|, s57
	v_exp_f32_e32 v2, v2
	s_nop 0
	v_add_f32_e32 v2, 1.0, v2
	v_cmp_gt_f32_e64 s[0:1], s75, v2
	s_nop 1
	v_cndmask_b32_e64 v65, 0, 32, s[0:1]
	v_ldexp_f32 v2, v2, v65
	v_log_f32_e32 v2, v2
	s_nop 0
	v_mul_f32_e32 v65, 0x3f317217, v2
	v_cmp_lt_f32_e64 s[4:5], |v2|, s59
	v_fma_f32 v65, v2, s58, -v65
	v_fmac_f32_e32 v65, 0x3377d1cf, v2
	v_fmac_f32_e32 v65, 0x3f317217, v2
	v_cndmask_b32_e64 v2, v2, v65, s[4:5]
	v_cndmask_b32_e64 v65, 0, v243, s[0:1]
	v_sub_f32_e32 v2, v2, v65
	v_add_f32_e32 v2, v60, v2
	v_sub_f32_e32 v2, -0.5, v2
	v_mul_f32_e32 v2, 0x3fb8aa3b, v2
	v_exp_f32_e32 v2, v2
	s_nop 0
	v_mul_f32_e32 v2, 0xbfb8aa3b, v2
	v_exp_f32_e32 v65, v2
	v_add_f32_e32 v2, v61, v81
	v_mul_f32_e32 v2, 0xbfb8aa3b, v2
	v_exp_f32_e32 v2, v2
	s_nop 0
	v_add_f32_e32 v2, 1.0, v2
	v_rcp_f32_e32 v133, v2
	v_add_f32_e32 v2, v66, v86
	v_max_f32_e64 v60, -v2, 0
	v_mul_f32_e64 v2, |v2|, s57
	v_exp_f32_e32 v2, v2
	s_nop 0
	v_add_f32_e32 v2, 1.0, v2
	v_cmp_gt_f32_e64 s[0:1], s75, v2
	s_nop 1
	v_cndmask_b32_e64 v61, 0, 32, s[0:1]
	v_ldexp_f32 v2, v2, v61
	v_log_f32_e32 v2, v2
	s_nop 0
	v_mul_f32_e32 v61, 0x3f317217, v2
	v_cmp_lt_f32_e64 s[4:5], |v2|, s59
	v_fma_f32 v61, v2, s58, -v61
	v_fmac_f32_e32 v61, 0x3377d1cf, v2
	v_fmac_f32_e32 v61, 0x3f317217, v2
	v_cndmask_b32_e64 v2, v2, v61, s[4:5]
	v_cndmask_b32_e64 v61, 0, v243, s[0:1]
	v_sub_f32_e32 v2, v2, v61
	v_add_f32_e32 v2, v60, v2
	v_sub_f32_e32 v2, -0.5, v2
	v_mul_f32_e32 v2, 0x3fb8aa3b, v2
	v_exp_f32_e32 v2, v2
	s_nop 0
	v_mul_f32_e32 v2, 0xbfb8aa3b, v2
	v_exp_f32_e32 v66, v2
	v_add_f32_e32 v2, v62, v82
; __device__ __forceinline__ float sigmoidf_(float x) { return __builtin_amdgcn_rcpf(1.0f + __expf(-x)); }
; __device__ __forceinline__ void st_bf4(unsigned char* q, f32x4 v) { u32x2 w; w.x = cvt_pk_bf16(v[0], v[1]); w.y = cvt_pk_bf16(v[2], v[3]); *(u32x2*)q = w; }
; __device__ __forceinline__ void rwkv_prep_item(const Params& p, const Lt& lt, int l, int item) {
;     ...
;             for (int j = 0; j < 4; ++j) {
;                 const float z = -(w0v[j] + aw[j]);
;                 const float sp = fmaxf(z, 0.f) + __logf(1.0f + __expf(-fabsf(z)));
;                 dec[j] = __expf(-__expf(-sp - 0.5f));
;                 a[j] = sigmoidf_(a0v[j] + aa[j]);
;                 kk[j] = k[j] * kkv[j];
;                 nrm += kk[j] * kk[j];
;                 k2[j] = k[j] * (1.0f + (a[j] - 1.0f) * kav[j]);
;                 bon += r[j] * k2[j] * rkv[j];
;             }
;             va[ct] = a; vkk[ct] = kk;
;             { const int cc = ct * 16 + quad * 4; *(f32x4*)(ob + cc * 4) = dec; st_bf4(ob + 512 + cc * 2, k2); st_bf4(ob + 640 + cc * 2, v); st_bf4(ob + 768 + cc * 2, r); }
;             st_bf4((unsigned char*)((bf16_t*)gate + (size_t)t * RW + c), ag);
;         }
	v_lshlrev_b32_e32 v62, 16, v136
	v_mul_f32_e32 v2, 0xbfb8aa3b, v2
	v_xor_b32_e32 v82, 0x80000000, v62
	v_exp_f32_e32 v2, v2
	s_nop 0
	v_add_f32_e32 v2, 1.0, v2
	v_rcp_f32_e32 v134, v2
	v_add_f32_e32 v2, v67, v87
	v_max_f32_e64 v60, -v2, 0
	v_mul_f32_e64 v2, |v2|, s57
	v_exp_f32_e32 v2, v2
	s_nop 0
	v_add_f32_e32 v2, 1.0, v2
	v_cmp_gt_f32_e64 s[0:1], s75, v2
	s_nop 1
	v_cndmask_b32_e64 v61, 0, 32, s[0:1]
	v_ldexp_f32 v2, v2, v61
	v_log_f32_e32 v2, v2
	s_nop 0
	v_mul_f32_e32 v61, 0x3f317217, v2
	v_cmp_lt_f32_e64 s[4:5], |v2|, s59
	v_fma_f32 v61, v2, s58, -v61
	v_fmac_f32_e32 v61, 0x3377d1cf, v2
	v_fmac_f32_e32 v61, 0x3f317217, v2
	v_cndmask_b32_e64 v2, v2, v61, s[4:5]
	v_cndmask_b32_e64 v61, 0, v243, s[0:1]
	s_or_b32 s0, s10, 32
	v_sub_f32_e32 v2, v2, v61
	v_add_f32_e32 v2, v60, v2
	v_sub_f32_e32 v2, -0.5, v2
	v_mul_f32_e32 v2, 0x3fb8aa3b, v2
	v_exp_f32_e32 v2, v2
	v_lshlrev_b32_e32 v60, 16, v137
	v_and_b32_e32 v61, 0xffff0000, v137
	v_xor_b32_e32 v81, 0x80000000, v61
	v_mul_f32_e32 v2, 0xbfb8aa3b, v2
	v_exp_f32_e32 v67, v2
	v_add_f32_e32 v2, v63, v83
	v_mul_f32_e32 v2, 0xbfb8aa3b, v2
	v_exp_f32_e32 v2, v2
	v_and_b32_e32 v63, 0xffff0000, v136
	v_xor_b32_e32 v83, 0x80000000, v63
	v_pk_fma_f32 v[82:83], v[0:1], v[138:139], v[82:83]
	v_add_f32_e32 v2, 1.0, v2
	v_rcp_f32_e32 v135, v2
	v_xor_b32_e32 v80, 0x80000000, v60
	v_pk_fma_f32 v[56:57], v[56:57], v[82:83], v[62:63]
	v_pk_add_f32 v[62:63], v[132:133], -1.0 op_sel_hi:[1,0]
	v_pk_fma_f32 v[80:81], v[100:101], v[140:141], v[80:81]
	s_waitcnt vmcnt(1)
	v_pk_fma_f32 v[62:63], v[76:77], v[62:63], 1.0 op_sel_hi:[1,1,0]
	v_pk_mul_f32 v[136:137], v[72:73], v[56:57]
	v_pk_mul_f32 v[56:57], v[56:57], v[62:63]
	v_pk_fma_f32 v[58:59], v[58:59], v[80:81], v[60:61]
	v_pk_add_f32 v[60:61], v[134:135], -1.0 op_sel_hi:[1,0]
	v_mul_f32_e32 v2, v150, v56
	v_pk_fma_f32 v[60:61], v[78:79], v[60:61], 1.0 op_sel_hi:[1,1,0]
	s_waitcnt vmcnt(0)
	v_fmac_f32_e32 v159, v68, v2
	v_mul_f32_e32 v2, v151, v57
	v_pk_mul_f32 v[60:61], v[58:59], v[60:61]
	v_sub_u32_e32 v233, v44, v232
	ds_write_b128 v233, v[64:67]
	v_lshl_add_u64 v[44:45], v[118:119], 0, v[108:109]
	v_fmac_f32_e32 v159, v69, v2
	v_mul_f32_e32 v2, v148, v60
	v_cvt_pk_bf16_f32 v46, v56, v57
	v_cvt_pk_bf16_f32 v47, v60, v61
	v_sub_u32_e32 v233, v44, v232
	ds_write_b64 v233, v[40:41] offset:640
	v_cvt_pk_bf16_f32 v40, v150, v151
	v_cvt_pk_bf16_f32 v41, v148, v149
	v_fmac_f32_e32 v159, v70, v2
	v_mul_f32_e32 v2, v149, v61
	v_sub_u32_e32 v233, v44, v232
	ds_write_b64 v233, v[46:47] offset:512
	v_sub_u32_e32 v233, v44, v232
	ds_write_b64 v233, v[40:41] offset:768
	v_or_b32_e32 v44, s0, v180
	v_fmac_f32_e32 v159, v71, v2
	v_lshlrev_b32_e32 v2, 7, v44
	v_sub_u32_e32 v233, v116, v227
	ds_write_b64 v233, v[36:37] offset:32
	v_lshl_add_u64 v[36:37], v[88:89], 0, v[2:3]
	v_pk_mul_f32 v[138:139], v[74:75], v[58:59]
	v_lshl_add_u64 v[38:39], v[92:93], 0, v[2:3]
	global_load_dwordx4 v[40:43], v[36:37], off
	global_load_dwordx4 v[56:59], v[38:39], off
	global_load_dwordx4 v[60:63], v[36:37], off offset:64
	global_load_dwordx4 v[68:71], v[38:39], off offset:64
	v_lshlrev_b32_e32 v2, 8, v44
	v_lshl_add_u64 v[36:37], v[94:95], 0, v[2:3]
	v_or_b32_e32 v2, s0, v181
	v_lshlrev_b32_e32 v2, 2, v2
	global_load_dwordx4 v[52:55], v[36:37], off
	global_load_dwordx4 v[48:51], v[36:37], off offset:64
	global_load_dwordx4 v[44:47], v[36:37], off offset:128
	s_nop 0
	global_load_dwordx4 v[36:39], v[36:37], off offset:192
	v_pk_mul_f32 v[140:141], v[136:137], v[136:137]
	v_pk_mul_f32 v[142:143], v[138:139], v[138:139]
	s_waitcnt vmcnt(7)
	v_mfma_f32_16x16x32_bf16 v[40:43], v[40:43], v[20:23], 0
	s_waitcnt vmcnt(6)
	v_mfma_f32_16x16x32_bf16 v[56:59], v[56:59], v[28:31], 0
	s_waitcnt vmcnt(5)
	v_mfma_f32_16x16x32_bf16 v[64:67], v[60:63], v[24:27], v[40:43]
	s_waitcnt vmcnt(4)
	v_mfma_f32_16x16x32_bf16 v[60:63], v[68:71], v[32:35], v[56:59]
	global_load_dwordx4 v[68:71], v158, s[8:9] offset:128
	s_nop 2
	global_load_dwordx4 v[56:59], v158, s[8:9] offset:3200
	global_load_dwordx4 v[40:43], v2, s[52:53]
	global_load_dwordx2 v[72:73], v[126:127], off offset:64
	global_load_dwordx2 v[152:153], v[126:127], off offset:1600
	global_load_dwordx2 v[76:77], v[126:127], off offset:3136
	s_waitcnt vmcnt(9)
	v_mfma_f32_16x16x32_bf16 v[52:55], v[52:55], v[4:7], 0
	global_load_dwordx2 v[80:81], v[124:125], off offset:1600
	s_waitcnt vmcnt(3)
	v_lshlrev_b32_e32 v74, 16, v72
	s_waitcnt vmcnt(1)
	v_lshlrev_b32_e32 v106, 16, v76
	v_and_b32_e32 v107, 0xffff0000, v76
	v_lshlrev_b32_e32 v108, 16, v77
	v_and_b32_e32 v109, 0xffff0000, v77
	global_load_dwordx2 v[76:77], v[124:125], off offset:64
	v_and_b32_e32 v75, 0xffff0000, v72
	v_xor_b32_e32 v85, 0x80000000, v75
	v_xor_b32_e32 v84, 0x80000000, v74
	v_lshlrev_b32_e32 v72, 16, v73
	v_and_b32_e32 v73, 0xffff0000, v73
	v_mfma_f32_16x16x32_bf16 v[48:51], v[48:51], v[8:11], v[52:55]
	s_waitcnt vmcnt(1)
	v_lshlrev_b32_e32 v154, 16, v80
	v_and_b32_e32 v155, 0xffff0000, v80
	v_lshlrev_b32_e32 v156, 16, v81
	v_and_b32_e32 v157, 0xffff0000, v81
	global_load_dwordx2 v[80:81], v[124:125], off offset:3136
	v_mfma_f32_16x16x32_bf16 v[44:47], v[44:47], v[12:15], v[48:51]
	s_waitcnt vmcnt(1)
	v_lshlrev_b32_e32 v78, 16, v76
	v_and_b32_e32 v79, 0xffff0000, v76
	v_pk_fma_f32 v[78:79], v[0:1], v[78:79], v[84:85]
	v_lshlrev_b32_e32 v76, 16, v77
	v_and_b32_e32 v77, 0xffff0000, v77
	v_xor_b32_e32 v85, 0x80000000, v73
	v_xor_b32_e32 v84, 0x80000000, v72
	v_pk_fma_f32 v[146:147], v[68:69], v[78:79], v[74:75]
	v_xor_b32_e32 v69, 0x80000000, v107
	v_xor_b32_e32 v68, 0x80000000, v106
	v_pk_fma_f32 v[76:77], v[100:101], v[76:77], v[84:85]
	v_mfma_f32_16x16x32_bf16 v[36:39], v[36:39], v[16:19], v[44:47]
	v_fma_f32 v144, v70, v76, v72
	v_fma_f32 v145, v71, v77, v73
	s_waitcnt vmcnt(0)
; __device__ __forceinline__ float sigmoidf_(float x) { return __builtin_amdgcn_rcpf(1.0f + __expf(-x)); }
; __device__ __forceinline__ f32x4 ld_bf4(const bf16_t* q) { const u32x2 u = *(const u32x2*)q; return (f32x4){bflo(u.x), bfhi(u.x), bflo(u.y), bfhi(u.y)}; }
; __device__ __forceinline__ void rwkv_prep_item(const Params& p, const Lt& lt, int l, int item) {
;     ...
;             const int c = h * 64 + ct * 16 + quad * 4;
;             const f32x4 mr = *(const f32x4*)(mu + c), mk = *(const f32x4*)(mu + COL_K + c), mv = *(const f32x4*)(mu + COL_V + c);
;             const f32x4 cr = ld_bf4(pt + c), ck = ld_bf4(pt + COL_K + c), cv = ld_bf4(pt + COL_V + c);
;             const f32x4 qr = ld_bf4(pp + c) * pm, qk = ld_bf4(pp + COL_K + c) * pm, qv = ld_bf4(pp + COL_V + c) * pm;
;             const f32x4 r = cr + (qr - cr) * mr, k = ck + (qk - ck) * mk, v = cv + (qv - cv) * mv;
;             const f32x4 w0v = *(const f32x4*)(w0 + c), a0v = *(const f32x4*)(a0 + c), kkv = *(const f32x4*)(kkp + c), kav = *(const f32x4*)(kap + c), rkv = *(const f32x4*)(rkp + c);
;             f32x4 dec, a, kk, k2;
; #pragma unroll
;             for (int j = 0; j < 4; ++j) {
;                 const float z = -(w0v[j] + aw[j]);
;                 const float sp = fmaxf(z, 0.f) + __logf(1.0f + __expf(-fabsf(z)));
;                 dec[j] = __expf(-__expf(-sp - 0.5f));
;                 a[j] = sigmoidf_(a0v[j] + aa[j]);
	v_lshlrev_b32_e32 v82, 16, v80
	v_and_b32_e32 v83, 0xffff0000, v80
	v_lshlrev_b32_e32 v80, 16, v81
	v_and_b32_e32 v81, 0xffff0000, v81
	v_lshl_add_u64 v[44:45], v[118:119], 0, v[102:103]
	v_cvt_pk_bf16_f32 v36, v36, v37
	v_cvt_pk_bf16_f32 v37, v38, v39
	v_pk_fma_f32 v[148:149], v[0:1], v[82:83], v[68:69]
	v_xor_b32_e32 v69, 0x80000000, v109
	v_xor_b32_e32 v68, 0x80000000, v108
	v_pk_fma_f32 v[150:151], v[100:101], v[80:81], v[68:69]
	global_load_dwordx4 v[84:87], v158, s[42:43] offset:128
	global_load_dwordx4 v[80:83], v158, s[44:45] offset:128
	global_load_dwordx4 v[72:75], v158, s[46:47] offset:128
	global_load_dwordx4 v[76:79], v158, s[48:49] offset:128
	global_load_dwordx4 v[68:71], v158, s[50:51] offset:128
	v_pk_fma_f32 v[40:41], v[40:41], v[148:149], v[106:107]
	v_pk_fma_f32 v[42:43], v[42:43], v[150:151], v[108:109]
	v_cvt_pk_bf16_f32 v40, v40, v41
	v_cvt_pk_bf16_f32 v41, v42, v43
	s_waitcnt vmcnt(4)
	v_add_f32_e32 v2, v64, v84
	v_max_f32_e64 v64, -v2, 0
	v_mul_f32_e64 v2, |v2|, s57
	v_exp_f32_e32 v2, v2
	s_nop 0
	v_add_f32_e32 v2, 1.0, v2
	v_cmp_gt_f32_e64 s[0:1], s75, v2
	s_nop 1
	v_cndmask_b32_e64 v84, 0, 32, s[0:1]
	v_ldexp_f32 v2, v2, v84
	v_log_f32_e32 v2, v2
	s_nop 0
	v_mul_f32_e32 v84, 0x3f317217, v2
	v_cmp_lt_f32_e64 s[4:5], |v2|, s59
	v_fma_f32 v84, v2, s58, -v84
	v_fmac_f32_e32 v84, 0x3377d1cf, v2
	v_fmac_f32_e32 v84, 0x3f317217, v2
	v_cndmask_b32_e64 v2, v2, v84, s[4:5]
	v_cndmask_b32_e64 v84, 0, v243, s[0:1]
	v_sub_f32_e32 v2, v2, v84
	v_add_f32_e32 v2, v64, v2
	v_sub_f32_e32 v2, -0.5, v2
	v_mul_f32_e32 v2, 0x3fb8aa3b, v2
	v_exp_f32_e32 v2, v2
	s_nop 0
	v_mul_f32_e32 v2, 0xbfb8aa3b, v2
	v_exp_f32_e32 v64, v2
	s_waitcnt vmcnt(3)
	v_add_f32_e32 v2, v60, v80
	v_mul_f32_e32 v2, 0xbfb8aa3b, v2
	v_exp_f32_e32 v2, v2
	s_nop 0
	v_add_f32_e32 v2, 1.0, v2
	v_rcp_f32_e32 v80, v2
	v_add_f32_e32 v2, v65, v85
	v_max_f32_e64 v60, -v2, 0
	v_mul_f32_e64 v2, |v2|, s57
	v_exp_f32_e32 v2, v2
	s_nop 0
	v_add_f32_e32 v2, 1.0, v2
	v_cmp_gt_f32_e64 s[0:1], s75, v2
	s_nop 1
	v_cndmask_b32_e64 v65, 0, 32, s[0:1]
	v_ldexp_f32 v2, v2, v65
	v_log_f32_e32 v2, v2
	s_nop 0
	v_mul_f32_e32 v65, 0x3f317217, v2
	v_cmp_lt_f32_e64 s[4:5], |v2|, s59
	v_fma_f32 v65, v2, s58, -v65
	v_fmac_f32_e32 v65, 0x3377d1cf, v2
	v_fmac_f32_e32 v65, 0x3f317217, v2
	v_cndmask_b32_e64 v2, v2, v65, s[4:5]
	v_cndmask_b32_e64 v65, 0, v243, s[0:1]
	v_sub_f32_e32 v2, v2, v65
	v_add_f32_e32 v2, v60, v2
	v_sub_f32_e32 v2, -0.5, v2
	v_mul_f32_e32 v2, 0x3fb8aa3b, v2
	v_exp_f32_e32 v2, v2
	s_nop 0
	v_mul_f32_e32 v2, 0xbfb8aa3b, v2
	v_exp_f32_e32 v65, v2
	v_add_f32_e32 v2, v61, v81
	v_mul_f32_e32 v2, 0xbfb8aa3b, v2
	v_exp_f32_e32 v2, v2
	s_nop 0
	v_add_f32_e32 v2, 1.0, v2
	v_rcp_f32_e32 v81, v2
	v_add_f32_e32 v2, v66, v86
	v_max_f32_e64 v60, -v2, 0
	v_mul_f32_e64 v2, |v2|, s57
	v_exp_f32_e32 v2, v2
	s_nop 0
	v_add_f32_e32 v2, 1.0, v2
	v_cmp_gt_f32_e64 s[0:1], s75, v2
	s_nop 1
	v_cndmask_b32_e64 v61, 0, 32, s[0:1]
	v_ldexp_f32 v2, v2, v61
	v_log_f32_e32 v2, v2
	s_nop 0
	v_mul_f32_e32 v61, 0x3f317217, v2
	v_cmp_lt_f32_e64 s[4:5], |v2|, s59
	v_fma_f32 v61, v2, s58, -v61
	v_fmac_f32_e32 v61, 0x3377d1cf, v2
	v_fmac_f32_e32 v61, 0x3f317217, v2
	v_cndmask_b32_e64 v2, v2, v61, s[4:5]
	v_cndmask_b32_e64 v61, 0, v243, s[0:1]
	v_sub_f32_e32 v2, v2, v61
	v_add_f32_e32 v2, v60, v2
	v_sub_f32_e32 v2, -0.5, v2
	v_mul_f32_e32 v2, 0x3fb8aa3b, v2
	v_exp_f32_e32 v2, v2
	s_nop 0
	v_mul_f32_e32 v2, 0xbfb8aa3b, v2
	v_exp_f32_e32 v66, v2
	v_add_f32_e32 v2, v62, v82
	v_mul_f32_e32 v2, 0xbfb8aa3b, v2
	v_exp_f32_e32 v2, v2
	v_lshlrev_b32_e32 v62, 16, v152
	v_add_f32_e32 v2, 1.0, v2
	v_rcp_f32_e32 v82, v2
	v_add_f32_e32 v2, v67, v87
	v_max_f32_e64 v60, -v2, 0
	v_mul_f32_e64 v2, |v2|, s57
	v_exp_f32_e32 v2, v2
	s_nop 0
	v_add_f32_e32 v2, 1.0, v2
	v_cmp_gt_f32_e64 s[0:1], s75, v2
	s_nop 1
	v_cndmask_b32_e64 v61, 0, 32, s[0:1]
	v_ldexp_f32 v2, v2, v61
	v_log_f32_e32 v2, v2
	s_nop 0
	v_mul_f32_e32 v61, 0x3f317217, v2
	v_fma_f32 v61, v2, s58, -v61
	v_fmac_f32_e32 v61, 0x3377d1cf, v2
	v_fmac_f32_e32 v61, 0x3f317217, v2
	v_cmp_lt_f32_e64 s[4:5], |v2|, s59
	s_nop 1
	v_cndmask_b32_e64 v2, v2, v61, s[4:5]
	v_cndmask_b32_e64 v61, 0, v243, s[0:1]
	v_sub_f32_e32 v2, v2, v61
	v_add_f32_e32 v2, v60, v2
	v_sub_f32_e32 v2, -0.5, v2
	v_mul_f32_e32 v2, 0x3fb8aa3b, v2
	v_exp_f32_e32 v2, v2
	v_lshlrev_b32_e32 v60, 16, v153
	v_and_b32_e32 v61, 0xffff0000, v153
	v_xor_b32_e32 v85, 0x80000000, v61
	v_mul_f32_e32 v2, 0xbfb8aa3b, v2
	v_exp_f32_e32 v67, v2
	v_add_f32_e32 v2, v63, v83
	v_mul_f32_e32 v2, 0xbfb8aa3b, v2
	v_exp_f32_e32 v2, v2
	v_and_b32_e32 v63, 0xffff0000, v152
	v_xor_b32_e32 v84, 0x80000000, v60
	v_pk_fma_f32 v[86:87], v[100:101], v[156:157], v[84:85]
	v_add_f32_e32 v2, 1.0, v2
	v_rcp_f32_e32 v83, v2
	v_xor_b32_e32 v85, 0x80000000, v63
	v_xor_b32_e32 v84, 0x80000000, v62
	v_pk_fma_f32 v[84:85], v[0:1], v[154:155], v[84:85]
	v_pk_fma_f32 v[58:59], v[58:59], v[86:87], v[60:61]
	v_pk_fma_f32 v[56:57], v[56:57], v[84:85], v[62:63]
	v_pk_add_f32 v[62:63], v[80:81], -1.0 op_sel_hi:[1,0]
	s_waitcnt vmcnt(2)
	v_pk_mul_f32 v[72:73], v[72:73], v[56:57]
	s_waitcnt vmcnt(1)
	v_pk_fma_f32 v[62:63], v[76:77], v[62:63], 1.0 op_sel_hi:[1,1,0]
	v_pk_add_f32 v[60:61], v[82:83], -1.0 op_sel_hi:[1,0]
	v_pk_mul_f32 v[56:57], v[56:57], v[62:63]
	v_pk_fma_f32 v[60:61], v[78:79], v[60:61], 1.0 op_sel_hi:[1,1,0]
	v_mul_f32_e32 v2, v146, v56
	s_waitcnt vmcnt(0)
; __device__ __forceinline__ float sigmoidf_(float x) { return __builtin_amdgcn_rcpf(1.0f + __expf(-x)); }
; __device__ __forceinline__ void st_bf4(unsigned char* q, f32x4 v) { u32x2 w; w.x = cvt_pk_bf16(v[0], v[1]); w.y = cvt_pk_bf16(v[2], v[3]); *(u32x2*)q = w; }
; __device__ __forceinline__ void rwkv_prep_item(const Params& p, const Lt& lt, int l, int item) {
;     ...
;             const f32x4 r = cr + (qr - cr) * mr, k = ck + (qk - ck) * mk, v = cv + (qv - cv) * mv;
;             const f32x4 w0v = *(const f32x4*)(w0 + c), a0v = *(const f32x4*)(a0 + c), kkv = *(const f32x4*)(kkp + c), kav = *(const f32x4*)(kap + c), rkv = *(const f32x4*)(rkp + c);
;             f32x4 dec, a, kk, k2;
; #pragma unroll
;             for (int j = 0; j < 4; ++j) {
;                 const float z = -(w0v[j] + aw[j]);
;                 const float sp = fmaxf(z, 0.f) + __logf(1.0f + __expf(-fabsf(z)));
;                 dec[j] = __expf(-__expf(-sp - 0.5f));
;                 a[j] = sigmoidf_(a0v[j] + aa[j]);
;                 kk[j] = k[j] * kkv[j];
;                 nrm += kk[j] * kk[j];
;                 k2[j] = k[j] * (1.0f + (a[j] - 1.0f) * kav[j]);
;                 bon += r[j] * k2[j] * rkv[j];
;             }
;             va[ct] = a; vkk[ct] = kk;
;             { const int cc = ct * 16 + quad * 4; *(f32x4*)(ob + cc * 4) = dec; st_bf4(ob + 512 + cc * 2, k2); st_bf4(ob + 640 + cc * 2, v); st_bf4(ob + 768 + cc * 2, r); }
;             st_bf4((unsigned char*)((bf16_t*)gate + (size_t)t * RW + c), ag);
;         }
	v_fmac_f32_e32 v159, v68, v2
	v_mul_f32_e32 v2, v147, v57
	v_pk_mul_f32 v[60:61], v[58:59], v[60:61]
	v_sub_u32_e32 v233, v44, v232
	ds_write_b128 v233, v[64:67]
	v_lshl_add_u64 v[44:45], v[118:119], 0, v[104:105]
	v_fmac_f32_e32 v159, v69, v2
	v_mul_f32_e32 v2, v144, v60
	v_sub_u32_e32 v233, v44, v232
	ds_write_b64 v233, v[40:41] offset:640
	v_cvt_pk_bf16_f32 v40, v146, v147
	v_cvt_pk_bf16_f32 v41, v144, v145
	s_or_b32 s0, s10, 48
	v_fmac_f32_e32 v159, v70, v2
	v_mul_f32_e32 v2, v145, v61
	v_sub_u32_e32 v233, v44, v232
	ds_write_b64 v233, v[40:41] offset:768
	v_or_b32_e32 v40, s0, v180
	v_fmac_f32_e32 v159, v71, v2
	v_cvt_pk_bf16_f32 v46, v56, v57
	v_cvt_pk_bf16_f32 v47, v60, v61
	v_lshlrev_b32_e32 v2, 7, v40
	v_sub_u32_e32 v233, v44, v232
	ds_write_b64 v233, v[46:47] offset:512
	v_sub_u32_e32 v233, v116, v227
	ds_write_b64 v233, v[36:37] offset:64
	v_lshl_add_u64 v[36:37], v[88:89], 0, v[2:3]
	v_pk_mul_f32 v[74:75], v[74:75], v[58:59]
	v_lshl_add_u64 v[38:39], v[92:93], 0, v[2:3]
	global_load_dwordx4 v[52:55], v[36:37], off
	global_load_dwordx4 v[56:59], v[38:39], off
	global_load_dwordx4 v[60:63], v[36:37], off offset:64
	global_load_dwordx4 v[64:67], v[38:39], off offset:64
	v_lshlrev_b32_e32 v2, 8, v40
	v_lshl_add_u64 v[36:37], v[94:95], 0, v[2:3]
	v_or_b32_e32 v2, s0, v181
	v_lshlrev_b32_e32 v2, 2, v2
	global_load_dwordx4 v[48:51], v[36:37], off
	global_load_dwordx4 v[44:47], v[36:37], off offset:64
	global_load_dwordx4 v[40:43], v[36:37], off offset:128
	s_nop 0
	global_load_dwordx4 v[36:39], v[36:37], off offset:192
	v_pk_mul_f32 v[84:85], v[72:73], v[72:73]
	v_pk_mul_f32 v[76:77], v[74:75], v[74:75]
	s_waitcnt vmcnt(7)
	v_mfma_f32_16x16x32_bf16 v[20:23], v[52:55], v[20:23], 0
	s_waitcnt vmcnt(6)
	v_mfma_f32_16x16x32_bf16 v[28:31], v[56:59], v[28:31], 0
	s_waitcnt vmcnt(5)
	v_mfma_f32_16x16x32_bf16 v[52:55], v[60:63], v[24:27], v[20:23]
	s_waitcnt vmcnt(4)
	v_mfma_f32_16x16x32_bf16 v[28:31], v[64:67], v[32:35], v[28:31]
	global_load_dwordx4 v[32:35], v158, s[8:9] offset:192
	global_load_dwordx4 v[24:27], v158, s[8:9] offset:3264
	global_load_dwordx4 v[20:23], v2, s[52:53]
	global_load_dwordx2 v[56:57], v[126:127], off offset:96
	global_load_dwordx2 v[104:105], v[126:127], off offset:1632
	global_load_dwordx2 v[60:61], v[126:127], off offset:3168
	s_waitcnt vmcnt(9)
	v_mfma_f32_16x16x32_bf16 v[4:7], v[48:51], v[4:7], 0
	global_load_dwordx2 v[64:65], v[124:125], off offset:1632
	s_waitcnt vmcnt(3)
	v_lshlrev_b32_e32 v58, 16, v56
	s_waitcnt vmcnt(1)
	v_lshlrev_b32_e32 v78, 16, v60
	v_and_b32_e32 v79, 0xffff0000, v60
	v_lshlrev_b32_e32 v86, 16, v61
	v_and_b32_e32 v87, 0xffff0000, v61
	global_load_dwordx2 v[60:61], v[124:125], off offset:96
	v_and_b32_e32 v59, 0xffff0000, v56
	v_xor_b32_e32 v69, 0x80000000, v59
	v_xor_b32_e32 v68, 0x80000000, v58
	v_lshlrev_b32_e32 v56, 16, v57
	v_and_b32_e32 v57, 0xffff0000, v57
	v_mfma_f32_16x16x32_bf16 v[4:7], v[44:47], v[8:11], v[4:7]
	s_waitcnt vmcnt(1)
	v_lshlrev_b32_e32 v106, 16, v64
	v_and_b32_e32 v107, 0xffff0000, v64
	v_lshlrev_b32_e32 v108, 16, v65
	v_and_b32_e32 v109, 0xffff0000, v65
	global_load_dwordx2 v[64:65], v[124:125], off offset:3168
	v_mfma_f32_16x16x32_bf16 v[4:7], v[40:43], v[12:15], v[4:7]
	v_lshl_add_u64 v[12:13], v[118:119], 0, v[96:97]
	s_waitcnt vmcnt(1)
	v_lshlrev_b32_e32 v62, 16, v60
	v_and_b32_e32 v63, 0xffff0000, v60
	v_pk_fma_f32 v[62:63], v[0:1], v[62:63], v[68:69]
	v_lshlrev_b32_e32 v60, 16, v61
	v_and_b32_e32 v61, 0xffff0000, v61
	v_xor_b32_e32 v69, 0x80000000, v57
	v_xor_b32_e32 v68, 0x80000000, v56
	v_pk_fma_f32 v[92:93], v[32:33], v[62:63], v[58:59]
	v_xor_b32_e32 v33, 0x80000000, v79
	v_xor_b32_e32 v32, 0x80000000, v78
	v_pk_fma_f32 v[60:61], v[100:101], v[60:61], v[68:69]
	v_mfma_f32_16x16x32_bf16 v[4:7], v[36:39], v[16:19], v[4:7]
	v_fma_f32 v88, v34, v60, v56
	v_fma_f32 v89, v35, v61, v57
	s_waitcnt vmcnt(0)
	v_lshlrev_b32_e32 v66, 16, v64
	v_and_b32_e32 v67, 0xffff0000, v64
	v_lshlrev_b32_e32 v64, 16, v65
	v_and_b32_e32 v65, 0xffff0000, v65
	s_nop 0
	v_cvt_pk_bf16_f32 v4, v4, v5
	v_cvt_pk_bf16_f32 v5, v6, v7
	v_pk_fma_f32 v[94:95], v[0:1], v[66:67], v[32:33]
	v_xor_b32_e32 v33, 0x80000000, v87
	v_xor_b32_e32 v32, 0x80000000, v86
	v_pk_fma_f32 v[102:103], v[100:101], v[64:65], v[32:33]
	global_load_dwordx4 v[60:63], v158, s[42:43] offset:192
	global_load_dwordx4 v[68:71], v158, s[44:45] offset:192
	global_load_dwordx4 v[56:59], v158, s[46:47] offset:192
	global_load_dwordx4 v[64:67], v158, s[48:49] offset:192
	global_load_dwordx4 v[32:35], v158, s[50:51] offset:192
	v_pk_fma_f32 v[10:11], v[20:21], v[94:95], v[78:79]
	v_pk_fma_f32 v[8:9], v[22:23], v[102:103], v[86:87]
	v_cvt_pk_bf16_f32 v10, v10, v11
	v_cvt_pk_bf16_f32 v11, v8, v9
	v_cvt_pk_bf16_f32 v8, v92, v93
	v_cvt_pk_bf16_f32 v9, v88, v89
	s_waitcnt vmcnt(4)
	v_add_f32_e32 v2, v52, v60
	v_max_f32_e64 v52, -v2, 0
	v_mul_f32_e64 v2, |v2|, s57
	v_exp_f32_e32 v2, v2
	s_nop 0
	v_add_f32_e32 v2, 1.0, v2
	v_cmp_gt_f32_e64 s[0:1], s75, v2
	s_nop 1
	v_cndmask_b32_e64 v60, 0, 32, s[0:1]
	v_ldexp_f32 v2, v2, v60
	v_log_f32_e32 v2, v2
	s_nop 0
	v_mul_f32_e32 v60, 0x3f317217, v2
	v_cmp_lt_f32_e64 s[4:5], |v2|, s59
	v_fma_f32 v60, v2, s58, -v60
	v_fmac_f32_e32 v60, 0x3377d1cf, v2
	v_fmac_f32_e32 v60, 0x3f317217, v2
	v_cndmask_b32_e64 v2, v2, v60, s[4:5]
	v_cndmask_b32_e64 v60, 0, v243, s[0:1]
	v_sub_f32_e32 v2, v2, v60
	v_add_f32_e32 v2, v52, v2
	v_sub_f32_e32 v2, -0.5, v2
	v_mul_f32_e32 v2, 0x3fb8aa3b, v2
	v_exp_f32_e32 v2, v2
	s_nop 0
	v_mul_f32_e32 v2, 0xbfb8aa3b, v2
	v_exp_f32_e32 v52, v2
	s_waitcnt vmcnt(3)
; __device__ __forceinline__ float quad_sum(float v) { v += xor16(v); v += xor32(v); return v; }
; __device__ __forceinline__ float sigmoidf_(float x) { return __builtin_amdgcn_rcpf(1.0f + __expf(-x)); }
; __device__ __forceinline__ void st_bf4(unsigned char* q, f32x4 v) { u32x2 w; w.x = cvt_pk_bf16(v[0], v[1]); w.y = cvt_pk_bf16(v[2], v[3]); *(u32x2*)q = w; }
; __device__ __forceinline__ void rwkv_prep_item(const Params& p, const Lt& lt, int l, int item) {
;     ...
;             const f32x4 r = cr + (qr - cr) * mr, k = ck + (qk - ck) * mk, v = cv + (qv - cv) * mv;
;             const f32x4 w0v = *(const f32x4*)(w0 + c), a0v = *(const f32x4*)(a0 + c), kkv = *(const f32x4*)(kkp + c), kav = *(const f32x4*)(kap + c), rkv = *(const f32x4*)(rkp + c);
;             f32x4 dec, a, kk, k2;
; #pragma unroll
;             for (int j = 0; j < 4; ++j) {
;                 const float z = -(w0v[j] + aw[j]);
;                 const float sp = fmaxf(z, 0.f) + __logf(1.0f + __expf(-fabsf(z)));
;                 dec[j] = __expf(-__expf(-sp - 0.5f));
;                 a[j] = sigmoidf_(a0v[j] + aa[j]);
;                 kk[j] = k[j] * kkv[j];
;                 nrm += kk[j] * kk[j];
;                 k2[j] = k[j] * (1.0f + (a[j] - 1.0f) * kav[j]);
;                 bon += r[j] * k2[j] * rkv[j];
;             }
;             va[ct] = a; vkk[ct] = kk;
;             { const int cc = ct * 16 + quad * 4; *(f32x4*)(ob + cc * 4) = dec; st_bf4(ob + 512 + cc * 2, k2); st_bf4(ob + 640 + cc * 2, v); st_bf4(ob + 768 + cc * 2, r); }
;             st_bf4((unsigned char*)((bf16_t*)gate + (size_t)t * RW + c), ag);
;         }
;         nrm = quad_sum(nrm); bon = quad_sum(bon);
	v_add_f32_e32 v2, v28, v68
	v_mul_f32_e32 v2, 0xbfb8aa3b, v2
	v_exp_f32_e32 v2, v2
	s_nop 0
	v_add_f32_e32 v2, 1.0, v2
	v_rcp_f32_e32 v28, v2
	v_add_f32_e32 v2, v53, v61
	v_and_b32_e32 v61, 0xffff0000, v105
	v_max_f32_e64 v53, -v2, 0
	v_mul_f32_e64 v2, |v2|, s57
	v_exp_f32_e32 v2, v2
	s_nop 0
	v_add_f32_e32 v2, 1.0, v2
	v_cmp_gt_f32_e64 s[0:1], s75, v2
	s_nop 1
	v_cndmask_b32_e64 v60, 0, 32, s[0:1]
	v_ldexp_f32 v2, v2, v60
	v_log_f32_e32 v2, v2
	s_nop 0
	v_mul_f32_e32 v60, 0x3f317217, v2
	v_fma_f32 v60, v2, s58, -v60
	v_fmac_f32_e32 v60, 0x3377d1cf, v2
	v_fmac_f32_e32 v60, 0x3f317217, v2
	v_cmp_lt_f32_e64 s[4:5], |v2|, s59
	s_nop 1
	v_cndmask_b32_e64 v2, v2, v60, s[4:5]
	v_cndmask_b32_e64 v60, 0, v243, s[0:1]
	v_sub_f32_e32 v2, v2, v60
	v_add_f32_e32 v2, v53, v2
	v_sub_f32_e32 v2, -0.5, v2
	v_mul_f32_e32 v2, 0x3fb8aa3b, v2
	v_exp_f32_e32 v2, v2
	s_nop 0
	v_mul_f32_e32 v2, 0xbfb8aa3b, v2
	v_exp_f32_e32 v53, v2
	v_add_f32_e32 v2, v29, v69
	v_mul_f32_e32 v2, 0xbfb8aa3b, v2
	v_exp_f32_e32 v2, v2
	v_xor_b32_e32 v69, 0x80000000, v61
	v_add_f32_e32 v2, 1.0, v2
	v_rcp_f32_e32 v29, v2
	v_add_f32_e32 v2, v54, v62
	v_max_f32_e64 v54, -v2, 0
	v_mul_f32_e64 v2, |v2|, s57
	v_exp_f32_e32 v2, v2
	v_lshlrev_b32_e32 v62, 16, v104
	v_add_f32_e32 v2, 1.0, v2
	v_cmp_gt_f32_e64 s[0:1], s75, v2
	s_nop 1
	v_cndmask_b32_e64 v60, 0, 32, s[0:1]
	v_ldexp_f32 v2, v2, v60
	v_log_f32_e32 v2, v2
	s_nop 0
	v_mul_f32_e32 v60, 0x3f317217, v2
	v_fma_f32 v60, v2, s58, -v60
	v_fmac_f32_e32 v60, 0x3377d1cf, v2
	v_fmac_f32_e32 v60, 0x3f317217, v2
	v_cmp_lt_f32_e64 s[4:5], |v2|, s59
	s_nop 1
	v_cndmask_b32_e64 v2, v2, v60, s[4:5]
	v_cndmask_b32_e64 v60, 0, v243, s[0:1]
	v_sub_f32_e32 v2, v2, v60
	v_add_f32_e32 v2, v54, v2
	v_sub_f32_e32 v2, -0.5, v2
	v_mul_f32_e32 v2, 0x3fb8aa3b, v2
	v_exp_f32_e32 v2, v2
	s_nop 0
	v_mul_f32_e32 v2, 0xbfb8aa3b, v2
	v_exp_f32_e32 v54, v2
	v_add_f32_e32 v2, v30, v70
	v_mul_f32_e32 v2, 0xbfb8aa3b, v2
	v_exp_f32_e32 v2, v2
	v_xor_b32_e32 v70, 0x80000000, v62
	v_add_f32_e32 v2, 1.0, v2
	v_rcp_f32_e32 v30, v2
	v_add_f32_e32 v2, v55, v63
	v_max_f32_e64 v55, -v2, 0
	v_mul_f32_e64 v2, |v2|, s57
	v_exp_f32_e32 v2, v2
	v_and_b32_e32 v63, 0xffff0000, v104
	v_add_f32_e32 v2, 1.0, v2
	v_cmp_gt_f32_e64 s[0:1], s75, v2
	s_nop 1
	v_cndmask_b32_e64 v60, 0, 32, s[0:1]
	v_ldexp_f32 v2, v2, v60
	v_log_f32_e32 v2, v2
	s_nop 0
	v_mul_f32_e32 v60, 0x3f317217, v2
	v_fma_f32 v60, v2, s58, -v60
	v_fmac_f32_e32 v60, 0x3377d1cf, v2
	v_fmac_f32_e32 v60, 0x3f317217, v2
	v_cmp_lt_f32_e64 s[4:5], |v2|, s59
	s_nop 1
	v_cndmask_b32_e64 v2, v2, v60, s[4:5]
	v_cndmask_b32_e64 v60, 0, v243, s[0:1]
	v_sub_f32_e32 v2, v2, v60
	v_add_f32_e32 v2, v55, v2
	v_sub_f32_e32 v2, -0.5, v2
	v_mul_f32_e32 v2, 0x3fb8aa3b, v2
	v_exp_f32_e32 v2, v2
	v_lshlrev_b32_e32 v60, 16, v105
	v_xor_b32_e32 v68, 0x80000000, v60
	v_pk_fma_f32 v[68:69], v[100:101], v[108:109], v[68:69]
	v_mul_f32_e32 v2, 0xbfb8aa3b, v2
	v_exp_f32_e32 v55, v2
	v_add_f32_e32 v2, v31, v71
	v_mul_f32_e32 v2, 0xbfb8aa3b, v2
	v_exp_f32_e32 v2, v2
	v_xor_b32_e32 v71, 0x80000000, v63
	v_pk_fma_f32 v[0:1], v[0:1], v[106:107], v[70:71]
	v_sub_u32_e32 v233, v12, v232
	ds_write_b128 v233, v[52:55]
	v_add_f32_e32 v2, 1.0, v2
	v_rcp_f32_e32 v31, v2
	v_pk_fma_f32 v[24:25], v[24:25], v[0:1], v[62:63]
	v_pk_add_f32 v[62:63], v[28:29], -1.0 op_sel_hi:[1,0]
	s_waitcnt vmcnt(2)
	v_pk_mul_f32 v[0:1], v[56:57], v[24:25]
	s_waitcnt vmcnt(1)
	v_pk_fma_f32 v[62:63], v[64:65], v[62:63], 1.0 op_sel_hi:[1,1,0]
	v_pk_mul_f32 v[56:57], v[0:1], v[0:1]
	v_pk_mul_f32 v[62:63], v[24:25], v[62:63]
	v_pk_fma_f32 v[24:25], v[26:27], v[68:69], v[60:61]
	v_pk_add_f32 v[26:27], v[30:31], -1.0 op_sel_hi:[1,0]
	v_mul_f32_e32 v2, v92, v62
	v_pk_fma_f32 v[26:27], v[66:67], v[26:27], 1.0 op_sel_hi:[1,1,0]
	s_waitcnt vmcnt(0)
	v_fmac_f32_e32 v159, v32, v2
	v_mul_f32_e32 v2, v93, v63
	v_pk_mul_f32 v[26:27], v[24:25], v[26:27]
	v_fmac_f32_e32 v159, v33, v2
	v_mul_f32_e32 v2, v88, v26
	v_fmac_f32_e32 v159, v34, v2
	v_add_f32_e32 v2, v128, v129
	v_add_f32_e32 v2, v130, v2
	v_add_f32_e32 v2, v131, v2
	v_add_f32_e32 v2, v2, v140
	v_add_f32_e32 v2, v141, v2
	v_add_f32_e32 v2, v142, v2
	v_add_f32_e32 v2, v143, v2
	v_add_f32_e32 v2, v2, v84
	v_add_f32_e32 v2, v85, v2
	v_add_f32_e32 v2, v76, v2
	v_add_f32_e32 v2, v77, v2
	v_pk_mul_f32 v[24:25], v[58:59], v[24:25]
	v_add_f32_e32 v2, v2, v56
	v_pk_mul_f32 v[32:33], v[24:25], v[24:25]
	v_add_f32_e32 v2, v57, v2
	v_add_f32_e32 v2, v32, v2
	v_add_f32_e32 v2, v33, v2
	v_lshl_add_u64 v[12:13], v[118:119], 0, v[98:99]
	v_cvt_pk_bf16_f32 v14, v62, v63
	v_cvt_pk_bf16_f32 v15, v26, v27
	v_sub_u32_e32 v233, v12, v232
	ds_write_b64 v233, v[14:15] offset:512
	v_sub_u32_e32 v233, v12, v232
	ds_write_b64 v233, v[10:11] offset:640
	v_sub_u32_e32 v233, v12, v232
	ds_write_b64 v233, v[8:9] offset:768
	v_sub_u32_e32 v233, v116, v227
	ds_write_b64 v233, v[4:5] offset:96
	ds_bpermute_b32 v4, v182, v2
	v_mul_f32_e32 v32, v89, v27
	v_fmac_f32_e32 v159, v35, v32
	s_waitcnt lgkmcnt(0)
	v_add_f32_e32 v2, v2, v4
	ds_bpermute_b32 v4, v183, v2
	s_waitcnt lgkmcnt(0)
; __device__ __forceinline__ float quad_sum(float v) { v += xor16(v); v += xor32(v); return v; }
; __device__ __forceinline__ void st_bf4(unsigned char* q, f32x4 v) { u32x2 w; w.x = cvt_pk_bf16(v[0], v[1]); w.y = cvt_pk_bf16(v[2], v[3]); *(u32x2*)q = w; }
; __device__ __forceinline__ void rwkv_prep_item(const Params& p, const Lt& lt, int l, int item) {
;     ...
;         nrm = quad_sum(nrm); bon = quad_sum(bon);
;         const float inv = rsqrtf(fmaxf(nrm, 1e-24f));
; #pragma unroll
;         for (int ct = 0; ct < 4; ++ct) {
;             const int cc = ct * 16 + quad * 4;
;             const f32x4 kkn = vkk[ct] * inv;
;             st_bf4(ob + 256 + cc * 2, -kkn);
;             st_bf4(ob + 384 + cc * 2, kkn * va[ct]);
;         }
;         if (quad == 0) bonus[(size_t)t * 16 + h] = bon;
;     }
	v_add_f32_e32 v5, v2, v4
	v_max_f32_e32 v5, 0x179abe15, v5
	v_rsq_f32_e32 v6, v5
	ds_bpermute_b32 v2, v182, v159
	v_pk_mul_f32 v[8:9], v[120:121], v[6:7] op_sel_hi:[1,0]
	v_pk_mul_f32 v[10:11], v[122:123], v[6:7] op_sel_hi:[1,0]
	v_xor_b32_e32 v12, 0x80000000, v9
	v_xor_b32_e32 v5, 0x80000000, v11
	v_xor_b32_e32 v7, 0x80000000, v10
	v_xor_b32_e32 v13, 0x80000000, v8
	v_pk_mul_f32 v[10:11], v[114:115], v[10:11]
	v_pk_mul_f32 v[8:9], v[110:111], v[8:9]
	v_cvt_pk_bf16_f32 v12, v13, v12
	v_cvt_pk_bf16_f32 v8, v8, v9
	v_cvt_pk_bf16_f32 v9, v10, v11
	v_cvt_pk_bf16_f32 v13, v7, v5
	v_sub_u32_e32 v233, v112, v232
	ds_write_b64 v233, v[8:9] offset:384
	v_pk_mul_f32 v[8:9], v[136:137], v[6:7] op_sel_hi:[1,0]
	v_pk_mul_f32 v[10:11], v[138:139], v[6:7] op_sel_hi:[1,0]
	v_sub_u32_e32 v233, v112, v232
	ds_write_b64 v233, v[12:13] offset:256
	v_xor_b32_e32 v5, 0x80000000, v11
	v_xor_b32_e32 v7, 0x80000000, v10
	v_xor_b32_e32 v12, 0x80000000, v9
	v_xor_b32_e32 v13, 0x80000000, v8
	v_pk_mul_f32 v[10:11], v[134:135], v[10:11]
	v_pk_mul_f32 v[8:9], v[132:133], v[8:9]
	s_waitcnt lgkmcnt(0)
	v_add_f32_e32 v2, v159, v2
	v_cvt_pk_bf16_f32 v8, v8, v9
	v_cvt_pk_bf16_f32 v9, v10, v11
	ds_bpermute_b32 v4, v183, v2
	v_cvt_pk_bf16_f32 v12, v13, v12
	v_cvt_pk_bf16_f32 v13, v7, v5
	v_sub_u32_e32 v233, v112, v232
	ds_write_b64 v233, v[8:9] offset:416
	v_pk_mul_f32 v[8:9], v[72:73], v[6:7] op_sel_hi:[1,0]
	v_pk_mul_f32 v[10:11], v[74:75], v[6:7] op_sel_hi:[1,0]
	v_sub_u32_e32 v233, v112, v232
	ds_write_b64 v233, v[12:13] offset:288
	v_xor_b32_e32 v5, 0x80000000, v11
	v_xor_b32_e32 v7, 0x80000000, v10
	v_xor_b32_e32 v12, 0x80000000, v9
	v_xor_b32_e32 v13, 0x80000000, v8
	v_pk_mul_f32 v[10:11], v[82:83], v[10:11]
	v_pk_mul_f32 v[8:9], v[80:81], v[8:9]
	v_cvt_pk_bf16_f32 v12, v13, v12
	v_cvt_pk_bf16_f32 v13, v7, v5
	v_cvt_pk_bf16_f32 v8, v8, v9
	v_cvt_pk_bf16_f32 v9, v10, v11
	v_pk_mul_f32 v[0:1], v[0:1], v[6:7] op_sel_hi:[1,0]
	v_pk_mul_f32 v[6:7], v[24:25], v[6:7] op_sel_hi:[1,0]
	v_sub_u32_e32 v233, v112, v232
	ds_write_b64 v233, v[8:9] offset:448
	v_xor_b32_e32 v5, 0x80000000, v7
	v_xor_b32_e32 v9, 0x80000000, v6
	v_xor_b32_e32 v8, 0x80000000, v1
	v_xor_b32_e32 v10, 0x80000000, v0
	v_pk_mul_f32 v[6:7], v[30:31], v[6:7]
	v_pk_mul_f32 v[0:1], v[28:29], v[0:1]
	v_cvt_pk_bf16_f32 v8, v10, v8
	v_cvt_pk_bf16_f32 v9, v9, v5
	v_cvt_pk_bf16_f32 v0, v0, v1
	v_cvt_pk_bf16_f32 v1, v6, v7
	v_sub_u32_e32 v233, v112, v232
	ds_write_b64 v233, v[12:13] offset:320
	v_sub_u32_e32 v233, v112, v232
	ds_write_b64 v233, v[8:9] offset:352
	v_sub_u32_e32 v233, v112, v232
	ds_write_b64 v233, v[0:1] offset:480
	s_waitcnt lgkmcnt(0)
	v_mov_b32_e32 v228, v234
	v_mov_b32_e32 v229, v235
	ds_read_b128 v[210:213], v226 offset:0
	ds_read_b128 v[214:217], v226 offset:1040
	ds_read_b128 v[218:221], v226 offset:2080
	ds_read_b128 v[222:225], v226 offset:3120
	s_waitcnt lgkmcnt(3)
	global_store_dwordx4 v[228:229], v[210:213], off
	v_lshl_add_u64 v[228:229], v[228:229], 0, v[194:195]
	s_waitcnt lgkmcnt(2)
	global_store_dwordx4 v[228:229], v[214:217], off
	v_lshl_add_u64 v[228:229], v[228:229], 0, v[194:195]
	s_waitcnt lgkmcnt(1)
	global_store_dwordx4 v[228:229], v[218:221], off
	v_lshl_add_u64 v[228:229], v[228:229], 0, v[194:195]
	s_waitcnt lgkmcnt(0)
	global_store_dwordx4 v[228:229], v[222:225], off
	v_lshl_add_u64 v[228:229], v[228:229], 0, v[194:195]
	ds_read_b128 v[210:213], v226 offset:4160
	ds_read_b128 v[214:217], v226 offset:5200
	ds_read_b128 v[218:221], v226 offset:6240
	ds_read_b128 v[222:225], v226 offset:7280
	s_waitcnt lgkmcnt(3)
	global_store_dwordx4 v[228:229], v[210:213], off
	v_lshl_add_u64 v[228:229], v[228:229], 0, v[194:195]
	s_waitcnt lgkmcnt(2)
	global_store_dwordx4 v[228:229], v[214:217], off
	v_lshl_add_u64 v[228:229], v[228:229], 0, v[194:195]
	s_waitcnt lgkmcnt(1)
	global_store_dwordx4 v[228:229], v[218:221], off
	v_lshl_add_u64 v[228:229], v[228:229], 0, v[194:195]
	s_waitcnt lgkmcnt(0)
	global_store_dwordx4 v[228:229], v[222:225], off
	v_lshl_add_u64 v[228:229], v[228:229], 0, v[194:195]
	ds_read_b128 v[210:213], v226 offset:8320
	ds_read_b128 v[214:217], v226 offset:9360
	ds_read_b128 v[218:221], v226 offset:10400
	ds_read_b128 v[222:225], v226 offset:11440
	s_waitcnt lgkmcnt(3)
	global_store_dwordx4 v[228:229], v[210:213], off
	v_lshl_add_u64 v[228:229], v[228:229], 0, v[194:195]
	s_waitcnt lgkmcnt(2)
	global_store_dwordx4 v[228:229], v[214:217], off
	v_lshl_add_u64 v[228:229], v[228:229], 0, v[194:195]
	s_waitcnt lgkmcnt(1)
	global_store_dwordx4 v[228:229], v[218:221], off
	v_lshl_add_u64 v[228:229], v[228:229], 0, v[194:195]
	s_waitcnt lgkmcnt(0)
	global_store_dwordx4 v[228:229], v[222:225], off
	v_lshl_add_u64 v[228:229], v[228:229], 0, v[194:195]
	ds_read_b128 v[210:213], v226 offset:12480
	ds_read_b128 v[214:217], v226 offset:13520
	ds_read_b128 v[218:221], v226 offset:14560
	ds_read_b128 v[222:225], v226 offset:15600
	s_waitcnt lgkmcnt(3)
	global_store_dwordx4 v[228:229], v[210:213], off
	v_lshl_add_u64 v[228:229], v[228:229], 0, v[194:195]
	s_waitcnt lgkmcnt(2)
	global_store_dwordx4 v[228:229], v[214:217], off
	v_lshl_add_u64 v[228:229], v[228:229], 0, v[194:195]
	s_waitcnt lgkmcnt(1)
	global_store_dwordx4 v[228:229], v[218:221], off
	v_lshl_add_u64 v[228:229], v[228:229], 0, v[194:195]
	s_waitcnt lgkmcnt(0)
	global_store_dwordx4 v[228:229], v[222:225], off
	v_lshl_add_u64 v[228:229], v[228:229], 0, v[194:195]
	v_lshl_add_u64 v[234:235], v[234:235], 0, v[198:199]
	s_and_saveexec_b64 s[0:1], vcc
	s_cbranch_execz .LBB0_342
	s_lshl_b32 s10, s56, 2
	v_lshl_add_u64 v[0:1], v[90:91], 0, s[10:11]
	s_waitcnt lgkmcnt(0)
	v_add_f32_e32 v2, v2, v4
	global_store_dword v[0:1], v2, off offset:8
	s_branch .LBB0_342
